# early2 + tail priority 2 + faster wake + saddr-form LDS-DMA (8 fewer VALU adds/iteration) + folded m0 s_nops: all load-segment trims together
# speedup vs baseline: 1.0047x; 1.0047x over previous
; #define PG8_STAGE(bufoff, gbase, voff) do { _Pragma("unroll") for (int _i = 0; _i < 2; ++_i) \
;         __builtin_amdgcn_global_load_lds((const unsigned*)((const char*)(gbase) + (voff)[_i]), (PG8_LAS unsigned*)(lds + (bufoff) + ldsw + _i * 8192), 16, 0, 0); } while (0)
; #define PG8_LDA(dst, b, h) do { _Pragma("unroll") for (int m = 0; m < 4; ++m) _Pragma("unroll") for (int k = 0; k < 2; ++k) dst[m][k] = *(const PG8_LAS bf16x8*)(lds + PG8_SA(b, h) + aoff + m * 2048 + k * 1024); } while (0)
; #define PG8_LDB(dst, b, h) do { _Pragma("unroll") for (int n = 0; n < 2; ++n) _Pragma("unroll") for (int k = 0; k < 2; ++k) dst[n][k] = *(const PG8_LAS bf16x8*)(lds + PG8_SB(b, h) + boff + n * 2048 + k * 1024); } while (0)
; #define PG8_MMA(ai, bj, At, Bt) do { __builtin_amdgcn_s_setprio(1); _Pragma("unroll") for (int m = 0; m < 4; ++m) _Pragma("unroll") for (int n = 0; n < 2; ++n) _Pragma("unroll") for (int k = 0; k < 2; ++k) \
;         acc[ai][bj][m][n] = __builtin_amdgcn_mfma_f32_16x16x32_bf16(Bt[n][k], At[m][k], acc[ai][bj][m][n], 0, 0, 0); __builtin_amdgcn_s_setprio(0); } while (0)
; #define PG8_WAIT_V(n) asm volatile("s_waitcnt vmcnt(" #n ")" ::: "memory")
; #define PG8_WAIT_L(n) asm volatile("s_waitcnt lgkmcnt(" #n ")" ::: "memory")
; #define PG8_BAR __builtin_amdgcn_s_barrier()
; #define PG8_SCHED __builtin_amdgcn_sched_barrier(0)
; template <class Epi, class Sched, bool ALIGN_EPI = false, bool SP2 = false>
; __device__ __forceinline__ void gemm_phase(PG8_LAS unsigned char* lds, const Gemm g, const Sched& S, const Epi& E) {
;     ...
;             const char* a1 = cA + (size_t)(t + 1) * kstep;
;             const char* a2 = last ? nA : cA + (size_t)(t + 2) * kstep; const char* b2 = last ? nB : cB + (size_t)(t + 2) * kstep;
;             const char* a3 = a2 + kstep; const char* b3 = b2 + kstep;
;             if constexpr (SP2) {
;             PG8_LDB(B0, 0, 0); PG8_LDB(B1, 0, 1); PG8_SCHED; PG8_LDA(At, 0, 0); PG8_STAGE(PG8_SA(1, 1), a1 + hstep, voffA);
;             PG8_WAIT_V(8); PG8_WAIT_L(0); PG8_BAR; PG8_MMA(0, 0, At, B0); PG8_MMA(0, 1, At, B1); PG8_BAR; PG8_SCHED;
;             PG8_LDA(At, 0, 1); PG8_STAGE(PG8_SB(0, 0), b2, voffB); PG8_STAGE(PG8_SB(0, 1), b2 + hstep, voffB); PG8_STAGE(PG8_SA(0, 0), a2, voffA);
;             PG8_WAIT_V(8); PG8_WAIT_L(0); PG8_BAR; PG8_MMA(1, 0, At, B0); PG8_MMA(1, 1, At, B1); PG8_BAR; PG8_SCHED;
.LBB0_200:
	ds_read_b128 v[148:151], v164
	ds_read_b128 v[152:155], v164 offset:1024
	ds_read_b128 v[156:159], v164 offset:2048
	ds_read_b128 v[168:171], v164 offset:3072
	ds_read_b128 v[172:175], v165
	ds_read_b128 v[176:179], v165 offset:1024
	ds_read_b128 v[180:183], v165 offset:2048
	ds_read_b128 v[184:187], v165 offset:3072
	s_add_u32 s52, s70, 0xfff80080
	s_addc_u32 s53, s71, -1
	s_cmp_eq_u32 s93, 28
	s_cselect_b32 s75, s39, s53
	s_cselect_b32 s74, s69, s52
	s_cselect_b32 s73, s35, s92
	s_cselect_b32 s72, s90, s91
	s_add_i32 m0, s33, 0xc000
	ds_read_b128 v[188:191], v166
	ds_read_b128 v[192:195], v166 offset:1024
	ds_read_b128 v[196:199], v166 offset:2048
	ds_read_b128 v[200:203], v166 offset:3072
	ds_read_b128 v[204:207], v166 offset:4096
	ds_read_b128 v[208:211], v166 offset:5120
	ds_read_b128 v[212:215], v166 offset:6144
	ds_read_b128 v[216:219], v166 offset:7168
	global_load_lds_dwordx4 v138, s[70:71]
	s_add_i32 m0, s33, 0xe000
	s_nop 0
	global_load_lds_dwordx4 v140, s[70:71]
	s_waitcnt vmcnt(8)
	s_waitcnt lgkmcnt(0)
	s_setprio 1
	s_barrier
	v_mfma_f32_16x16x32_bf16 v[124:127], v[148:151], v[188:191], v[124:127]
	v_mfma_f32_16x16x32_bf16 v[120:123], v[156:159], v[188:191], v[120:123]
	v_mfma_f32_16x16x32_bf16 v[116:119], v[148:151], v[196:199], v[116:119]
	v_mfma_f32_16x16x32_bf16 v[108:111], v[156:159], v[196:199], v[108:111]
	v_mfma_f32_16x16x32_bf16 v[100:103], v[148:151], v[204:207], v[100:103]
	v_mfma_f32_16x16x32_bf16 v[92:95], v[156:159], v[204:207], v[92:95]
	v_mfma_f32_16x16x32_bf16 v[84:87], v[148:151], v[212:215], v[84:87]
	v_mfma_f32_16x16x32_bf16 v[76:79], v[156:159], v[212:215], v[76:79]
	v_mfma_f32_16x16x32_bf16 v[124:127], v[152:155], v[192:195], v[124:127]
	v_mfma_f32_16x16x32_bf16 v[120:123], v[168:171], v[192:195], v[120:123]
	v_mfma_f32_16x16x32_bf16 v[116:119], v[152:155], v[200:203], v[116:119]
	v_mfma_f32_16x16x32_bf16 v[108:111], v[168:171], v[200:203], v[108:111]
	v_mfma_f32_16x16x32_bf16 v[100:103], v[152:155], v[208:211], v[100:103]
	v_mfma_f32_16x16x32_bf16 v[92:95], v[168:171], v[208:211], v[92:95]
	v_mfma_f32_16x16x32_bf16 v[84:87], v[152:155], v[216:219], v[84:87]
	v_mfma_f32_16x16x32_bf16 v[76:79], v[168:171], v[216:219], v[76:79]
	s_setprio 0
	s_setprio 1
	v_mfma_f32_16x16x32_bf16 v[112:115], v[172:175], v[188:191], v[112:115]
	v_mfma_f32_16x16x32_bf16 v[104:107], v[180:183], v[188:191], v[104:107]
	v_mfma_f32_16x16x32_bf16 v[96:99], v[172:175], v[196:199], v[96:99]
	v_mfma_f32_16x16x32_bf16 v[88:91], v[180:183], v[196:199], v[88:91]
	v_mfma_f32_16x16x32_bf16 v[80:83], v[172:175], v[204:207], v[80:83]
	v_mfma_f32_16x16x32_bf16 v[72:75], v[180:183], v[204:207], v[72:75]
	v_mfma_f32_16x16x32_bf16 v[68:71], v[172:175], v[212:215], v[68:71]
	v_mfma_f32_16x16x32_bf16 v[64:67], v[180:183], v[212:215], v[64:67]
	v_mfma_f32_16x16x32_bf16 v[112:115], v[176:179], v[192:195], v[112:115]
	v_mfma_f32_16x16x32_bf16 v[104:107], v[184:187], v[192:195], v[104:107]
	v_mfma_f32_16x16x32_bf16 v[96:99], v[176:179], v[200:203], v[96:99]
	v_mfma_f32_16x16x32_bf16 v[88:91], v[184:187], v[200:203], v[88:91]
	v_mfma_f32_16x16x32_bf16 v[80:83], v[176:179], v[208:211], v[80:83]
	v_mfma_f32_16x16x32_bf16 v[72:75], v[184:187], v[208:211], v[72:75]
	s_setprio 2
	s_barrier
	v_mfma_f32_16x16x32_bf16 v[68:71], v[176:179], v[216:219], v[68:71]
	v_mfma_f32_16x16x32_bf16 v[64:67], v[184:187], v[216:219], v[64:67]
	s_setprio 0
	s_add_i32 s52, s84, s3
	v_lshl_add_u64 v[220:221], s[72:73], 0, v[132:133]
	s_mov_b32 m0, s52
	ds_read_b128 v[188:191], v166 offset:16384
	ds_read_b128 v[192:195], v166 offset:17408
	ds_read_b128 v[196:199], v166 offset:18432
	ds_read_b128 v[200:203], v166 offset:19456
	ds_read_b128 v[204:207], v166 offset:20480
	ds_read_b128 v[208:211], v166 offset:21504
	ds_read_b128 v[212:215], v166 offset:22528
	ds_read_b128 v[216:219], v166 offset:23552
	global_load_lds_dwordx4 v[220:221], off
	s_add_i32 m0, s52, 0x2000
	s_add_u32 s96, s72, 0x80000
	v_lshl_add_u64 v[222:223], s[72:73], 0, v[128:129]
	s_addc_u32 s97, s73, 0
	s_add_i32 s52, s85, s3
	global_load_lds_dwordx4 v[222:223], off
	s_mov_b32 m0, s52
	v_lshl_add_u64 v[226:227], s[74:75], 0, v[130:131]
	global_load_lds_dwordx4 v132, s[96:97]
	s_add_i32 m0, s52, 0x2000
	s_nop 0
	global_load_lds_dwordx4 v128, s[96:97]
	s_mov_b32 m0, s33
	v_lshl_add_u64 v[224:225], s[74:75], 0, v[134:135]
	global_load_lds_dwordx4 v[224:225], off
	s_mov_b32 m0, s76
	s_nop 0
	global_load_lds_dwordx4 v[226:227], off
	s_waitcnt vmcnt(8)
	s_waitcnt lgkmcnt(0)
	s_setprio 1
	s_barrier
	v_mfma_f32_16x16x32_bf16 v[60:63], v[148:151], v[188:191], v[60:63]
	v_mfma_f32_16x16x32_bf16 v[56:59], v[156:159], v[188:191], v[56:59]
	v_mfma_f32_16x16x32_bf16 v[52:55], v[148:151], v[196:199], v[52:55]
	v_mfma_f32_16x16x32_bf16 v[44:47], v[156:159], v[196:199], v[44:47]
	v_mfma_f32_16x16x32_bf16 v[36:39], v[148:151], v[204:207], v[36:39]
	v_mfma_f32_16x16x32_bf16 v[28:31], v[156:159], v[204:207], v[28:31]
	v_mfma_f32_16x16x32_bf16 v[20:23], v[148:151], v[212:215], v[20:23]
	v_mfma_f32_16x16x32_bf16 v[12:15], v[156:159], v[212:215], v[12:15]
	v_mfma_f32_16x16x32_bf16 v[60:63], v[152:155], v[192:195], v[60:63]
	v_mfma_f32_16x16x32_bf16 v[56:59], v[168:171], v[192:195], v[56:59]
	v_mfma_f32_16x16x32_bf16 v[52:55], v[152:155], v[200:203], v[52:55]
	v_mfma_f32_16x16x32_bf16 v[44:47], v[168:171], v[200:203], v[44:47]
	v_mfma_f32_16x16x32_bf16 v[36:39], v[152:155], v[208:211], v[36:39]
	v_mfma_f32_16x16x32_bf16 v[28:31], v[168:171], v[208:211], v[28:31]
	v_mfma_f32_16x16x32_bf16 v[20:23], v[152:155], v[216:219], v[20:23]
	v_mfma_f32_16x16x32_bf16 v[12:15], v[168:171], v[216:219], v[12:15]
	s_setprio 0
	s_setprio 1
	v_mfma_f32_16x16x32_bf16 v[48:51], v[172:175], v[188:191], v[48:51]
	v_mfma_f32_16x16x32_bf16 v[40:43], v[180:183], v[188:191], v[40:43]
	v_mfma_f32_16x16x32_bf16 v[32:35], v[172:175], v[196:199], v[32:35]
	v_mfma_f32_16x16x32_bf16 v[24:27], v[180:183], v[196:199], v[24:27]
	v_mfma_f32_16x16x32_bf16 v[16:19], v[172:175], v[204:207], v[16:19]
	v_mfma_f32_16x16x32_bf16 v[8:11], v[180:183], v[204:207], v[8:11]
	v_mfma_f32_16x16x32_bf16 v[4:7], v[172:175], v[212:215], v[4:7]
	v_mfma_f32_16x16x32_bf16 v[0:3], v[180:183], v[212:215], v[0:3]
	v_mfma_f32_16x16x32_bf16 v[48:51], v[176:179], v[192:195], v[48:51]
	v_mfma_f32_16x16x32_bf16 v[40:43], v[184:187], v[192:195], v[40:43]
	v_mfma_f32_16x16x32_bf16 v[32:35], v[176:179], v[200:203], v[32:35]
	v_mfma_f32_16x16x32_bf16 v[24:27], v[184:187], v[200:203], v[24:27]
	v_mfma_f32_16x16x32_bf16 v[16:19], v[176:179], v[208:211], v[16:19]
	v_mfma_f32_16x16x32_bf16 v[8:11], v[184:187], v[208:211], v[8:11]
	s_setprio 2
	s_barrier
; #define PG8_STAGE(bufoff, gbase, voff) do { _Pragma("unroll") for (int _i = 0; _i < 2; ++_i) \
;         __builtin_amdgcn_global_load_lds((const unsigned*)((const char*)(gbase) + (voff)[_i]), (PG8_LAS unsigned*)(lds + (bufoff) + ldsw + _i * 8192), 16, 0, 0); } while (0)
; #define PG8_LDA(dst, b, h) do { _Pragma("unroll") for (int m = 0; m < 4; ++m) _Pragma("unroll") for (int k = 0; k < 2; ++k) dst[m][k] = *(const PG8_LAS bf16x8*)(lds + PG8_SA(b, h) + aoff + m * 2048 + k * 1024); } while (0)
; #define PG8_LDB(dst, b, h) do { _Pragma("unroll") for (int n = 0; n < 2; ++n) _Pragma("unroll") for (int k = 0; k < 2; ++k) dst[n][k] = *(const PG8_LAS bf16x8*)(lds + PG8_SB(b, h) + boff + n * 2048 + k * 1024); } while (0)
; #define PG8_MMA(ai, bj, At, Bt) do { __builtin_amdgcn_s_setprio(1); _Pragma("unroll") for (int m = 0; m < 4; ++m) _Pragma("unroll") for (int n = 0; n < 2; ++n) _Pragma("unroll") for (int k = 0; k < 2; ++k) \
;         acc[ai][bj][m][n] = __builtin_amdgcn_mfma_f32_16x16x32_bf16(Bt[n][k], At[m][k], acc[ai][bj][m][n], 0, 0, 0); __builtin_amdgcn_s_setprio(0); } while (0)
; #define PG8_WAIT_V(n) asm volatile("s_waitcnt vmcnt(" #n ")" ::: "memory")
; #define PG8_WAIT_L(n) asm volatile("s_waitcnt lgkmcnt(" #n ")" ::: "memory")
; #define PG8_BAR __builtin_amdgcn_s_barrier()
; #define PG8_SCHED __builtin_amdgcn_sched_barrier(0)
; template <class Epi, class Sched, bool ALIGN_EPI = false, bool SP2 = false>
; __device__ __forceinline__ void gemm_phase(PG8_LAS unsigned char* lds, const Gemm g, const Sched& S, const Epi& E) {
;     ...
;             PG8_WAIT_V(8); PG8_WAIT_L(0); PG8_BAR; PG8_MMA(1, 0, At, B0); PG8_MMA(1, 1, At, B1); PG8_BAR; PG8_SCHED;
;             PG8_LDB(B0, 1, 0); PG8_LDB(B1, 1, 1); PG8_SCHED; PG8_LDA(At, 1, 0); PG8_STAGE(PG8_SA(0, 1), a2 + hstep, voffA);
;             PG8_WAIT_V(8); PG8_WAIT_L(0); PG8_BAR; PG8_MMA(0, 0, At, B0); PG8_MMA(0, 1, At, B1); PG8_BAR; PG8_SCHED;
	v_mfma_f32_16x16x32_bf16 v[4:7], v[176:179], v[216:219], v[4:7]
	v_mfma_f32_16x16x32_bf16 v[0:3], v[184:187], v[216:219], v[0:3]
	s_setprio 0
	s_add_i32 s52, 0, 0x18000
	v_add_u32_e32 v136, s52, v161
	s_add_i32 s53, 0, 0x1c000
	ds_read_b128 v[148:151], v136
	ds_read_b128 v[152:155], v136 offset:1024
	ds_read_b128 v[156:159], v136 offset:2048
	ds_read_b128 v[168:171], v136 offset:3072
	v_add_u32_e32 v136, s53, v161
	ds_read_b128 v[172:175], v136
	ds_read_b128 v[176:179], v136 offset:1024
	ds_read_b128 v[180:183], v136 offset:2048
	ds_read_b128 v[184:187], v136 offset:3072
	s_add_u32 s74, s74, 0x80000
	s_addc_u32 s75, s75, 0
	s_mov_b32 m0, s77
	ds_read_b128 v[188:191], v166 offset:32768
	ds_read_b128 v[192:195], v166 offset:33792
	ds_read_b128 v[196:199], v166 offset:34816
	ds_read_b128 v[200:203], v166 offset:35840
	ds_read_b128 v[204:207], v166 offset:36864
	ds_read_b128 v[208:211], v166 offset:37888
	ds_read_b128 v[212:215], v166 offset:38912
	ds_read_b128 v[216:219], v166 offset:39936
	global_load_lds_dwordx4 v134, s[74:75]
	s_mov_b32 m0, s78
	s_nop 0
	global_load_lds_dwordx4 v130, s[74:75]
	s_waitcnt vmcnt(8)
	s_waitcnt lgkmcnt(0)
	s_setprio 1
	s_barrier
	v_mfma_f32_16x16x32_bf16 v[124:127], v[148:151], v[188:191], v[124:127]
	v_mfma_f32_16x16x32_bf16 v[120:123], v[156:159], v[188:191], v[120:123]
	v_mfma_f32_16x16x32_bf16 v[116:119], v[148:151], v[196:199], v[116:119]
	v_mfma_f32_16x16x32_bf16 v[108:111], v[156:159], v[196:199], v[108:111]
	v_mfma_f32_16x16x32_bf16 v[100:103], v[148:151], v[204:207], v[100:103]
	v_mfma_f32_16x16x32_bf16 v[92:95], v[156:159], v[204:207], v[92:95]
	v_mfma_f32_16x16x32_bf16 v[84:87], v[148:151], v[212:215], v[84:87]
	v_mfma_f32_16x16x32_bf16 v[76:79], v[156:159], v[212:215], v[76:79]
	v_mfma_f32_16x16x32_bf16 v[124:127], v[152:155], v[192:195], v[124:127]
	v_mfma_f32_16x16x32_bf16 v[120:123], v[168:171], v[192:195], v[120:123]
	v_mfma_f32_16x16x32_bf16 v[116:119], v[152:155], v[200:203], v[116:119]
	v_mfma_f32_16x16x32_bf16 v[108:111], v[168:171], v[200:203], v[108:111]
	v_mfma_f32_16x16x32_bf16 v[100:103], v[152:155], v[208:211], v[100:103]
	v_mfma_f32_16x16x32_bf16 v[92:95], v[168:171], v[208:211], v[92:95]
	v_mfma_f32_16x16x32_bf16 v[84:87], v[152:155], v[216:219], v[84:87]
	v_mfma_f32_16x16x32_bf16 v[76:79], v[168:171], v[216:219], v[76:79]
	s_setprio 0
	s_setprio 1
	v_mfma_f32_16x16x32_bf16 v[112:115], v[172:175], v[188:191], v[112:115]
	v_mfma_f32_16x16x32_bf16 v[104:107], v[180:183], v[188:191], v[104:107]
	v_mfma_f32_16x16x32_bf16 v[96:99], v[172:175], v[196:199], v[96:99]
	v_mfma_f32_16x16x32_bf16 v[88:91], v[180:183], v[196:199], v[88:91]
	v_mfma_f32_16x16x32_bf16 v[80:83], v[172:175], v[204:207], v[80:83]
	v_mfma_f32_16x16x32_bf16 v[72:75], v[180:183], v[204:207], v[72:75]
	v_mfma_f32_16x16x32_bf16 v[68:71], v[172:175], v[212:215], v[68:71]
	v_mfma_f32_16x16x32_bf16 v[64:67], v[180:183], v[212:215], v[64:67]
	v_mfma_f32_16x16x32_bf16 v[112:115], v[176:179], v[192:195], v[112:115]
	v_mfma_f32_16x16x32_bf16 v[104:107], v[184:187], v[192:195], v[104:107]
	v_mfma_f32_16x16x32_bf16 v[96:99], v[176:179], v[200:203], v[96:99]
	v_mfma_f32_16x16x32_bf16 v[88:91], v[184:187], v[200:203], v[88:91]
	v_mfma_f32_16x16x32_bf16 v[80:83], v[176:179], v[208:211], v[80:83]
	v_mfma_f32_16x16x32_bf16 v[72:75], v[184:187], v[208:211], v[72:75]
	s_setprio 2
	s_barrier
; #define PG8_STAGE(bufoff, gbase, voff) do { _Pragma("unroll") for (int _i = 0; _i < 2; ++_i) \
;         __builtin_amdgcn_global_load_lds((const unsigned*)((const char*)(gbase) + (voff)[_i]), (PG8_LAS unsigned*)(lds + (bufoff) + ldsw + _i * 8192), 16, 0, 0); } while (0)
; #define PG8_LDA(dst, b, h) do { _Pragma("unroll") for (int m = 0; m < 4; ++m) _Pragma("unroll") for (int k = 0; k < 2; ++k) dst[m][k] = *(const PG8_LAS bf16x8*)(lds + PG8_SA(b, h) + aoff + m * 2048 + k * 1024); } while (0)
; #define PG8_MMA(ai, bj, At, Bt) do { __builtin_amdgcn_s_setprio(1); _Pragma("unroll") for (int m = 0; m < 4; ++m) _Pragma("unroll") for (int n = 0; n < 2; ++n) _Pragma("unroll") for (int k = 0; k < 2; ++k) \
;         acc[ai][bj][m][n] = __builtin_amdgcn_mfma_f32_16x16x32_bf16(Bt[n][k], At[m][k], acc[ai][bj][m][n], 0, 0, 0); __builtin_amdgcn_s_setprio(0); } while (0)
; #define PG8_WAIT_V(n) asm volatile("s_waitcnt vmcnt(" #n ")" ::: "memory")
; #define PG8_WAIT_L(n) asm volatile("s_waitcnt lgkmcnt(" #n ")" ::: "memory")
; #define PG8_BAR __builtin_amdgcn_s_barrier()
; #define PG8_SCHED __builtin_amdgcn_sched_barrier(0)
; template <class Epi, class Sched, bool ALIGN_EPI = false, bool SP2 = false>
; __device__ __forceinline__ void gemm_phase(PG8_LAS unsigned char* lds, const Gemm g, const Sched& S, const Epi& E) {
;     ...
;             PG8_WAIT_V(8); PG8_WAIT_L(0); PG8_BAR; PG8_MMA(0, 0, At, B0); PG8_MMA(0, 1, At, B1); PG8_BAR; PG8_SCHED;
;             PG8_LDA(At, 1, 1); PG8_STAGE(PG8_SB(1, 0), b3, voffB); PG8_STAGE(PG8_SB(1, 1), b3 + hstep, voffB); PG8_STAGE(PG8_SA(1, 0), a3, voffA);
;             PG8_WAIT_V(8); PG8_WAIT_L(0); PG8_BAR; PG8_MMA(1, 0, At, B0); PG8_MMA(1, 1, At, B1); PG8_BAR; PG8_SCHED;
	v_mfma_f32_16x16x32_bf16 v[68:71], v[176:179], v[216:219], v[68:71]
	v_mfma_f32_16x16x32_bf16 v[64:67], v[184:187], v[216:219], v[64:67]
	s_setprio 0
	s_add_i32 s52, s52, s3
	v_lshl_add_u64 v[220:221], v[220:221], 0, s[12:13]
	s_mov_b32 m0, s52
	ds_read_b128 v[188:191], v166 offset:49152
	ds_read_b128 v[192:195], v166 offset:50176
	ds_read_b128 v[196:199], v166 offset:51200
	ds_read_b128 v[200:203], v166 offset:52224
	ds_read_b128 v[204:207], v166 offset:53248
	ds_read_b128 v[208:211], v166 offset:54272
	ds_read_b128 v[212:215], v166 offset:55296
	ds_read_b128 v[216:219], v166 offset:56320
	global_load_lds_dwordx4 v[220:221], off
	s_add_i32 m0, s52, 0x2000
	s_add_u32 s72, s72, 0x80080
	v_lshl_add_u64 v[220:221], v[222:223], 0, s[12:13]
	s_addc_u32 s73, s73, 0
	s_add_i32 s52, s53, s3
	global_load_lds_dwordx4 v[220:221], off
	s_mov_b32 m0, s52
	s_nop 0
	global_load_lds_dwordx4 v132, s[72:73]
	s_add_i32 m0, s52, 0x2000
	s_nop 0
	global_load_lds_dwordx4 v128, s[72:73]
	s_mov_b32 m0, s80
	v_lshl_add_u64 v[220:221], v[224:225], 0, s[12:13]
	global_load_lds_dwordx4 v[220:221], off
	s_mov_b32 m0, s81
	v_lshl_add_u64 v[220:221], v[226:227], 0, s[12:13]
	global_load_lds_dwordx4 v[220:221], off
	s_waitcnt vmcnt(8)
	s_waitcnt lgkmcnt(0)
	s_setprio 1
	s_barrier
	v_mfma_f32_16x16x32_bf16 v[60:63], v[148:151], v[188:191], v[60:63]
	v_mfma_f32_16x16x32_bf16 v[56:59], v[156:159], v[188:191], v[56:59]
	v_mfma_f32_16x16x32_bf16 v[52:55], v[148:151], v[196:199], v[52:55]
	v_mfma_f32_16x16x32_bf16 v[44:47], v[156:159], v[196:199], v[44:47]
	v_mfma_f32_16x16x32_bf16 v[36:39], v[148:151], v[204:207], v[36:39]
	v_mfma_f32_16x16x32_bf16 v[28:31], v[156:159], v[204:207], v[28:31]
	v_mfma_f32_16x16x32_bf16 v[20:23], v[148:151], v[212:215], v[20:23]
	v_mfma_f32_16x16x32_bf16 v[12:15], v[156:159], v[212:215], v[12:15]
	v_mfma_f32_16x16x32_bf16 v[60:63], v[152:155], v[192:195], v[60:63]
	v_mfma_f32_16x16x32_bf16 v[56:59], v[168:171], v[192:195], v[56:59]
	v_mfma_f32_16x16x32_bf16 v[52:55], v[152:155], v[200:203], v[52:55]
	v_mfma_f32_16x16x32_bf16 v[44:47], v[168:171], v[200:203], v[44:47]
	v_mfma_f32_16x16x32_bf16 v[36:39], v[152:155], v[208:211], v[36:39]
	v_mfma_f32_16x16x32_bf16 v[28:31], v[168:171], v[208:211], v[28:31]
	v_mfma_f32_16x16x32_bf16 v[20:23], v[152:155], v[216:219], v[20:23]
	v_mfma_f32_16x16x32_bf16 v[12:15], v[168:171], v[216:219], v[12:15]
	s_setprio 0
	s_setprio 1
	v_mfma_f32_16x16x32_bf16 v[48:51], v[172:175], v[188:191], v[48:51]
	v_mfma_f32_16x16x32_bf16 v[40:43], v[180:183], v[188:191], v[40:43]
	v_mfma_f32_16x16x32_bf16 v[32:35], v[172:175], v[196:199], v[32:35]
	v_mfma_f32_16x16x32_bf16 v[24:27], v[180:183], v[196:199], v[24:27]
	v_mfma_f32_16x16x32_bf16 v[16:19], v[172:175], v[204:207], v[16:19]
	v_mfma_f32_16x16x32_bf16 v[8:11], v[180:183], v[204:207], v[8:11]
	v_mfma_f32_16x16x32_bf16 v[4:7], v[172:175], v[212:215], v[4:7]
	v_mfma_f32_16x16x32_bf16 v[0:3], v[180:183], v[212:215], v[0:3]
	v_mfma_f32_16x16x32_bf16 v[48:51], v[176:179], v[192:195], v[48:51]
	v_mfma_f32_16x16x32_bf16 v[40:43], v[184:187], v[192:195], v[40:43]
	v_mfma_f32_16x16x32_bf16 v[32:35], v[176:179], v[200:203], v[32:35]
	v_mfma_f32_16x16x32_bf16 v[24:27], v[184:187], v[200:203], v[24:27]
	v_mfma_f32_16x16x32_bf16 v[16:19], v[176:179], v[208:211], v[16:19]
	v_mfma_f32_16x16x32_bf16 v[8:11], v[184:187], v[208:211], v[8:11]
	s_setprio 2
	s_barrier
	v_mfma_f32_16x16x32_bf16 v[4:7], v[176:179], v[216:219], v[4:7]
	v_mfma_f32_16x16x32_bf16 v[0:3], v[184:187], v[216:219], v[0:3]
	s_setprio 0
	s_add_i32 s93, s93, 2
	s_add_u32 s70, s70, 0x100
	s_addc_u32 s71, s71, 0
	s_add_u32 s91, s91, 0x100
	s_addc_u32 s92, s92, 0
	s_cmp_gt_u32 s93, 29
	s_cbranch_scc0 .LBB0_200
	s_and_b64 vcc, exec, s[14:15]
	s_cbranch_vccz .LBB0_203
	s_barrier

; #define PG8_STAGE(bufoff, gbase, voff) do { _Pragma("unroll") for (int _i = 0; _i < 2; ++_i) \
;         __builtin_amdgcn_global_load_lds((const unsigned*)((const char*)(gbase) + (voff)[_i]), (PG8_LAS unsigned*)(lds + (bufoff) + ldsw + _i * 8192), 16, 0, 0); } while (0)
; #define PG8_LDA(dst, b, h) do { _Pragma("unroll") for (int m = 0; m < 4; ++m) _Pragma("unroll") for (int k = 0; k < 2; ++k) dst[m][k] = *(const PG8_LAS bf16x8*)(lds + PG8_SA(b, h) + aoff + m * 2048 + k * 1024); } while (0)
; #define PG8_LDB(dst, b, h) do { _Pragma("unroll") for (int n = 0; n < 2; ++n) _Pragma("unroll") for (int k = 0; k < 2; ++k) dst[n][k] = *(const PG8_LAS bf16x8*)(lds + PG8_SB(b, h) + boff + n * 2048 + k * 1024); } while (0)
; #define PG8_MMA(ai, bj, At, Bt) do { __builtin_amdgcn_s_setprio(1); _Pragma("unroll") for (int m = 0; m < 4; ++m) _Pragma("unroll") for (int n = 0; n < 2; ++n) _Pragma("unroll") for (int k = 0; k < 2; ++k) \
;         acc[ai][bj][m][n] = __builtin_amdgcn_mfma_f32_16x16x32_bf16(Bt[n][k], At[m][k], acc[ai][bj][m][n], 0, 0, 0); __builtin_amdgcn_s_setprio(0); } while (0)
; #define PG8_WAIT_V(n) asm volatile("s_waitcnt vmcnt(" #n ")" ::: "memory")
; #define PG8_WAIT_L(n) asm volatile("s_waitcnt lgkmcnt(" #n ")" ::: "memory")
; #define PG8_BAR __builtin_amdgcn_s_barrier()
; #define PG8_SCHED __builtin_amdgcn_sched_barrier(0)
; template <class Epi, class Sched, bool ALIGN_EPI = false, bool SP2 = false>
; __device__ __forceinline__ void gemm_phase(PG8_LAS unsigned char* lds, const Gemm g, const Sched& S, const Epi& E) {
;     ...
;             const char* a1 = cA + (size_t)(t + 1) * kstep;
;             const char* a2 = last ? nA : cA + (size_t)(t + 2) * kstep; const char* b2 = last ? nB : cB + (size_t)(t + 2) * kstep;
;             const char* a3 = a2 + kstep; const char* b3 = b2 + kstep;
;             if constexpr (SP2) {
;             PG8_LDB(B0, 0, 0); PG8_LDB(B1, 0, 1); PG8_SCHED; PG8_LDA(At, 0, 0); PG8_STAGE(PG8_SA(1, 1), a1 + hstep, voffA);
;             PG8_WAIT_V(8); PG8_WAIT_L(0); PG8_BAR; PG8_MMA(0, 0, At, B0); PG8_MMA(0, 1, At, B1); PG8_BAR; PG8_SCHED;
;             PG8_LDA(At, 0, 1); PG8_STAGE(PG8_SB(0, 0), b2, voffB); PG8_STAGE(PG8_SB(0, 1), b2 + hstep, voffB); PG8_STAGE(PG8_SA(0, 0), a2, voffA);
;             PG8_WAIT_V(8); PG8_WAIT_L(0); PG8_BAR; PG8_MMA(1, 0, At, B0); PG8_MMA(1, 1, At, B1); PG8_BAR; PG8_SCHED;
.LBB0_374:
	ds_read_b128 v[128:131], v230
	ds_read_b128 v[132:135], v230 offset:1024
	ds_read_b128 v[158:161], v230 offset:2048
	ds_read_b128 v[162:165], v230 offset:3072
	ds_read_b128 v[166:169], v231
	ds_read_b128 v[170:173], v231 offset:1024
	ds_read_b128 v[174:177], v231 offset:2048
	ds_read_b128 v[178:181], v231 offset:3072
	s_add_u32 s52, s76, 0xfff80080
	s_addc_u32 s53, s77, -1
	s_cmp_eq_u32 vcc_hi, 28
	s_cselect_b32 s81, s11, s53
	s_cselect_b32 s80, s55, s52
	s_cselect_b32 s79, s51, vcc_lo
	s_cselect_b32 s78, s73, s75
	s_add_i32 m0, s28, 0xc000
	ds_read_b128 v[182:185], v232
	ds_read_b128 v[186:189], v232 offset:1024
	ds_read_b128 v[190:193], v232 offset:2048
	ds_read_b128 v[194:197], v232 offset:3072
	ds_read_b128 v[198:201], v232 offset:4096
	ds_read_b128 v[202:205], v232 offset:5120
	ds_read_b128 v[206:209], v232 offset:6144
	ds_read_b128 v[210:213], v232 offset:7168
	global_load_lds_dwordx4 v150, s[76:77]
	s_add_i32 m0, s28, 0xe000
	s_nop 0
	global_load_lds_dwordx4 v152, s[76:77]
	s_waitcnt vmcnt(8)
	s_waitcnt lgkmcnt(0)
	s_setprio 1
	s_barrier
	v_mfma_f32_16x16x32_bf16 v[124:127], v[128:131], v[182:185], v[124:127]
	v_mfma_f32_16x16x32_bf16 v[120:123], v[158:161], v[182:185], v[120:123]
	v_mfma_f32_16x16x32_bf16 v[116:119], v[128:131], v[190:193], v[116:119]
	v_mfma_f32_16x16x32_bf16 v[112:115], v[158:161], v[190:193], v[112:115]
	v_mfma_f32_16x16x32_bf16 v[108:111], v[128:131], v[198:201], v[108:111]
	v_mfma_f32_16x16x32_bf16 v[104:107], v[158:161], v[198:201], v[104:107]
	v_mfma_f32_16x16x32_bf16 v[100:103], v[128:131], v[206:209], v[100:103]
	v_mfma_f32_16x16x32_bf16 v[96:99], v[158:161], v[206:209], v[96:99]
	v_mfma_f32_16x16x32_bf16 v[124:127], v[132:135], v[186:189], v[124:127]
	v_mfma_f32_16x16x32_bf16 v[120:123], v[162:165], v[186:189], v[120:123]
	v_mfma_f32_16x16x32_bf16 v[116:119], v[132:135], v[194:197], v[116:119]
	v_mfma_f32_16x16x32_bf16 v[112:115], v[162:165], v[194:197], v[112:115]
	v_mfma_f32_16x16x32_bf16 v[108:111], v[132:135], v[202:205], v[108:111]
	v_mfma_f32_16x16x32_bf16 v[104:107], v[162:165], v[202:205], v[104:107]
	v_mfma_f32_16x16x32_bf16 v[100:103], v[132:135], v[210:213], v[100:103]
	v_mfma_f32_16x16x32_bf16 v[96:99], v[162:165], v[210:213], v[96:99]
	s_setprio 0
	s_setprio 1
	v_mfma_f32_16x16x32_bf16 v[60:63], v[166:169], v[182:185], v[60:63]
	v_mfma_f32_16x16x32_bf16 v[56:59], v[174:177], v[182:185], v[56:59]
	v_mfma_f32_16x16x32_bf16 v[52:55], v[166:169], v[190:193], v[52:55]
	v_mfma_f32_16x16x32_bf16 v[48:51], v[174:177], v[190:193], v[48:51]
	v_mfma_f32_16x16x32_bf16 v[44:47], v[166:169], v[198:201], v[44:47]
	v_mfma_f32_16x16x32_bf16 v[40:43], v[174:177], v[198:201], v[40:43]
	v_mfma_f32_16x16x32_bf16 v[36:39], v[166:169], v[206:209], v[36:39]
	v_mfma_f32_16x16x32_bf16 v[32:35], v[174:177], v[206:209], v[32:35]
	v_mfma_f32_16x16x32_bf16 v[60:63], v[170:173], v[186:189], v[60:63]
	v_mfma_f32_16x16x32_bf16 v[56:59], v[178:181], v[186:189], v[56:59]
	v_mfma_f32_16x16x32_bf16 v[52:55], v[170:173], v[194:197], v[52:55]
	v_mfma_f32_16x16x32_bf16 v[48:51], v[178:181], v[194:197], v[48:51]
	v_mfma_f32_16x16x32_bf16 v[44:47], v[170:173], v[202:205], v[44:47]
	v_mfma_f32_16x16x32_bf16 v[40:43], v[178:181], v[202:205], v[40:43]
	s_setprio 2
	s_barrier
	v_mfma_f32_16x16x32_bf16 v[36:39], v[170:173], v[210:213], v[36:39]
	v_mfma_f32_16x16x32_bf16 v[32:35], v[178:181], v[210:213], v[32:35]
	s_setprio 0
	s_add_i32 s52, s93, s3
	v_lshl_add_u64 v[214:215], s[78:79], 0, v[138:139]
	s_mov_b32 m0, s52
	ds_read_b128 v[182:185], v232 offset:16384
	ds_read_b128 v[186:189], v232 offset:17408
	ds_read_b128 v[190:193], v232 offset:18432
	ds_read_b128 v[194:197], v232 offset:19456
	ds_read_b128 v[198:201], v232 offset:20480
	ds_read_b128 v[202:205], v232 offset:21504
	ds_read_b128 v[206:209], v232 offset:22528
	ds_read_b128 v[210:213], v232 offset:23552
	global_load_lds_dwordx4 v[214:215], off
	s_add_i32 m0, s52, 0x2000
	s_add_u32 s52, s78, 0x80000
	v_lshl_add_u64 v[216:217], s[78:79], 0, v[142:143]
	s_addc_u32 s53, s79, 0
	s_add_i32 s56, s10, s3
	global_load_lds_dwordx4 v[216:217], off
	s_mov_b32 m0, s56
	v_lshl_add_u64 v[220:221], s[80:81], 0, v[140:141]
	global_load_lds_dwordx4 v138, s[52:53]
	s_add_i32 m0, s56, 0x2000
	s_nop 0
	global_load_lds_dwordx4 v142, s[52:53]
	s_mov_b32 m0, s28
	v_lshl_add_u64 v[218:219], s[80:81], 0, v[136:137]
	global_load_lds_dwordx4 v[218:219], off
	s_mov_b32 m0, s29
	s_nop 0
	global_load_lds_dwordx4 v[220:221], off
	s_waitcnt vmcnt(8)
	s_waitcnt lgkmcnt(0)
	s_setprio 1
	s_barrier
	v_mfma_f32_16x16x32_bf16 v[92:95], v[128:131], v[182:185], v[92:95]
	v_mfma_f32_16x16x32_bf16 v[88:91], v[158:161], v[182:185], v[88:91]
	v_mfma_f32_16x16x32_bf16 v[84:87], v[128:131], v[190:193], v[84:87]
	v_mfma_f32_16x16x32_bf16 v[80:83], v[158:161], v[190:193], v[80:83]
	v_mfma_f32_16x16x32_bf16 v[76:79], v[128:131], v[198:201], v[76:79]
	v_mfma_f32_16x16x32_bf16 v[72:75], v[158:161], v[198:201], v[72:75]
	v_mfma_f32_16x16x32_bf16 v[68:71], v[128:131], v[206:209], v[68:71]
	v_mfma_f32_16x16x32_bf16 v[64:67], v[158:161], v[206:209], v[64:67]
	v_mfma_f32_16x16x32_bf16 v[92:95], v[132:135], v[186:189], v[92:95]
	v_mfma_f32_16x16x32_bf16 v[88:91], v[162:165], v[186:189], v[88:91]
	v_mfma_f32_16x16x32_bf16 v[84:87], v[132:135], v[194:197], v[84:87]
	v_mfma_f32_16x16x32_bf16 v[80:83], v[162:165], v[194:197], v[80:83]
	v_mfma_f32_16x16x32_bf16 v[76:79], v[132:135], v[202:205], v[76:79]
	v_mfma_f32_16x16x32_bf16 v[72:75], v[162:165], v[202:205], v[72:75]
	v_mfma_f32_16x16x32_bf16 v[68:71], v[132:135], v[210:213], v[68:71]
	v_mfma_f32_16x16x32_bf16 v[64:67], v[162:165], v[210:213], v[64:67]
	s_setprio 0
	s_setprio 1
	v_mfma_f32_16x16x32_bf16 v[28:31], v[166:169], v[182:185], v[28:31]
	v_mfma_f32_16x16x32_bf16 v[24:27], v[174:177], v[182:185], v[24:27]
	v_mfma_f32_16x16x32_bf16 v[20:23], v[166:169], v[190:193], v[20:23]
	v_mfma_f32_16x16x32_bf16 v[16:19], v[174:177], v[190:193], v[16:19]
	v_mfma_f32_16x16x32_bf16 v[12:15], v[166:169], v[198:201], v[12:15]
	v_mfma_f32_16x16x32_bf16 v[8:11], v[174:177], v[198:201], v[8:11]
	v_mfma_f32_16x16x32_bf16 v[4:7], v[166:169], v[206:209], v[4:7]
	v_mfma_f32_16x16x32_bf16 v[0:3], v[174:177], v[206:209], v[0:3]
	v_mfma_f32_16x16x32_bf16 v[28:31], v[170:173], v[186:189], v[28:31]
	v_mfma_f32_16x16x32_bf16 v[24:27], v[178:181], v[186:189], v[24:27]
	v_mfma_f32_16x16x32_bf16 v[20:23], v[170:173], v[194:197], v[20:23]
	v_mfma_f32_16x16x32_bf16 v[16:19], v[178:181], v[194:197], v[16:19]
	v_mfma_f32_16x16x32_bf16 v[12:15], v[170:173], v[202:205], v[12:15]
	v_mfma_f32_16x16x32_bf16 v[8:11], v[178:181], v[202:205], v[8:11]
	s_setprio 2
	s_barrier
; #define PG8_STAGE(bufoff, gbase, voff) do { _Pragma("unroll") for (int _i = 0; _i < 2; ++_i) \
;         __builtin_amdgcn_global_load_lds((const unsigned*)((const char*)(gbase) + (voff)[_i]), (PG8_LAS unsigned*)(lds + (bufoff) + ldsw + _i * 8192), 16, 0, 0); } while (0)
; #define PG8_LDA(dst, b, h) do { _Pragma("unroll") for (int m = 0; m < 4; ++m) _Pragma("unroll") for (int k = 0; k < 2; ++k) dst[m][k] = *(const PG8_LAS bf16x8*)(lds + PG8_SA(b, h) + aoff + m * 2048 + k * 1024); } while (0)
; #define PG8_LDB(dst, b, h) do { _Pragma("unroll") for (int n = 0; n < 2; ++n) _Pragma("unroll") for (int k = 0; k < 2; ++k) dst[n][k] = *(const PG8_LAS bf16x8*)(lds + PG8_SB(b, h) + boff + n * 2048 + k * 1024); } while (0)
; #define PG8_MMA(ai, bj, At, Bt) do { __builtin_amdgcn_s_setprio(1); _Pragma("unroll") for (int m = 0; m < 4; ++m) _Pragma("unroll") for (int n = 0; n < 2; ++n) _Pragma("unroll") for (int k = 0; k < 2; ++k) \
;         acc[ai][bj][m][n] = __builtin_amdgcn_mfma_f32_16x16x32_bf16(Bt[n][k], At[m][k], acc[ai][bj][m][n], 0, 0, 0); __builtin_amdgcn_s_setprio(0); } while (0)
; #define PG8_WAIT_V(n) asm volatile("s_waitcnt vmcnt(" #n ")" ::: "memory")
; #define PG8_WAIT_L(n) asm volatile("s_waitcnt lgkmcnt(" #n ")" ::: "memory")
; #define PG8_BAR __builtin_amdgcn_s_barrier()
; #define PG8_SCHED __builtin_amdgcn_sched_barrier(0)
; template <class Epi, class Sched, bool ALIGN_EPI = false, bool SP2 = false>
; __device__ __forceinline__ void gemm_phase(PG8_LAS unsigned char* lds, const Gemm g, const Sched& S, const Epi& E) {
;     ...
;             PG8_WAIT_V(8); PG8_WAIT_L(0); PG8_BAR; PG8_MMA(1, 0, At, B0); PG8_MMA(1, 1, At, B1); PG8_BAR; PG8_SCHED;
;             PG8_LDB(B0, 1, 0); PG8_LDB(B1, 1, 1); PG8_SCHED; PG8_LDA(At, 1, 0); PG8_STAGE(PG8_SA(0, 1), a2 + hstep, voffA);
;             PG8_WAIT_V(8); PG8_WAIT_L(0); PG8_BAR; PG8_MMA(0, 0, At, B0); PG8_MMA(0, 1, At, B1); PG8_BAR; PG8_SCHED;
	v_mfma_f32_16x16x32_bf16 v[4:7], v[170:173], v[210:213], v[4:7]
	v_mfma_f32_16x16x32_bf16 v[0:3], v[178:181], v[210:213], v[0:3]
	s_setprio 0
	s_add_i32 s56, 0, 0x18000
	s_add_i32 s57, 0, 0x1c000
	v_add_u32_e32 v162, s56, v228
	v_add_u32_e32 v178, s57, v228
	ds_read_b128 v[128:131], v162
	ds_read_b128 v[132:135], v162 offset:1024
	ds_read_b128 v[158:161], v162 offset:2048
	ds_read_b128 v[162:165], v162 offset:3072
	ds_read_b128 v[166:169], v178
	ds_read_b128 v[170:173], v178 offset:1024
	ds_read_b128 v[174:177], v178 offset:2048
	ds_read_b128 v[178:181], v178 offset:3072
	s_add_u32 s52, s80, 0x80000
	s_addc_u32 s53, s81, 0
	s_mov_b32 m0, s33
	ds_read_b128 v[182:185], v232 offset:32768
	ds_read_b128 v[186:189], v232 offset:33792
	ds_read_b128 v[190:193], v232 offset:34816
	ds_read_b128 v[194:197], v232 offset:35840
	ds_read_b128 v[198:201], v232 offset:36864
	ds_read_b128 v[202:205], v232 offset:37888
	ds_read_b128 v[206:209], v232 offset:38912
	ds_read_b128 v[210:213], v232 offset:39936
	global_load_lds_dwordx4 v136, s[52:53]
	s_mov_b32 m0, s38
	s_nop 0
	global_load_lds_dwordx4 v140, s[52:53]
	s_waitcnt vmcnt(8)
	s_waitcnt lgkmcnt(0)
	s_setprio 1
	s_barrier
	v_mfma_f32_16x16x32_bf16 v[124:127], v[128:131], v[182:185], v[124:127]
	v_mfma_f32_16x16x32_bf16 v[120:123], v[158:161], v[182:185], v[120:123]
	v_mfma_f32_16x16x32_bf16 v[116:119], v[128:131], v[190:193], v[116:119]
	v_mfma_f32_16x16x32_bf16 v[112:115], v[158:161], v[190:193], v[112:115]
	v_mfma_f32_16x16x32_bf16 v[108:111], v[128:131], v[198:201], v[108:111]
	v_mfma_f32_16x16x32_bf16 v[104:107], v[158:161], v[198:201], v[104:107]
	v_mfma_f32_16x16x32_bf16 v[100:103], v[128:131], v[206:209], v[100:103]
	v_mfma_f32_16x16x32_bf16 v[96:99], v[158:161], v[206:209], v[96:99]
	v_mfma_f32_16x16x32_bf16 v[124:127], v[132:135], v[186:189], v[124:127]
	v_mfma_f32_16x16x32_bf16 v[120:123], v[162:165], v[186:189], v[120:123]
	v_mfma_f32_16x16x32_bf16 v[116:119], v[132:135], v[194:197], v[116:119]
	v_mfma_f32_16x16x32_bf16 v[112:115], v[162:165], v[194:197], v[112:115]
	v_mfma_f32_16x16x32_bf16 v[108:111], v[132:135], v[202:205], v[108:111]
	v_mfma_f32_16x16x32_bf16 v[104:107], v[162:165], v[202:205], v[104:107]
	v_mfma_f32_16x16x32_bf16 v[100:103], v[132:135], v[210:213], v[100:103]
	v_mfma_f32_16x16x32_bf16 v[96:99], v[162:165], v[210:213], v[96:99]
	s_setprio 0
	s_setprio 1
	v_mfma_f32_16x16x32_bf16 v[60:63], v[166:169], v[182:185], v[60:63]
	v_mfma_f32_16x16x32_bf16 v[56:59], v[174:177], v[182:185], v[56:59]
	v_mfma_f32_16x16x32_bf16 v[52:55], v[166:169], v[190:193], v[52:55]
	v_mfma_f32_16x16x32_bf16 v[48:51], v[174:177], v[190:193], v[48:51]
	v_mfma_f32_16x16x32_bf16 v[44:47], v[166:169], v[198:201], v[44:47]
	v_mfma_f32_16x16x32_bf16 v[40:43], v[174:177], v[198:201], v[40:43]
	v_mfma_f32_16x16x32_bf16 v[36:39], v[166:169], v[206:209], v[36:39]
	v_mfma_f32_16x16x32_bf16 v[32:35], v[174:177], v[206:209], v[32:35]
	v_mfma_f32_16x16x32_bf16 v[60:63], v[170:173], v[186:189], v[60:63]
	v_mfma_f32_16x16x32_bf16 v[56:59], v[178:181], v[186:189], v[56:59]
	v_mfma_f32_16x16x32_bf16 v[52:55], v[170:173], v[194:197], v[52:55]
	v_mfma_f32_16x16x32_bf16 v[48:51], v[178:181], v[194:197], v[48:51]
	v_mfma_f32_16x16x32_bf16 v[44:47], v[170:173], v[202:205], v[44:47]
	v_mfma_f32_16x16x32_bf16 v[40:43], v[178:181], v[202:205], v[40:43]
	s_setprio 2
	s_barrier
; #define PG8_STAGE(bufoff, gbase, voff) do { _Pragma("unroll") for (int _i = 0; _i < 2; ++_i) \
;         __builtin_amdgcn_global_load_lds((const unsigned*)((const char*)(gbase) + (voff)[_i]), (PG8_LAS unsigned*)(lds + (bufoff) + ldsw + _i * 8192), 16, 0, 0); } while (0)
; #define PG8_LDA(dst, b, h) do { _Pragma("unroll") for (int m = 0; m < 4; ++m) _Pragma("unroll") for (int k = 0; k < 2; ++k) dst[m][k] = *(const PG8_LAS bf16x8*)(lds + PG8_SA(b, h) + aoff + m * 2048 + k * 1024); } while (0)
; #define PG8_MMA(ai, bj, At, Bt) do { __builtin_amdgcn_s_setprio(1); _Pragma("unroll") for (int m = 0; m < 4; ++m) _Pragma("unroll") for (int n = 0; n < 2; ++n) _Pragma("unroll") for (int k = 0; k < 2; ++k) \
;         acc[ai][bj][m][n] = __builtin_amdgcn_mfma_f32_16x16x32_bf16(Bt[n][k], At[m][k], acc[ai][bj][m][n], 0, 0, 0); __builtin_amdgcn_s_setprio(0); } while (0)
; #define PG8_WAIT_V(n) asm volatile("s_waitcnt vmcnt(" #n ")" ::: "memory")
; #define PG8_WAIT_L(n) asm volatile("s_waitcnt lgkmcnt(" #n ")" ::: "memory")
; #define PG8_BAR __builtin_amdgcn_s_barrier()
; #define PG8_SCHED __builtin_amdgcn_sched_barrier(0)
; template <class Epi, class Sched, bool ALIGN_EPI = false, bool SP2 = false>
; __device__ __forceinline__ void gemm_phase(PG8_LAS unsigned char* lds, const Gemm g, const Sched& S, const Epi& E) {
;     ...
;             PG8_WAIT_V(8); PG8_WAIT_L(0); PG8_BAR; PG8_MMA(0, 0, At, B0); PG8_MMA(0, 1, At, B1); PG8_BAR; PG8_SCHED;
;             PG8_LDA(At, 1, 1); PG8_STAGE(PG8_SB(1, 0), b3, voffB); PG8_STAGE(PG8_SB(1, 1), b3 + hstep, voffB); PG8_STAGE(PG8_SA(1, 0), a3, voffA);
;             PG8_WAIT_V(8); PG8_WAIT_L(0); PG8_BAR; PG8_MMA(1, 0, At, B0); PG8_MMA(1, 1, At, B1); PG8_BAR; PG8_SCHED;
	v_mfma_f32_16x16x32_bf16 v[36:39], v[170:173], v[210:213], v[36:39]
	v_mfma_f32_16x16x32_bf16 v[32:35], v[178:181], v[210:213], v[32:35]
	s_setprio 0
	s_add_i32 s52, s56, s3
	v_lshl_add_u64 v[214:215], v[214:215], 0, s[14:15]
	s_mov_b32 m0, s52
	ds_read_b128 v[182:185], v232 offset:49152
	ds_read_b128 v[186:189], v232 offset:50176
	ds_read_b128 v[190:193], v232 offset:51200
	ds_read_b128 v[194:197], v232 offset:52224
	ds_read_b128 v[198:201], v232 offset:53248
	ds_read_b128 v[202:205], v232 offset:54272
	ds_read_b128 v[206:209], v232 offset:55296
	ds_read_b128 v[210:213], v232 offset:56320
	global_load_lds_dwordx4 v[214:215], off
	s_add_i32 m0, s52, 0x2000
	s_add_u32 s52, s78, 0x80080
	v_lshl_add_u64 v[214:215], v[216:217], 0, s[14:15]
	s_addc_u32 s53, s79, 0
	s_add_i32 s56, s57, s3
	global_load_lds_dwordx4 v[214:215], off
	s_mov_b32 m0, s56
	s_nop 0
	global_load_lds_dwordx4 v138, s[52:53]
	s_add_i32 m0, s56, 0x2000
	s_nop 0
	global_load_lds_dwordx4 v142, s[52:53]
	s_mov_b32 m0, s88
	v_lshl_add_u64 v[214:215], v[218:219], 0, s[14:15]
	global_load_lds_dwordx4 v[214:215], off
	s_mov_b32 m0, s89
	v_lshl_add_u64 v[214:215], v[220:221], 0, s[14:15]
	global_load_lds_dwordx4 v[214:215], off
	s_waitcnt vmcnt(8)
	s_waitcnt lgkmcnt(0)
	s_setprio 1
	s_barrier
	v_mfma_f32_16x16x32_bf16 v[92:95], v[128:131], v[182:185], v[92:95]
	v_mfma_f32_16x16x32_bf16 v[88:91], v[158:161], v[182:185], v[88:91]
	v_mfma_f32_16x16x32_bf16 v[84:87], v[128:131], v[190:193], v[84:87]
	v_mfma_f32_16x16x32_bf16 v[80:83], v[158:161], v[190:193], v[80:83]
	v_mfma_f32_16x16x32_bf16 v[76:79], v[128:131], v[198:201], v[76:79]
	v_mfma_f32_16x16x32_bf16 v[72:75], v[158:161], v[198:201], v[72:75]
	v_mfma_f32_16x16x32_bf16 v[68:71], v[128:131], v[206:209], v[68:71]
	v_mfma_f32_16x16x32_bf16 v[64:67], v[158:161], v[206:209], v[64:67]
	v_mfma_f32_16x16x32_bf16 v[92:95], v[132:135], v[186:189], v[92:95]
	v_mfma_f32_16x16x32_bf16 v[88:91], v[162:165], v[186:189], v[88:91]
	v_mfma_f32_16x16x32_bf16 v[84:87], v[132:135], v[194:197], v[84:87]
	v_mfma_f32_16x16x32_bf16 v[80:83], v[162:165], v[194:197], v[80:83]
	v_mfma_f32_16x16x32_bf16 v[76:79], v[132:135], v[202:205], v[76:79]
	v_mfma_f32_16x16x32_bf16 v[72:75], v[162:165], v[202:205], v[72:75]
	v_mfma_f32_16x16x32_bf16 v[68:71], v[132:135], v[210:213], v[68:71]
	v_mfma_f32_16x16x32_bf16 v[64:67], v[162:165], v[210:213], v[64:67]
	s_setprio 0
	s_setprio 1
	v_mfma_f32_16x16x32_bf16 v[28:31], v[166:169], v[182:185], v[28:31]
	v_mfma_f32_16x16x32_bf16 v[24:27], v[174:177], v[182:185], v[24:27]
	v_mfma_f32_16x16x32_bf16 v[20:23], v[166:169], v[190:193], v[20:23]
	v_mfma_f32_16x16x32_bf16 v[16:19], v[174:177], v[190:193], v[16:19]
	v_mfma_f32_16x16x32_bf16 v[12:15], v[166:169], v[198:201], v[12:15]
	v_mfma_f32_16x16x32_bf16 v[8:11], v[174:177], v[198:201], v[8:11]
	v_mfma_f32_16x16x32_bf16 v[4:7], v[166:169], v[206:209], v[4:7]
	v_mfma_f32_16x16x32_bf16 v[0:3], v[174:177], v[206:209], v[0:3]
	v_mfma_f32_16x16x32_bf16 v[28:31], v[170:173], v[186:189], v[28:31]
	v_mfma_f32_16x16x32_bf16 v[24:27], v[178:181], v[186:189], v[24:27]
	v_mfma_f32_16x16x32_bf16 v[20:23], v[170:173], v[194:197], v[20:23]
	v_mfma_f32_16x16x32_bf16 v[16:19], v[178:181], v[194:197], v[16:19]
	v_mfma_f32_16x16x32_bf16 v[12:15], v[170:173], v[202:205], v[12:15]
	v_mfma_f32_16x16x32_bf16 v[8:11], v[178:181], v[202:205], v[8:11]
	s_setprio 2
	s_barrier
	v_mfma_f32_16x16x32_bf16 v[4:7], v[170:173], v[210:213], v[4:7]
	v_mfma_f32_16x16x32_bf16 v[0:3], v[178:181], v[210:213], v[0:3]
	s_setprio 0
	s_add_i32 vcc_hi, vcc_hi, 2
	s_add_u32 s76, s76, 0x100
	s_addc_u32 s77, s77, 0
	s_add_u32 s75, s75, 0x100
	s_addc_u32 vcc_lo, vcc_lo, 0
	s_cmp_gt_u32 vcc_hi, 29
	s_cbranch_scc0 .LBB0_374
	s_and_b64 vcc, exec, s[48:49]
	s_cbranch_vccz .LBB0_377
	s_barrier

; #define PG8_STAGE(bufoff, gbase, voff) do { _Pragma("unroll") for (int _i = 0; _i < 2; ++_i) \
;         __builtin_amdgcn_global_load_lds((const unsigned*)((const char*)(gbase) + (voff)[_i]), (PG8_LAS unsigned*)(lds + (bufoff) + ldsw + _i * 8192), 16, 0, 0); } while (0)
; #define PG8_LDA(dst, b, h) do { _Pragma("unroll") for (int m = 0; m < 4; ++m) _Pragma("unroll") for (int k = 0; k < 2; ++k) dst[m][k] = *(const PG8_LAS bf16x8*)(lds + PG8_SA(b, h) + aoff + m * 2048 + k * 1024); } while (0)
; #define PG8_LDB(dst, b, h) do { _Pragma("unroll") for (int n = 0; n < 2; ++n) _Pragma("unroll") for (int k = 0; k < 2; ++k) dst[n][k] = *(const PG8_LAS bf16x8*)(lds + PG8_SB(b, h) + boff + n * 2048 + k * 1024); } while (0)
; #define PG8_MMA(ai, bj, At, Bt) do { __builtin_amdgcn_s_setprio(1); _Pragma("unroll") for (int m = 0; m < 4; ++m) _Pragma("unroll") for (int n = 0; n < 2; ++n) _Pragma("unroll") for (int k = 0; k < 2; ++k) \
;         acc[ai][bj][m][n] = __builtin_amdgcn_mfma_f32_16x16x32_bf16(Bt[n][k], At[m][k], acc[ai][bj][m][n], 0, 0, 0); __builtin_amdgcn_s_setprio(0); } while (0)
; #define PG8_WAIT_V(n) asm volatile("s_waitcnt vmcnt(" #n ")" ::: "memory")
; #define PG8_WAIT_L(n) asm volatile("s_waitcnt lgkmcnt(" #n ")" ::: "memory")
; #define PG8_BAR __builtin_amdgcn_s_barrier()
; #define PG8_SCHED __builtin_amdgcn_sched_barrier(0)
; template <class Epi, class Sched, bool ALIGN_EPI = false, bool SP2 = false>
; __device__ __forceinline__ void gemm_phase(PG8_LAS unsigned char* lds, const Gemm g, const Sched& S, const Epi& E) {
;     ...
;             const char* a1 = cA + (size_t)(t + 1) * kstep;
;             const char* a2 = last ? nA : cA + (size_t)(t + 2) * kstep; const char* b2 = last ? nB : cB + (size_t)(t + 2) * kstep;
;             const char* a3 = a2 + kstep; const char* b3 = b2 + kstep;
;             if constexpr (SP2) {
;             PG8_LDB(B0, 0, 0); PG8_LDB(B1, 0, 1); PG8_SCHED; PG8_LDA(At, 0, 0); PG8_STAGE(PG8_SA(1, 1), a1 + hstep, voffA);
;             PG8_WAIT_V(8); PG8_WAIT_L(0); PG8_BAR; PG8_MMA(0, 0, At, B0); PG8_MMA(0, 1, At, B1); PG8_BAR; PG8_SCHED;
;             PG8_LDA(At, 0, 1); PG8_STAGE(PG8_SB(0, 0), b2, voffB); PG8_STAGE(PG8_SB(0, 1), b2 + hstep, voffB); PG8_STAGE(PG8_SA(0, 0), a2, voffA);
;             PG8_WAIT_V(8); PG8_WAIT_L(0); PG8_BAR; PG8_MMA(1, 0, At, B0); PG8_MMA(1, 1, At, B1); PG8_BAR; PG8_SCHED;
.LBB0_410:
	ds_read_b128 v[166:169], v145
	ds_read_b128 v[170:173], v145 offset:1024
	ds_read_b128 v[174:177], v145 offset:2048
	ds_read_b128 v[178:181], v145 offset:3072
	ds_read_b128 v[182:185], v149
	ds_read_b128 v[186:189], v149 offset:1024
	ds_read_b128 v[190:193], v149 offset:2048
	ds_read_b128 v[194:197], v149 offset:3072
	s_add_u32 s52, s74, 0xfff80080
	s_addc_u32 s53, s75, -1
	s_cmp_eq_u32 s51, 4
	s_cselect_b32 s79, s55, s53
	s_cselect_b32 s78, s54, s52
	s_cselect_b32 s77, s69, s49
	s_cselect_b32 s76, s68, s37
	s_mov_b32 m0, s80
	ds_read_b128 v[198:201], v164
	ds_read_b128 v[202:205], v164 offset:1024
	ds_read_b128 v[206:209], v164 offset:2048
	ds_read_b128 v[210:213], v164 offset:3072
	ds_read_b128 v[214:217], v164 offset:4096
	ds_read_b128 v[218:221], v164 offset:5120
	ds_read_b128 v[222:225], v164 offset:6144
	ds_read_b128 v[226:229], v164 offset:7168
	global_load_lds_dwordx4 v160, s[74:75]
	s_mov_b32 m0, s81
	s_nop 0
	global_load_lds_dwordx4 v162, s[74:75]
	s_waitcnt vmcnt(8)
	s_waitcnt lgkmcnt(0)
	s_setprio 1
	s_barrier
	v_mfma_f32_16x16x32_bf16 v[124:127], v[166:169], v[198:201], v[124:127]
	v_mfma_f32_16x16x32_bf16 v[120:123], v[174:177], v[198:201], v[120:123]
	v_mfma_f32_16x16x32_bf16 v[116:119], v[166:169], v[206:209], v[116:119]
	v_mfma_f32_16x16x32_bf16 v[108:111], v[174:177], v[206:209], v[108:111]
	v_mfma_f32_16x16x32_bf16 v[100:103], v[166:169], v[214:217], v[100:103]
	v_mfma_f32_16x16x32_bf16 v[92:95], v[174:177], v[214:217], v[92:95]
	v_mfma_f32_16x16x32_bf16 v[84:87], v[166:169], v[222:225], v[84:87]
	v_mfma_f32_16x16x32_bf16 v[76:79], v[174:177], v[222:225], v[76:79]
	v_mfma_f32_16x16x32_bf16 v[124:127], v[170:173], v[202:205], v[124:127]
	v_mfma_f32_16x16x32_bf16 v[120:123], v[178:181], v[202:205], v[120:123]
	v_mfma_f32_16x16x32_bf16 v[116:119], v[170:173], v[210:213], v[116:119]
	v_mfma_f32_16x16x32_bf16 v[108:111], v[178:181], v[210:213], v[108:111]
	v_mfma_f32_16x16x32_bf16 v[100:103], v[170:173], v[218:221], v[100:103]
	v_mfma_f32_16x16x32_bf16 v[92:95], v[178:181], v[218:221], v[92:95]
	v_mfma_f32_16x16x32_bf16 v[84:87], v[170:173], v[226:229], v[84:87]
	v_mfma_f32_16x16x32_bf16 v[76:79], v[178:181], v[226:229], v[76:79]
	s_setprio 0
	s_setprio 1
	v_mfma_f32_16x16x32_bf16 v[112:115], v[182:185], v[198:201], v[112:115]
	v_mfma_f32_16x16x32_bf16 v[104:107], v[190:193], v[198:201], v[104:107]
	v_mfma_f32_16x16x32_bf16 v[96:99], v[182:185], v[206:209], v[96:99]
	v_mfma_f32_16x16x32_bf16 v[88:91], v[190:193], v[206:209], v[88:91]
	v_mfma_f32_16x16x32_bf16 v[80:83], v[182:185], v[214:217], v[80:83]
	v_mfma_f32_16x16x32_bf16 v[72:75], v[190:193], v[214:217], v[72:75]
	v_mfma_f32_16x16x32_bf16 v[68:71], v[182:185], v[222:225], v[68:71]
	v_mfma_f32_16x16x32_bf16 v[64:67], v[190:193], v[222:225], v[64:67]
	v_mfma_f32_16x16x32_bf16 v[112:115], v[186:189], v[202:205], v[112:115]
	v_mfma_f32_16x16x32_bf16 v[104:107], v[194:197], v[202:205], v[104:107]
	v_mfma_f32_16x16x32_bf16 v[96:99], v[186:189], v[210:213], v[96:99]
	v_mfma_f32_16x16x32_bf16 v[88:91], v[194:197], v[210:213], v[88:91]
	v_mfma_f32_16x16x32_bf16 v[80:83], v[186:189], v[218:221], v[80:83]
	v_mfma_f32_16x16x32_bf16 v[72:75], v[194:197], v[218:221], v[72:75]
	s_setprio 2
	s_barrier
	v_mfma_f32_16x16x32_bf16 v[68:71], v[186:189], v[226:229], v[68:71]
	v_mfma_f32_16x16x32_bf16 v[64:67], v[194:197], v[226:229], v[64:67]
	s_setprio 0
	s_mov_b32 m0, s84
	v_lshl_add_u64 v[230:231], s[76:77], 0, v[138:139]
	s_add_u32 s52, s76, 0x80000
	ds_read_b128 v[198:201], v164 offset:16384
	ds_read_b128 v[202:205], v164 offset:17408
	ds_read_b128 v[206:209], v164 offset:18432
	ds_read_b128 v[210:213], v164 offset:19456
	ds_read_b128 v[214:217], v164 offset:20480
	ds_read_b128 v[218:221], v164 offset:21504
	ds_read_b128 v[222:225], v164 offset:22528
	ds_read_b128 v[226:229], v164 offset:23552
	global_load_lds_dwordx4 v[230:231], off
	v_lshl_add_u64 v[232:233], s[76:77], 0, v[142:143]
	s_mov_b32 m0, s85
	s_addc_u32 s53, s77, 0
	global_load_lds_dwordx4 v[232:233], off
	s_mov_b32 m0, s86
	v_lshl_add_u64 v[236:237], s[78:79], 0, v[140:141]
	global_load_lds_dwordx4 v138, s[52:53]
	s_mov_b32 m0, s87
	s_nop 0
	global_load_lds_dwordx4 v142, s[52:53]
	s_mov_b32 m0, s10
	v_lshl_add_u64 v[234:235], s[78:79], 0, v[136:137]
	global_load_lds_dwordx4 v[234:235], off
	s_mov_b32 m0, s11
	s_nop 0
	global_load_lds_dwordx4 v[236:237], off
	s_waitcnt vmcnt(8)
	s_waitcnt lgkmcnt(0)
	s_setprio 1
	s_barrier
	v_mfma_f32_16x16x32_bf16 v[60:63], v[166:169], v[198:201], v[60:63]
	v_mfma_f32_16x16x32_bf16 v[56:59], v[174:177], v[198:201], v[56:59]
	v_mfma_f32_16x16x32_bf16 v[52:55], v[166:169], v[206:209], v[52:55]
	v_mfma_f32_16x16x32_bf16 v[44:47], v[174:177], v[206:209], v[44:47]
	v_mfma_f32_16x16x32_bf16 v[36:39], v[166:169], v[214:217], v[36:39]
	v_mfma_f32_16x16x32_bf16 v[28:31], v[174:177], v[214:217], v[28:31]
	v_mfma_f32_16x16x32_bf16 v[20:23], v[166:169], v[222:225], v[20:23]
	v_mfma_f32_16x16x32_bf16 v[12:15], v[174:177], v[222:225], v[12:15]
	v_mfma_f32_16x16x32_bf16 v[60:63], v[170:173], v[202:205], v[60:63]
	v_mfma_f32_16x16x32_bf16 v[56:59], v[178:181], v[202:205], v[56:59]
	v_mfma_f32_16x16x32_bf16 v[52:55], v[170:173], v[210:213], v[52:55]
	v_mfma_f32_16x16x32_bf16 v[44:47], v[178:181], v[210:213], v[44:47]
	v_mfma_f32_16x16x32_bf16 v[36:39], v[170:173], v[218:221], v[36:39]
	v_mfma_f32_16x16x32_bf16 v[28:31], v[178:181], v[218:221], v[28:31]
	v_mfma_f32_16x16x32_bf16 v[20:23], v[170:173], v[226:229], v[20:23]
	v_mfma_f32_16x16x32_bf16 v[12:15], v[178:181], v[226:229], v[12:15]
	s_setprio 0
	s_setprio 1
	v_mfma_f32_16x16x32_bf16 v[48:51], v[182:185], v[198:201], v[48:51]
	v_mfma_f32_16x16x32_bf16 v[40:43], v[190:193], v[198:201], v[40:43]
	v_mfma_f32_16x16x32_bf16 v[32:35], v[182:185], v[206:209], v[32:35]
	v_mfma_f32_16x16x32_bf16 v[24:27], v[190:193], v[206:209], v[24:27]
	v_mfma_f32_16x16x32_bf16 v[16:19], v[182:185], v[214:217], v[16:19]
	v_mfma_f32_16x16x32_bf16 v[8:11], v[190:193], v[214:217], v[8:11]
	v_mfma_f32_16x16x32_bf16 v[4:7], v[182:185], v[222:225], v[4:7]
	v_mfma_f32_16x16x32_bf16 v[0:3], v[190:193], v[222:225], v[0:3]
	v_mfma_f32_16x16x32_bf16 v[48:51], v[186:189], v[202:205], v[48:51]
	v_mfma_f32_16x16x32_bf16 v[40:43], v[194:197], v[202:205], v[40:43]
	v_mfma_f32_16x16x32_bf16 v[32:35], v[186:189], v[210:213], v[32:35]
	v_mfma_f32_16x16x32_bf16 v[24:27], v[194:197], v[210:213], v[24:27]
	v_mfma_f32_16x16x32_bf16 v[16:19], v[186:189], v[218:221], v[16:19]
	v_mfma_f32_16x16x32_bf16 v[8:11], v[194:197], v[218:221], v[8:11]
	s_setprio 2
	s_barrier
; #define PG8_STAGE(bufoff, gbase, voff) do { _Pragma("unroll") for (int _i = 0; _i < 2; ++_i) \
;         __builtin_amdgcn_global_load_lds((const unsigned*)((const char*)(gbase) + (voff)[_i]), (PG8_LAS unsigned*)(lds + (bufoff) + ldsw + _i * 8192), 16, 0, 0); } while (0)
; #define PG8_LDA(dst, b, h) do { _Pragma("unroll") for (int m = 0; m < 4; ++m) _Pragma("unroll") for (int k = 0; k < 2; ++k) dst[m][k] = *(const PG8_LAS bf16x8*)(lds + PG8_SA(b, h) + aoff + m * 2048 + k * 1024); } while (0)
; #define PG8_LDB(dst, b, h) do { _Pragma("unroll") for (int n = 0; n < 2; ++n) _Pragma("unroll") for (int k = 0; k < 2; ++k) dst[n][k] = *(const PG8_LAS bf16x8*)(lds + PG8_SB(b, h) + boff + n * 2048 + k * 1024); } while (0)
; #define PG8_MMA(ai, bj, At, Bt) do { __builtin_amdgcn_s_setprio(1); _Pragma("unroll") for (int m = 0; m < 4; ++m) _Pragma("unroll") for (int n = 0; n < 2; ++n) _Pragma("unroll") for (int k = 0; k < 2; ++k) \
;         acc[ai][bj][m][n] = __builtin_amdgcn_mfma_f32_16x16x32_bf16(Bt[n][k], At[m][k], acc[ai][bj][m][n], 0, 0, 0); __builtin_amdgcn_s_setprio(0); } while (0)
; #define PG8_WAIT_V(n) asm volatile("s_waitcnt vmcnt(" #n ")" ::: "memory")
; #define PG8_WAIT_L(n) asm volatile("s_waitcnt lgkmcnt(" #n ")" ::: "memory")
; #define PG8_BAR __builtin_amdgcn_s_barrier()
; #define PG8_SCHED __builtin_amdgcn_sched_barrier(0)
; template <class Epi, class Sched, bool ALIGN_EPI = false, bool SP2 = false>
; __device__ __forceinline__ void gemm_phase(PG8_LAS unsigned char* lds, const Gemm g, const Sched& S, const Epi& E) {
;     ...
;             PG8_WAIT_V(8); PG8_WAIT_L(0); PG8_BAR; PG8_MMA(1, 0, At, B0); PG8_MMA(1, 1, At, B1); PG8_BAR; PG8_SCHED;
;             PG8_LDB(B0, 1, 0); PG8_LDB(B1, 1, 1); PG8_SCHED; PG8_LDA(At, 1, 0); PG8_STAGE(PG8_SA(0, 1), a2 + hstep, voffA);
;             PG8_WAIT_V(8); PG8_WAIT_L(0); PG8_BAR; PG8_MMA(0, 0, At, B0); PG8_MMA(0, 1, At, B1); PG8_BAR; PG8_SCHED;
;             PG8_LDA(At, 1, 1); PG8_STAGE(PG8_SB(1, 0), b3, voffB); PG8_STAGE(PG8_SB(1, 1), b3 + hstep, voffB); PG8_STAGE(PG8_SA(1, 0), a3, voffA);
;             PG8_WAIT_V(8); PG8_WAIT_L(0); PG8_BAR; PG8_MMA(1, 0, At, B0); PG8_MMA(1, 1, At, B1); PG8_BAR; PG8_SCHED;
	v_mfma_f32_16x16x32_bf16 v[4:7], v[186:189], v[226:229], v[4:7]
	v_mfma_f32_16x16x32_bf16 v[0:3], v[194:197], v[226:229], v[0:3]
	s_setprio 0
	ds_read_b128 v[166:169], v148
	ds_read_b128 v[170:173], v148 offset:1024
	ds_read_b128 v[174:177], v148 offset:2048
	ds_read_b128 v[178:181], v148 offset:3072
	ds_read_b128 v[182:185], v165
	ds_read_b128 v[186:189], v165 offset:1024
	ds_read_b128 v[190:193], v165 offset:2048
	ds_read_b128 v[194:197], v165 offset:3072
	s_add_u32 s52, s78, 0x80000
	s_addc_u32 s53, s79, 0
	s_mov_b32 m0, s28
	ds_read_b128 v[198:201], v164 offset:32768
	ds_read_b128 v[202:205], v164 offset:33792
	ds_read_b128 v[206:209], v164 offset:34816
	ds_read_b128 v[210:213], v164 offset:35840
	ds_read_b128 v[214:217], v164 offset:36864
	ds_read_b128 v[218:221], v164 offset:37888
	ds_read_b128 v[222:225], v164 offset:38912
	ds_read_b128 v[226:229], v164 offset:39936
	global_load_lds_dwordx4 v136, s[52:53]
	s_mov_b32 m0, s29
	s_nop 0
	global_load_lds_dwordx4 v140, s[52:53]
	s_waitcnt vmcnt(8)
	s_waitcnt lgkmcnt(0)
	s_setprio 1
	s_barrier
	v_mfma_f32_16x16x32_bf16 v[124:127], v[166:169], v[198:201], v[124:127]
	v_mfma_f32_16x16x32_bf16 v[120:123], v[174:177], v[198:201], v[120:123]
	v_mfma_f32_16x16x32_bf16 v[116:119], v[166:169], v[206:209], v[116:119]
	v_mfma_f32_16x16x32_bf16 v[108:111], v[174:177], v[206:209], v[108:111]
	v_mfma_f32_16x16x32_bf16 v[100:103], v[166:169], v[214:217], v[100:103]
	v_mfma_f32_16x16x32_bf16 v[92:95], v[174:177], v[214:217], v[92:95]
	v_mfma_f32_16x16x32_bf16 v[84:87], v[166:169], v[222:225], v[84:87]
	v_mfma_f32_16x16x32_bf16 v[76:79], v[174:177], v[222:225], v[76:79]
	v_mfma_f32_16x16x32_bf16 v[124:127], v[170:173], v[202:205], v[124:127]
	v_mfma_f32_16x16x32_bf16 v[120:123], v[178:181], v[202:205], v[120:123]
	v_mfma_f32_16x16x32_bf16 v[116:119], v[170:173], v[210:213], v[116:119]
	v_mfma_f32_16x16x32_bf16 v[108:111], v[178:181], v[210:213], v[108:111]
	v_mfma_f32_16x16x32_bf16 v[100:103], v[170:173], v[218:221], v[100:103]
	v_mfma_f32_16x16x32_bf16 v[92:95], v[178:181], v[218:221], v[92:95]
	v_mfma_f32_16x16x32_bf16 v[84:87], v[170:173], v[226:229], v[84:87]
	v_mfma_f32_16x16x32_bf16 v[76:79], v[178:181], v[226:229], v[76:79]
	s_setprio 0
	s_setprio 1
	v_mfma_f32_16x16x32_bf16 v[112:115], v[182:185], v[198:201], v[112:115]
	v_mfma_f32_16x16x32_bf16 v[104:107], v[190:193], v[198:201], v[104:107]
	v_mfma_f32_16x16x32_bf16 v[96:99], v[182:185], v[206:209], v[96:99]
	v_mfma_f32_16x16x32_bf16 v[88:91], v[190:193], v[206:209], v[88:91]
	v_mfma_f32_16x16x32_bf16 v[80:83], v[182:185], v[214:217], v[80:83]
	v_mfma_f32_16x16x32_bf16 v[72:75], v[190:193], v[214:217], v[72:75]
	v_mfma_f32_16x16x32_bf16 v[68:71], v[182:185], v[222:225], v[68:71]
	v_mfma_f32_16x16x32_bf16 v[64:67], v[190:193], v[222:225], v[64:67]
	v_mfma_f32_16x16x32_bf16 v[112:115], v[186:189], v[202:205], v[112:115]
	v_mfma_f32_16x16x32_bf16 v[104:107], v[194:197], v[202:205], v[104:107]
	v_mfma_f32_16x16x32_bf16 v[96:99], v[186:189], v[210:213], v[96:99]
	v_mfma_f32_16x16x32_bf16 v[88:91], v[194:197], v[210:213], v[88:91]
	v_mfma_f32_16x16x32_bf16 v[80:83], v[186:189], v[218:221], v[80:83]
	v_mfma_f32_16x16x32_bf16 v[72:75], v[194:197], v[218:221], v[72:75]
	s_setprio 2
	s_barrier
	v_mfma_f32_16x16x32_bf16 v[68:71], v[186:189], v[226:229], v[68:71]
	v_mfma_f32_16x16x32_bf16 v[64:67], v[194:197], v[226:229], v[64:67]
	s_setprio 0
	s_mov_b32 m0, s89
	v_lshl_add_u64 v[230:231], v[230:231], 0, s[12:13]
	ds_read_b128 v[198:201], v164 offset:49152
	ds_read_b128 v[202:205], v164 offset:50176
	ds_read_b128 v[206:209], v164 offset:51200
	ds_read_b128 v[210:213], v164 offset:52224
	ds_read_b128 v[214:217], v164 offset:53248
	ds_read_b128 v[218:221], v164 offset:54272
	ds_read_b128 v[222:225], v164 offset:55296
	ds_read_b128 v[226:229], v164 offset:56320
	global_load_lds_dwordx4 v[230:231], off
	s_add_i32 m0, s89, 0x2000
	s_add_u32 s52, s76, 0x80080
	v_lshl_add_u64 v[230:231], v[232:233], 0, s[12:13]
	s_addc_u32 s53, s77, 0
	s_add_i32 s56, s88, s3
	global_load_lds_dwordx4 v[230:231], off
	s_mov_b32 m0, s56
	s_nop 0
	global_load_lds_dwordx4 v138, s[52:53]
	s_add_i32 m0, s56, 0x2000
	s_nop 0
	global_load_lds_dwordx4 v142, s[52:53]
	s_mov_b32 m0, s38
	v_lshl_add_u64 v[230:231], v[234:235], 0, s[12:13]
	global_load_lds_dwordx4 v[230:231], off
	s_mov_b32 m0, s39
	v_lshl_add_u64 v[230:231], v[236:237], 0, s[12:13]
	global_load_lds_dwordx4 v[230:231], off
	s_waitcnt vmcnt(8)
	s_waitcnt lgkmcnt(0)
	s_setprio 1
	s_barrier
	v_mfma_f32_16x16x32_bf16 v[60:63], v[166:169], v[198:201], v[60:63]
	v_mfma_f32_16x16x32_bf16 v[56:59], v[174:177], v[198:201], v[56:59]
	v_mfma_f32_16x16x32_bf16 v[52:55], v[166:169], v[206:209], v[52:55]
	v_mfma_f32_16x16x32_bf16 v[44:47], v[174:177], v[206:209], v[44:47]
	v_mfma_f32_16x16x32_bf16 v[36:39], v[166:169], v[214:217], v[36:39]
	v_mfma_f32_16x16x32_bf16 v[28:31], v[174:177], v[214:217], v[28:31]
	v_mfma_f32_16x16x32_bf16 v[20:23], v[166:169], v[222:225], v[20:23]
	v_mfma_f32_16x16x32_bf16 v[12:15], v[174:177], v[222:225], v[12:15]
	v_mfma_f32_16x16x32_bf16 v[60:63], v[170:173], v[202:205], v[60:63]
	v_mfma_f32_16x16x32_bf16 v[56:59], v[178:181], v[202:205], v[56:59]
	v_mfma_f32_16x16x32_bf16 v[52:55], v[170:173], v[210:213], v[52:55]
	v_mfma_f32_16x16x32_bf16 v[44:47], v[178:181], v[210:213], v[44:47]
	v_mfma_f32_16x16x32_bf16 v[36:39], v[170:173], v[218:221], v[36:39]
	v_mfma_f32_16x16x32_bf16 v[28:31], v[178:181], v[218:221], v[28:31]
	v_mfma_f32_16x16x32_bf16 v[20:23], v[170:173], v[226:229], v[20:23]
	v_mfma_f32_16x16x32_bf16 v[12:15], v[178:181], v[226:229], v[12:15]
	s_setprio 0
	s_setprio 1
	v_mfma_f32_16x16x32_bf16 v[48:51], v[182:185], v[198:201], v[48:51]
	v_mfma_f32_16x16x32_bf16 v[40:43], v[190:193], v[198:201], v[40:43]
	v_mfma_f32_16x16x32_bf16 v[32:35], v[182:185], v[206:209], v[32:35]
	v_mfma_f32_16x16x32_bf16 v[24:27], v[190:193], v[206:209], v[24:27]
	v_mfma_f32_16x16x32_bf16 v[16:19], v[182:185], v[214:217], v[16:19]
	v_mfma_f32_16x16x32_bf16 v[8:11], v[190:193], v[214:217], v[8:11]
	v_mfma_f32_16x16x32_bf16 v[4:7], v[182:185], v[222:225], v[4:7]
	v_mfma_f32_16x16x32_bf16 v[0:3], v[190:193], v[222:225], v[0:3]
	v_mfma_f32_16x16x32_bf16 v[48:51], v[186:189], v[202:205], v[48:51]
	v_mfma_f32_16x16x32_bf16 v[40:43], v[194:197], v[202:205], v[40:43]
	v_mfma_f32_16x16x32_bf16 v[32:35], v[186:189], v[210:213], v[32:35]
	v_mfma_f32_16x16x32_bf16 v[24:27], v[194:197], v[210:213], v[24:27]
	v_mfma_f32_16x16x32_bf16 v[16:19], v[186:189], v[218:221], v[16:19]
	v_mfma_f32_16x16x32_bf16 v[8:11], v[194:197], v[218:221], v[8:11]
	s_setprio 2
	s_barrier
	v_mfma_f32_16x16x32_bf16 v[4:7], v[186:189], v[226:229], v[4:7]
	v_mfma_f32_16x16x32_bf16 v[0:3], v[194:197], v[226:229], v[0:3]
	s_setprio 0
	s_add_i32 s51, s51, 2
	s_add_u32 s74, s74, 0x100
	s_addc_u32 s75, s75, 0
	s_add_u32 s37, s37, 0x100
	s_addc_u32 s49, s49, 0
	s_cmp_gt_u32 s51, 5
	s_cbranch_scc0 .LBB0_410
	s_and_b64 vcc, exec, s[14:15]
	s_cbranch_vccz .LBB0_413
	s_barrier

; #define PG8_STAGE(bufoff, gbase, voff) do { _Pragma("unroll") for (int _i = 0; _i < 2; ++_i) \
;         __builtin_amdgcn_global_load_lds((const unsigned*)((const char*)(gbase) + (voff)[_i]), (PG8_LAS unsigned*)(lds + (bufoff) + ldsw + _i * 8192), 16, 0, 0); } while (0)
; #define PG8_LDA(dst, b, h) do { _Pragma("unroll") for (int m = 0; m < 4; ++m) _Pragma("unroll") for (int k = 0; k < 2; ++k) dst[m][k] = *(const PG8_LAS bf16x8*)(lds + PG8_SA(b, h) + aoff + m * 2048 + k * 1024); } while (0)
; #define PG8_LDB(dst, b, h) do { _Pragma("unroll") for (int n = 0; n < 2; ++n) _Pragma("unroll") for (int k = 0; k < 2; ++k) dst[n][k] = *(const PG8_LAS bf16x8*)(lds + PG8_SB(b, h) + boff + n * 2048 + k * 1024); } while (0)
; #define PG8_MMA(ai, bj, At, Bt) do { __builtin_amdgcn_s_setprio(1); _Pragma("unroll") for (int m = 0; m < 4; ++m) _Pragma("unroll") for (int n = 0; n < 2; ++n) _Pragma("unroll") for (int k = 0; k < 2; ++k) \
;         acc[ai][bj][m][n] = __builtin_amdgcn_mfma_f32_16x16x32_bf16(Bt[n][k], At[m][k], acc[ai][bj][m][n], 0, 0, 0); __builtin_amdgcn_s_setprio(0); } while (0)
; #define PG8_WAIT_V(n) asm volatile("s_waitcnt vmcnt(" #n ")" ::: "memory")
; #define PG8_WAIT_L(n) asm volatile("s_waitcnt lgkmcnt(" #n ")" ::: "memory")
; #define PG8_BAR __builtin_amdgcn_s_barrier()
; #define PG8_SCHED __builtin_amdgcn_sched_barrier(0)
; template <class Epi, class Sched, bool ALIGN_EPI = false, bool SP2 = false>
; __device__ __forceinline__ void gemm_phase(PG8_LAS unsigned char* lds, const Gemm g, const Sched& S, const Epi& E) {
;     ...
;             const char* a1 = cA + (size_t)(t + 1) * kstep;
;             const char* a2 = last ? nA : cA + (size_t)(t + 2) * kstep; const char* b2 = last ? nB : cB + (size_t)(t + 2) * kstep;
;             const char* a3 = a2 + kstep; const char* b3 = b2 + kstep;
;             if constexpr (SP2) {
;             PG8_LDB(B0, 0, 0); PG8_LDB(B1, 0, 1); PG8_SCHED; PG8_LDA(At, 0, 0); PG8_STAGE(PG8_SA(1, 1), a1 + hstep, voffA);
;             PG8_WAIT_V(8); PG8_WAIT_L(0); PG8_BAR; PG8_MMA(0, 0, At, B0); PG8_MMA(0, 1, At, B1); PG8_BAR; PG8_SCHED;
;             PG8_LDA(At, 0, 1); PG8_STAGE(PG8_SB(0, 0), b2, voffB); PG8_STAGE(PG8_SB(0, 1), b2 + hstep, voffB); PG8_STAGE(PG8_SA(0, 0), a2, voffA);
;             PG8_WAIT_V(8); PG8_WAIT_L(0); PG8_BAR; PG8_MMA(1, 0, At, B0); PG8_MMA(1, 1, At, B1); PG8_BAR; PG8_SCHED;
.LBB0_545:
	ds_read_b128 v[112:115], v174
	ds_read_b128 v[116:119], v174 offset:1024
	ds_read_b128 v[120:123], v174 offset:2048
	ds_read_b128 v[124:127], v174 offset:3072
	ds_read_b128 v[164:167], v175
	ds_read_b128 v[168:171], v175 offset:1024
	ds_read_b128 v[178:181], v175 offset:2048
	ds_read_b128 v[182:185], v175 offset:3072
	s_add_u32 s52, s68, 0xfff80080
	s_addc_u32 s53, s69, -1
	s_cmp_eq_u32 s88, 28
	s_cselect_b32 s73, s41, s53
	s_cselect_b32 s72, s84, s52
	s_cselect_b32 s71, s37, s87
	s_cselect_b32 s70, s85, s86
	s_add_i32 m0, s39, 0xc000
	ds_read_b128 v[186:189], v176
	ds_read_b128 v[190:193], v176 offset:1024
	ds_read_b128 v[194:197], v176 offset:2048
	ds_read_b128 v[198:201], v176 offset:3072
	ds_read_b128 v[202:205], v176 offset:4096
	ds_read_b128 v[206:209], v176 offset:5120
	ds_read_b128 v[210:213], v176 offset:6144
	ds_read_b128 v[214:217], v176 offset:7168
	global_load_lds_dwordx4 v156, s[68:69]
	s_add_i32 m0, s39, 0xe000
	s_nop 0
	global_load_lds_dwordx4 v158, s[68:69]
	s_waitcnt vmcnt(8)
	s_waitcnt lgkmcnt(0)
	s_setprio 1
	s_barrier
	v_mfma_f32_16x16x32_bf16 v[140:143], v[112:115], v[186:189], v[140:143]
	v_mfma_f32_16x16x32_bf16 v[136:139], v[120:123], v[186:189], v[136:139]
	v_mfma_f32_16x16x32_bf16 v[108:111], v[112:115], v[194:197], v[108:111]
	v_mfma_f32_16x16x32_bf16 v[104:107], v[120:123], v[194:197], v[104:107]
	v_mfma_f32_16x16x32_bf16 v[92:95], v[112:115], v[202:205], v[92:95]
	v_mfma_f32_16x16x32_bf16 v[88:91], v[120:123], v[202:205], v[88:91]
	v_mfma_f32_16x16x32_bf16 v[76:79], v[112:115], v[210:213], v[76:79]
	v_mfma_f32_16x16x32_bf16 v[72:75], v[120:123], v[210:213], v[72:75]
	v_mfma_f32_16x16x32_bf16 v[140:143], v[116:119], v[190:193], v[140:143]
	v_mfma_f32_16x16x32_bf16 v[136:139], v[124:127], v[190:193], v[136:139]
	v_mfma_f32_16x16x32_bf16 v[108:111], v[116:119], v[198:201], v[108:111]
	v_mfma_f32_16x16x32_bf16 v[104:107], v[124:127], v[198:201], v[104:107]
	v_mfma_f32_16x16x32_bf16 v[92:95], v[116:119], v[206:209], v[92:95]
	v_mfma_f32_16x16x32_bf16 v[88:91], v[124:127], v[206:209], v[88:91]
	v_mfma_f32_16x16x32_bf16 v[76:79], v[116:119], v[214:217], v[76:79]
	v_mfma_f32_16x16x32_bf16 v[72:75], v[124:127], v[214:217], v[72:75]
	s_setprio 0
	s_setprio 1
	v_mfma_f32_16x16x32_bf16 v[132:135], v[164:167], v[186:189], v[132:135]
	v_mfma_f32_16x16x32_bf16 v[128:131], v[178:181], v[186:189], v[128:131]
	v_mfma_f32_16x16x32_bf16 v[100:103], v[164:167], v[194:197], v[100:103]
	v_mfma_f32_16x16x32_bf16 v[96:99], v[178:181], v[194:197], v[96:99]
	v_mfma_f32_16x16x32_bf16 v[84:87], v[164:167], v[202:205], v[84:87]
	v_mfma_f32_16x16x32_bf16 v[80:83], v[178:181], v[202:205], v[80:83]
	v_mfma_f32_16x16x32_bf16 v[68:71], v[164:167], v[210:213], v[68:71]
	v_mfma_f32_16x16x32_bf16 v[64:67], v[178:181], v[210:213], v[64:67]
	v_mfma_f32_16x16x32_bf16 v[132:135], v[168:171], v[190:193], v[132:135]
	v_mfma_f32_16x16x32_bf16 v[128:131], v[182:185], v[190:193], v[128:131]
	v_mfma_f32_16x16x32_bf16 v[100:103], v[168:171], v[198:201], v[100:103]
	v_mfma_f32_16x16x32_bf16 v[96:99], v[182:185], v[198:201], v[96:99]
	v_mfma_f32_16x16x32_bf16 v[84:87], v[168:171], v[206:209], v[84:87]
	v_mfma_f32_16x16x32_bf16 v[80:83], v[182:185], v[206:209], v[80:83]
	s_setprio 2
	s_barrier
	v_mfma_f32_16x16x32_bf16 v[68:71], v[168:171], v[214:217], v[68:71]
	v_mfma_f32_16x16x32_bf16 v[64:67], v[182:185], v[214:217], v[64:67]
	s_setprio 0
	s_add_i32 s52, s81, s29
	v_lshl_add_u64 v[218:219], s[70:71], 0, v[152:153]
	s_mov_b32 m0, s52
	ds_read_b128 v[186:189], v176 offset:16384
	ds_read_b128 v[190:193], v176 offset:17408
	ds_read_b128 v[194:197], v176 offset:18432
	ds_read_b128 v[198:201], v176 offset:19456
	ds_read_b128 v[202:205], v176 offset:20480
	ds_read_b128 v[206:209], v176 offset:21504
	ds_read_b128 v[210:213], v176 offset:22528
	ds_read_b128 v[214:217], v176 offset:23552
	global_load_lds_dwordx4 v[218:219], off
	s_add_i32 m0, s52, 0x2000
	s_add_u32 s52, s70, 0x80000
	v_lshl_add_u64 v[220:221], s[70:71], 0, v[148:149]
	s_addc_u32 s53, s71, 0
	s_add_i32 s56, s82, s29
	global_load_lds_dwordx4 v[220:221], off
	s_mov_b32 m0, s56
	v_lshl_add_u64 v[224:225], s[72:73], 0, v[150:151]
	global_load_lds_dwordx4 v152, s[52:53]
	s_add_i32 m0, s56, 0x2000
	s_nop 0
	global_load_lds_dwordx4 v148, s[52:53]
	s_mov_b32 m0, s39
	v_lshl_add_u64 v[222:223], s[72:73], 0, v[154:155]
	global_load_lds_dwordx4 v[222:223], off
	s_mov_b32 m0, s55
	s_nop 0
	global_load_lds_dwordx4 v[224:225], off
	s_waitcnt vmcnt(8)
	s_waitcnt lgkmcnt(0)
	s_setprio 1
	s_barrier
	v_mfma_f32_16x16x32_bf16 v[60:63], v[112:115], v[186:189], v[60:63]
	v_mfma_f32_16x16x32_bf16 v[56:59], v[120:123], v[186:189], v[56:59]
	v_mfma_f32_16x16x32_bf16 v[44:47], v[112:115], v[194:197], v[44:47]
	v_mfma_f32_16x16x32_bf16 v[40:43], v[120:123], v[194:197], v[40:43]
	v_mfma_f32_16x16x32_bf16 v[28:31], v[112:115], v[202:205], v[28:31]
	v_mfma_f32_16x16x32_bf16 v[24:27], v[120:123], v[202:205], v[24:27]
	v_mfma_f32_16x16x32_bf16 v[12:15], v[112:115], v[210:213], v[12:15]
	v_mfma_f32_16x16x32_bf16 v[8:11], v[120:123], v[210:213], v[8:11]
	v_mfma_f32_16x16x32_bf16 v[60:63], v[116:119], v[190:193], v[60:63]
	v_mfma_f32_16x16x32_bf16 v[56:59], v[124:127], v[190:193], v[56:59]
	v_mfma_f32_16x16x32_bf16 v[44:47], v[116:119], v[198:201], v[44:47]
	v_mfma_f32_16x16x32_bf16 v[40:43], v[124:127], v[198:201], v[40:43]
	v_mfma_f32_16x16x32_bf16 v[28:31], v[116:119], v[206:209], v[28:31]
	v_mfma_f32_16x16x32_bf16 v[24:27], v[124:127], v[206:209], v[24:27]
	v_mfma_f32_16x16x32_bf16 v[12:15], v[116:119], v[214:217], v[12:15]
	v_mfma_f32_16x16x32_bf16 v[8:11], v[124:127], v[214:217], v[8:11]
	s_setprio 0
	s_setprio 1
	v_mfma_f32_16x16x32_bf16 v[52:55], v[164:167], v[186:189], v[52:55]
	v_mfma_f32_16x16x32_bf16 v[48:51], v[178:181], v[186:189], v[48:51]
	v_mfma_f32_16x16x32_bf16 v[36:39], v[164:167], v[194:197], v[36:39]
	v_mfma_f32_16x16x32_bf16 v[32:35], v[178:181], v[194:197], v[32:35]
	v_mfma_f32_16x16x32_bf16 v[20:23], v[164:167], v[202:205], v[20:23]
	v_mfma_f32_16x16x32_bf16 v[16:19], v[178:181], v[202:205], v[16:19]
	v_mfma_f32_16x16x32_bf16 v[4:7], v[164:167], v[210:213], v[4:7]
	v_mfma_f32_16x16x32_bf16 v[0:3], v[178:181], v[210:213], v[0:3]
	v_mfma_f32_16x16x32_bf16 v[52:55], v[168:171], v[190:193], v[52:55]
	v_mfma_f32_16x16x32_bf16 v[48:51], v[182:185], v[190:193], v[48:51]
	v_mfma_f32_16x16x32_bf16 v[36:39], v[168:171], v[198:201], v[36:39]
	v_mfma_f32_16x16x32_bf16 v[32:35], v[182:185], v[198:201], v[32:35]
	v_mfma_f32_16x16x32_bf16 v[20:23], v[168:171], v[206:209], v[20:23]
	v_mfma_f32_16x16x32_bf16 v[16:19], v[182:185], v[206:209], v[16:19]
	s_setprio 2
	s_barrier
; #define PG8_STAGE(bufoff, gbase, voff) do { _Pragma("unroll") for (int _i = 0; _i < 2; ++_i) \
;         __builtin_amdgcn_global_load_lds((const unsigned*)((const char*)(gbase) + (voff)[_i]), (PG8_LAS unsigned*)(lds + (bufoff) + ldsw + _i * 8192), 16, 0, 0); } while (0)
; #define PG8_LDA(dst, b, h) do { _Pragma("unroll") for (int m = 0; m < 4; ++m) _Pragma("unroll") for (int k = 0; k < 2; ++k) dst[m][k] = *(const PG8_LAS bf16x8*)(lds + PG8_SA(b, h) + aoff + m * 2048 + k * 1024); } while (0)
; #define PG8_LDB(dst, b, h) do { _Pragma("unroll") for (int n = 0; n < 2; ++n) _Pragma("unroll") for (int k = 0; k < 2; ++k) dst[n][k] = *(const PG8_LAS bf16x8*)(lds + PG8_SB(b, h) + boff + n * 2048 + k * 1024); } while (0)
; #define PG8_MMA(ai, bj, At, Bt) do { __builtin_amdgcn_s_setprio(1); _Pragma("unroll") for (int m = 0; m < 4; ++m) _Pragma("unroll") for (int n = 0; n < 2; ++n) _Pragma("unroll") for (int k = 0; k < 2; ++k) \
;         acc[ai][bj][m][n] = __builtin_amdgcn_mfma_f32_16x16x32_bf16(Bt[n][k], At[m][k], acc[ai][bj][m][n], 0, 0, 0); __builtin_amdgcn_s_setprio(0); } while (0)
; #define PG8_WAIT_V(n) asm volatile("s_waitcnt vmcnt(" #n ")" ::: "memory")
; #define PG8_WAIT_L(n) asm volatile("s_waitcnt lgkmcnt(" #n ")" ::: "memory")
; #define PG8_BAR __builtin_amdgcn_s_barrier()
; #define PG8_SCHED __builtin_amdgcn_sched_barrier(0)
; template <class Epi, class Sched, bool ALIGN_EPI = false, bool SP2 = false>
; __device__ __forceinline__ void gemm_phase(PG8_LAS unsigned char* lds, const Gemm g, const Sched& S, const Epi& E) {
;     ...
;             PG8_WAIT_V(8); PG8_WAIT_L(0); PG8_BAR; PG8_MMA(1, 0, At, B0); PG8_MMA(1, 1, At, B1); PG8_BAR; PG8_SCHED;
;             PG8_LDB(B0, 1, 0); PG8_LDB(B1, 1, 1); PG8_SCHED; PG8_LDA(At, 1, 0); PG8_STAGE(PG8_SA(0, 1), a2 + hstep, voffA);
;             PG8_WAIT_V(8); PG8_WAIT_L(0); PG8_BAR; PG8_MMA(0, 0, At, B0); PG8_MMA(0, 1, At, B1); PG8_BAR; PG8_SCHED;
	v_mfma_f32_16x16x32_bf16 v[4:7], v[168:171], v[214:217], v[4:7]
	v_mfma_f32_16x16x32_bf16 v[0:3], v[182:185], v[214:217], v[0:3]
	s_setprio 0
	s_add_i32 s56, 0, 0x18000
	s_add_i32 s57, 0, 0x1c000
	v_add_u32_e32 v124, s56, v172
	v_add_u32_e32 v177, s57, v172
	ds_read_b128 v[112:115], v124
	ds_read_b128 v[116:119], v124 offset:1024
	ds_read_b128 v[120:123], v124 offset:2048
	ds_read_b128 v[124:127], v124 offset:3072
	ds_read_b128 v[164:167], v177
	ds_read_b128 v[168:171], v177 offset:1024
	ds_read_b128 v[178:181], v177 offset:2048
	ds_read_b128 v[182:185], v177 offset:3072
	s_add_u32 s52, s72, 0x80000
	s_addc_u32 s53, s73, 0
	s_mov_b32 m0, s74
	ds_read_b128 v[186:189], v176 offset:32768
	ds_read_b128 v[190:193], v176 offset:33792
	ds_read_b128 v[194:197], v176 offset:34816
	ds_read_b128 v[198:201], v176 offset:35840
	ds_read_b128 v[202:205], v176 offset:36864
	ds_read_b128 v[206:209], v176 offset:37888
	ds_read_b128 v[210:213], v176 offset:38912
	ds_read_b128 v[214:217], v176 offset:39936
	global_load_lds_dwordx4 v154, s[52:53]
	s_mov_b32 m0, s75
	s_nop 0
	global_load_lds_dwordx4 v150, s[52:53]
	s_waitcnt vmcnt(8)
	s_waitcnt lgkmcnt(0)
	s_setprio 1
	s_barrier
	v_mfma_f32_16x16x32_bf16 v[140:143], v[112:115], v[186:189], v[140:143]
	v_mfma_f32_16x16x32_bf16 v[136:139], v[120:123], v[186:189], v[136:139]
	v_mfma_f32_16x16x32_bf16 v[108:111], v[112:115], v[194:197], v[108:111]
	v_mfma_f32_16x16x32_bf16 v[104:107], v[120:123], v[194:197], v[104:107]
	v_mfma_f32_16x16x32_bf16 v[92:95], v[112:115], v[202:205], v[92:95]
	v_mfma_f32_16x16x32_bf16 v[88:91], v[120:123], v[202:205], v[88:91]
	v_mfma_f32_16x16x32_bf16 v[76:79], v[112:115], v[210:213], v[76:79]
	v_mfma_f32_16x16x32_bf16 v[72:75], v[120:123], v[210:213], v[72:75]
	v_mfma_f32_16x16x32_bf16 v[140:143], v[116:119], v[190:193], v[140:143]
	v_mfma_f32_16x16x32_bf16 v[136:139], v[124:127], v[190:193], v[136:139]
	v_mfma_f32_16x16x32_bf16 v[108:111], v[116:119], v[198:201], v[108:111]
	v_mfma_f32_16x16x32_bf16 v[104:107], v[124:127], v[198:201], v[104:107]
	v_mfma_f32_16x16x32_bf16 v[92:95], v[116:119], v[206:209], v[92:95]
	v_mfma_f32_16x16x32_bf16 v[88:91], v[124:127], v[206:209], v[88:91]
	v_mfma_f32_16x16x32_bf16 v[76:79], v[116:119], v[214:217], v[76:79]
	v_mfma_f32_16x16x32_bf16 v[72:75], v[124:127], v[214:217], v[72:75]
	s_setprio 0
	s_setprio 1
	v_mfma_f32_16x16x32_bf16 v[132:135], v[164:167], v[186:189], v[132:135]
	v_mfma_f32_16x16x32_bf16 v[128:131], v[178:181], v[186:189], v[128:131]
	v_mfma_f32_16x16x32_bf16 v[100:103], v[164:167], v[194:197], v[100:103]
	v_mfma_f32_16x16x32_bf16 v[96:99], v[178:181], v[194:197], v[96:99]
	v_mfma_f32_16x16x32_bf16 v[84:87], v[164:167], v[202:205], v[84:87]
	v_mfma_f32_16x16x32_bf16 v[80:83], v[178:181], v[202:205], v[80:83]
	v_mfma_f32_16x16x32_bf16 v[68:71], v[164:167], v[210:213], v[68:71]
	v_mfma_f32_16x16x32_bf16 v[64:67], v[178:181], v[210:213], v[64:67]
	v_mfma_f32_16x16x32_bf16 v[132:135], v[168:171], v[190:193], v[132:135]
	v_mfma_f32_16x16x32_bf16 v[128:131], v[182:185], v[190:193], v[128:131]
	v_mfma_f32_16x16x32_bf16 v[100:103], v[168:171], v[198:201], v[100:103]
	v_mfma_f32_16x16x32_bf16 v[96:99], v[182:185], v[198:201], v[96:99]
	v_mfma_f32_16x16x32_bf16 v[84:87], v[168:171], v[206:209], v[84:87]
	v_mfma_f32_16x16x32_bf16 v[80:83], v[182:185], v[206:209], v[80:83]
	s_setprio 2
	s_barrier
; #define PG8_STAGE(bufoff, gbase, voff) do { _Pragma("unroll") for (int _i = 0; _i < 2; ++_i) \
;         __builtin_amdgcn_global_load_lds((const unsigned*)((const char*)(gbase) + (voff)[_i]), (PG8_LAS unsigned*)(lds + (bufoff) + ldsw + _i * 8192), 16, 0, 0); } while (0)
; #define PG8_LDA(dst, b, h) do { _Pragma("unroll") for (int m = 0; m < 4; ++m) _Pragma("unroll") for (int k = 0; k < 2; ++k) dst[m][k] = *(const PG8_LAS bf16x8*)(lds + PG8_SA(b, h) + aoff + m * 2048 + k * 1024); } while (0)
; #define PG8_MMA(ai, bj, At, Bt) do { __builtin_amdgcn_s_setprio(1); _Pragma("unroll") for (int m = 0; m < 4; ++m) _Pragma("unroll") for (int n = 0; n < 2; ++n) _Pragma("unroll") for (int k = 0; k < 2; ++k) \
;         acc[ai][bj][m][n] = __builtin_amdgcn_mfma_f32_16x16x32_bf16(Bt[n][k], At[m][k], acc[ai][bj][m][n], 0, 0, 0); __builtin_amdgcn_s_setprio(0); } while (0)
; #define PG8_WAIT_V(n) asm volatile("s_waitcnt vmcnt(" #n ")" ::: "memory")
; #define PG8_WAIT_L(n) asm volatile("s_waitcnt lgkmcnt(" #n ")" ::: "memory")
; #define PG8_BAR __builtin_amdgcn_s_barrier()
; #define PG8_SCHED __builtin_amdgcn_sched_barrier(0)
; template <class Epi, class Sched, bool ALIGN_EPI = false, bool SP2 = false>
; __device__ __forceinline__ void gemm_phase(PG8_LAS unsigned char* lds, const Gemm g, const Sched& S, const Epi& E) {
;     ...
;             PG8_WAIT_V(8); PG8_WAIT_L(0); PG8_BAR; PG8_MMA(0, 0, At, B0); PG8_MMA(0, 1, At, B1); PG8_BAR; PG8_SCHED;
;             PG8_LDA(At, 1, 1); PG8_STAGE(PG8_SB(1, 0), b3, voffB); PG8_STAGE(PG8_SB(1, 1), b3 + hstep, voffB); PG8_STAGE(PG8_SA(1, 0), a3, voffA);
;             PG8_WAIT_V(8); PG8_WAIT_L(0); PG8_BAR; PG8_MMA(1, 0, At, B0); PG8_MMA(1, 1, At, B1); PG8_BAR; PG8_SCHED;
	v_mfma_f32_16x16x32_bf16 v[68:71], v[168:171], v[214:217], v[68:71]
	v_mfma_f32_16x16x32_bf16 v[64:67], v[182:185], v[214:217], v[64:67]
	s_setprio 0
	s_add_i32 s52, s56, s29
	v_lshl_add_u64 v[218:219], v[218:219], 0, s[12:13]
	s_mov_b32 m0, s52
	ds_read_b128 v[186:189], v176 offset:49152
	ds_read_b128 v[190:193], v176 offset:50176
	ds_read_b128 v[194:197], v176 offset:51200
	ds_read_b128 v[198:201], v176 offset:52224
	ds_read_b128 v[202:205], v176 offset:53248
	ds_read_b128 v[206:209], v176 offset:54272
	ds_read_b128 v[210:213], v176 offset:55296
	ds_read_b128 v[214:217], v176 offset:56320
	global_load_lds_dwordx4 v[218:219], off
	s_add_i32 m0, s52, 0x2000
	s_add_u32 s52, s70, 0x80080
	v_lshl_add_u64 v[218:219], v[220:221], 0, s[12:13]
	s_addc_u32 s53, s71, 0
	s_add_i32 s56, s57, s29
	global_load_lds_dwordx4 v[218:219], off
	s_mov_b32 m0, s56
	s_nop 0
	global_load_lds_dwordx4 v152, s[52:53]
	s_add_i32 m0, s56, 0x2000
	s_nop 0
	global_load_lds_dwordx4 v148, s[52:53]
	s_mov_b32 m0, s77
	v_lshl_add_u64 v[218:219], v[222:223], 0, s[12:13]
	global_load_lds_dwordx4 v[218:219], off
	s_mov_b32 m0, s78
	v_lshl_add_u64 v[218:219], v[224:225], 0, s[12:13]
	global_load_lds_dwordx4 v[218:219], off
	s_waitcnt vmcnt(8)
	s_waitcnt lgkmcnt(0)
	s_setprio 1
	s_barrier
	v_mfma_f32_16x16x32_bf16 v[60:63], v[112:115], v[186:189], v[60:63]
	v_mfma_f32_16x16x32_bf16 v[56:59], v[120:123], v[186:189], v[56:59]
	v_mfma_f32_16x16x32_bf16 v[44:47], v[112:115], v[194:197], v[44:47]
	v_mfma_f32_16x16x32_bf16 v[40:43], v[120:123], v[194:197], v[40:43]
	v_mfma_f32_16x16x32_bf16 v[28:31], v[112:115], v[202:205], v[28:31]
	v_mfma_f32_16x16x32_bf16 v[24:27], v[120:123], v[202:205], v[24:27]
	v_mfma_f32_16x16x32_bf16 v[12:15], v[112:115], v[210:213], v[12:15]
	v_mfma_f32_16x16x32_bf16 v[8:11], v[120:123], v[210:213], v[8:11]
	v_mfma_f32_16x16x32_bf16 v[60:63], v[116:119], v[190:193], v[60:63]
	v_mfma_f32_16x16x32_bf16 v[56:59], v[124:127], v[190:193], v[56:59]
	v_mfma_f32_16x16x32_bf16 v[44:47], v[116:119], v[198:201], v[44:47]
	v_mfma_f32_16x16x32_bf16 v[40:43], v[124:127], v[198:201], v[40:43]
	v_mfma_f32_16x16x32_bf16 v[28:31], v[116:119], v[206:209], v[28:31]
	v_mfma_f32_16x16x32_bf16 v[24:27], v[124:127], v[206:209], v[24:27]
	v_mfma_f32_16x16x32_bf16 v[12:15], v[116:119], v[214:217], v[12:15]
	v_mfma_f32_16x16x32_bf16 v[8:11], v[124:127], v[214:217], v[8:11]
	s_setprio 0
	s_setprio 1
	v_mfma_f32_16x16x32_bf16 v[52:55], v[164:167], v[186:189], v[52:55]
	v_mfma_f32_16x16x32_bf16 v[48:51], v[178:181], v[186:189], v[48:51]
	v_mfma_f32_16x16x32_bf16 v[36:39], v[164:167], v[194:197], v[36:39]
	v_mfma_f32_16x16x32_bf16 v[32:35], v[178:181], v[194:197], v[32:35]
	v_mfma_f32_16x16x32_bf16 v[20:23], v[164:167], v[202:205], v[20:23]
	v_mfma_f32_16x16x32_bf16 v[16:19], v[178:181], v[202:205], v[16:19]
	v_mfma_f32_16x16x32_bf16 v[4:7], v[164:167], v[210:213], v[4:7]
	v_mfma_f32_16x16x32_bf16 v[0:3], v[178:181], v[210:213], v[0:3]
	v_mfma_f32_16x16x32_bf16 v[52:55], v[168:171], v[190:193], v[52:55]
	v_mfma_f32_16x16x32_bf16 v[48:51], v[182:185], v[190:193], v[48:51]
	v_mfma_f32_16x16x32_bf16 v[36:39], v[168:171], v[198:201], v[36:39]
	v_mfma_f32_16x16x32_bf16 v[32:35], v[182:185], v[198:201], v[32:35]
	v_mfma_f32_16x16x32_bf16 v[20:23], v[168:171], v[206:209], v[20:23]
	v_mfma_f32_16x16x32_bf16 v[16:19], v[182:185], v[206:209], v[16:19]
	s_setprio 2
	s_barrier
	v_mfma_f32_16x16x32_bf16 v[4:7], v[168:171], v[214:217], v[4:7]
	v_mfma_f32_16x16x32_bf16 v[0:3], v[182:185], v[214:217], v[0:3]
	s_setprio 0
	s_add_i32 s88, s88, 2
	s_add_u32 s68, s68, 0x100
	s_addc_u32 s69, s69, 0
	s_add_u32 s86, s86, 0x100
	s_addc_u32 s87, s87, 0
	s_cmp_gt_u32 s88, 29
	s_cbranch_scc0 .LBB0_545
	s_and_b64 vcc, exec, s[14:15]
	s_cbranch_vccz .LBB0_548
	s_barrier

; #define PG8_STAGE(bufoff, gbase, voff) do { _Pragma("unroll") for (int _i = 0; _i < 2; ++_i) \
;         __builtin_amdgcn_global_load_lds((const unsigned*)((const char*)(gbase) + (voff)[_i]), (PG8_LAS unsigned*)(lds + (bufoff) + ldsw + _i * 8192), 16, 0, 0); } while (0)
; #define PG8_LDA(dst, b, h) do { _Pragma("unroll") for (int m = 0; m < 4; ++m) _Pragma("unroll") for (int k = 0; k < 2; ++k) dst[m][k] = *(const PG8_LAS bf16x8*)(lds + PG8_SA(b, h) + aoff + m * 2048 + k * 1024); } while (0)
; #define PG8_LDB(dst, b, h) do { _Pragma("unroll") for (int n = 0; n < 2; ++n) _Pragma("unroll") for (int k = 0; k < 2; ++k) dst[n][k] = *(const PG8_LAS bf16x8*)(lds + PG8_SB(b, h) + boff + n * 2048 + k * 1024); } while (0)
; #define PG8_MMA(ai, bj, At, Bt) do { __builtin_amdgcn_s_setprio(1); _Pragma("unroll") for (int m = 0; m < 4; ++m) _Pragma("unroll") for (int n = 0; n < 2; ++n) _Pragma("unroll") for (int k = 0; k < 2; ++k) \
;         acc[ai][bj][m][n] = __builtin_amdgcn_mfma_f32_16x16x32_bf16(Bt[n][k], At[m][k], acc[ai][bj][m][n], 0, 0, 0); __builtin_amdgcn_s_setprio(0); } while (0)
; #define PG8_WAIT_V(n) asm volatile("s_waitcnt vmcnt(" #n ")" ::: "memory")
; #define PG8_WAIT_L(n) asm volatile("s_waitcnt lgkmcnt(" #n ")" ::: "memory")
; #define PG8_BAR __builtin_amdgcn_s_barrier()
; #define PG8_SCHED __builtin_amdgcn_sched_barrier(0)
; template <class Epi, class Sched, bool ALIGN_EPI = false, bool SP2 = false>
; __device__ __forceinline__ void gemm_phase(PG8_LAS unsigned char* lds, const Gemm g, const Sched& S, const Epi& E) {
;     ...
;             const char* a1 = cA + (size_t)(t + 1) * kstep;
;             const char* a2 = last ? nA : cA + (size_t)(t + 2) * kstep; const char* b2 = last ? nB : cB + (size_t)(t + 2) * kstep;
;             const char* a3 = a2 + kstep; const char* b3 = b2 + kstep;
;             if constexpr (SP2) {
;             PG8_LDB(B0, 0, 0); PG8_LDB(B1, 0, 1); PG8_SCHED; PG8_LDA(At, 0, 0); PG8_STAGE(PG8_SA(1, 1), a1 + hstep, voffA);
;             PG8_WAIT_V(8); PG8_WAIT_L(0); PG8_BAR; PG8_MMA(0, 0, At, B0); PG8_MMA(0, 1, At, B1); PG8_BAR; PG8_SCHED;
;             PG8_LDA(At, 0, 1); PG8_STAGE(PG8_SB(0, 0), b2, voffB); PG8_STAGE(PG8_SB(0, 1), b2 + hstep, voffB); PG8_STAGE(PG8_SA(0, 0), a2, voffA);
;             PG8_WAIT_V(8); PG8_WAIT_L(0); PG8_BAR; PG8_MMA(1, 0, At, B0); PG8_MMA(1, 1, At, B1); PG8_BAR; PG8_SCHED;
.LBB0_624:
	ds_read_b128 v[128:131], v214
	ds_read_b128 v[132:135], v214 offset:1024
	ds_read_b128 v[158:161], v214 offset:2048
	ds_read_b128 v[162:165], v214 offset:3072
	ds_read_b128 v[166:169], v215
	ds_read_b128 v[170:173], v215 offset:1024
	ds_read_b128 v[174:177], v215 offset:2048
	ds_read_b128 v[178:181], v215 offset:3072
	s_add_u32 s52, s74, 0xffe00080
	s_addc_u32 s53, s75, -1
	s_cmpk_eq_i32 vcc_hi, 0x7c
	s_cselect_b32 s79, s51, s53
	s_cselect_b32 s78, s71, s52
	s_cselect_b32 s77, s49, vcc_lo
	s_cselect_b32 s76, s73, s93
	s_add_i32 m0, s83, 0xc000
	ds_read_b128 v[182:185], v216
	ds_read_b128 v[186:189], v216 offset:1024
	ds_read_b128 v[190:193], v216 offset:2048
	ds_read_b128 v[194:197], v216 offset:3072
	ds_read_b128 v[198:201], v216 offset:4096
	ds_read_b128 v[202:205], v216 offset:5120
	ds_read_b128 v[218:221], v216 offset:6144
	ds_read_b128 v[222:225], v216 offset:7168
	global_load_lds_dwordx4 v150, s[74:75]
	s_add_i32 m0, s83, 0xe000
	s_nop 0
	global_load_lds_dwordx4 v152, s[74:75]
	s_waitcnt vmcnt(8)
	s_waitcnt lgkmcnt(0)
	s_setprio 1
	s_barrier
	v_mfma_f32_16x16x32_bf16 v[124:127], v[128:131], v[182:185], v[124:127]
	v_mfma_f32_16x16x32_bf16 v[120:123], v[158:161], v[182:185], v[120:123]
	v_mfma_f32_16x16x32_bf16 v[116:119], v[128:131], v[190:193], v[116:119]
	v_mfma_f32_16x16x32_bf16 v[112:115], v[158:161], v[190:193], v[112:115]
	v_mfma_f32_16x16x32_bf16 v[108:111], v[128:131], v[198:201], v[108:111]
	v_mfma_f32_16x16x32_bf16 v[104:107], v[158:161], v[198:201], v[104:107]
	v_mfma_f32_16x16x32_bf16 v[100:103], v[128:131], v[218:221], v[100:103]
	v_mfma_f32_16x16x32_bf16 v[96:99], v[158:161], v[218:221], v[96:99]
	v_mfma_f32_16x16x32_bf16 v[124:127], v[132:135], v[186:189], v[124:127]
	v_mfma_f32_16x16x32_bf16 v[120:123], v[162:165], v[186:189], v[120:123]
	v_mfma_f32_16x16x32_bf16 v[116:119], v[132:135], v[194:197], v[116:119]
	v_mfma_f32_16x16x32_bf16 v[112:115], v[162:165], v[194:197], v[112:115]
	v_mfma_f32_16x16x32_bf16 v[108:111], v[132:135], v[202:205], v[108:111]
	v_mfma_f32_16x16x32_bf16 v[104:107], v[162:165], v[202:205], v[104:107]
	v_mfma_f32_16x16x32_bf16 v[100:103], v[132:135], v[222:225], v[100:103]
	v_mfma_f32_16x16x32_bf16 v[96:99], v[162:165], v[222:225], v[96:99]
	s_setprio 0
	s_setprio 1
	v_mfma_f32_16x16x32_bf16 v[60:63], v[166:169], v[182:185], v[60:63]
	v_mfma_f32_16x16x32_bf16 v[56:59], v[174:177], v[182:185], v[56:59]
	v_mfma_f32_16x16x32_bf16 v[52:55], v[166:169], v[190:193], v[52:55]
	v_mfma_f32_16x16x32_bf16 v[48:51], v[174:177], v[190:193], v[48:51]
	v_mfma_f32_16x16x32_bf16 v[44:47], v[166:169], v[198:201], v[44:47]
	v_mfma_f32_16x16x32_bf16 v[40:43], v[174:177], v[198:201], v[40:43]
	v_mfma_f32_16x16x32_bf16 v[36:39], v[166:169], v[218:221], v[36:39]
	v_mfma_f32_16x16x32_bf16 v[32:35], v[174:177], v[218:221], v[32:35]
	v_mfma_f32_16x16x32_bf16 v[60:63], v[170:173], v[186:189], v[60:63]
	v_mfma_f32_16x16x32_bf16 v[56:59], v[178:181], v[186:189], v[56:59]
	v_mfma_f32_16x16x32_bf16 v[52:55], v[170:173], v[194:197], v[52:55]
	v_mfma_f32_16x16x32_bf16 v[48:51], v[178:181], v[194:197], v[48:51]
	v_mfma_f32_16x16x32_bf16 v[44:47], v[170:173], v[202:205], v[44:47]
	v_mfma_f32_16x16x32_bf16 v[40:43], v[178:181], v[202:205], v[40:43]
	s_setprio 2
	s_barrier
	v_mfma_f32_16x16x32_bf16 v[36:39], v[170:173], v[222:225], v[36:39]
	v_mfma_f32_16x16x32_bf16 v[32:35], v[178:181], v[222:225], v[32:35]
	s_setprio 0
	s_add_i32 s52, s33, s82
	v_lshl_add_u64 v[226:227], s[76:77], 0, v[138:139]
	s_mov_b32 m0, s52
	ds_read_b128 v[182:185], v216 offset:16384
	ds_read_b128 v[186:189], v216 offset:17408
	ds_read_b128 v[190:193], v216 offset:18432
	ds_read_b128 v[194:197], v216 offset:19456
	ds_read_b128 v[198:201], v216 offset:20480
	ds_read_b128 v[202:205], v216 offset:21504
	ds_read_b128 v[218:221], v216 offset:22528
	ds_read_b128 v[222:225], v216 offset:23552
	global_load_lds_dwordx4 v[226:227], off
	s_add_i32 m0, s52, 0x2000
	s_add_u32 s52, s76, 0x200000
	v_lshl_add_u64 v[228:229], s[76:77], 0, v[142:143]
	s_addc_u32 s53, s77, 0
	s_add_i32 s56, s92, s82
	global_load_lds_dwordx4 v[228:229], off
	s_mov_b32 m0, s56
	v_lshl_add_u64 v[232:233], s[78:79], 0, v[140:141]
	global_load_lds_dwordx4 v138, s[52:53]
	s_add_i32 m0, s56, 0x2000
	s_nop 0
	global_load_lds_dwordx4 v142, s[52:53]
	s_mov_b32 m0, s83
	v_lshl_add_u64 v[230:231], s[78:79], 0, v[136:137]
	global_load_lds_dwordx4 v[230:231], off
	s_mov_b32 m0, s84
	s_nop 0
	global_load_lds_dwordx4 v[232:233], off
	s_waitcnt vmcnt(8)
	s_waitcnt lgkmcnt(0)
	s_setprio 1
	s_barrier
	v_mfma_f32_16x16x32_bf16 v[92:95], v[128:131], v[182:185], v[92:95]
	v_mfma_f32_16x16x32_bf16 v[88:91], v[158:161], v[182:185], v[88:91]
	v_mfma_f32_16x16x32_bf16 v[84:87], v[128:131], v[190:193], v[84:87]
	v_mfma_f32_16x16x32_bf16 v[80:83], v[158:161], v[190:193], v[80:83]
	v_mfma_f32_16x16x32_bf16 v[76:79], v[128:131], v[198:201], v[76:79]
	v_mfma_f32_16x16x32_bf16 v[72:75], v[158:161], v[198:201], v[72:75]
	v_mfma_f32_16x16x32_bf16 v[68:71], v[128:131], v[218:221], v[68:71]
	v_mfma_f32_16x16x32_bf16 v[64:67], v[158:161], v[218:221], v[64:67]
	v_mfma_f32_16x16x32_bf16 v[92:95], v[132:135], v[186:189], v[92:95]
	v_mfma_f32_16x16x32_bf16 v[88:91], v[162:165], v[186:189], v[88:91]
	v_mfma_f32_16x16x32_bf16 v[84:87], v[132:135], v[194:197], v[84:87]
	v_mfma_f32_16x16x32_bf16 v[80:83], v[162:165], v[194:197], v[80:83]
	v_mfma_f32_16x16x32_bf16 v[76:79], v[132:135], v[202:205], v[76:79]
	v_mfma_f32_16x16x32_bf16 v[72:75], v[162:165], v[202:205], v[72:75]
	v_mfma_f32_16x16x32_bf16 v[68:71], v[132:135], v[222:225], v[68:71]
	v_mfma_f32_16x16x32_bf16 v[64:67], v[162:165], v[222:225], v[64:67]
	s_setprio 0
	s_setprio 1
	v_mfma_f32_16x16x32_bf16 v[28:31], v[166:169], v[182:185], v[28:31]
	v_mfma_f32_16x16x32_bf16 v[24:27], v[174:177], v[182:185], v[24:27]
	v_mfma_f32_16x16x32_bf16 v[20:23], v[166:169], v[190:193], v[20:23]
	v_mfma_f32_16x16x32_bf16 v[16:19], v[174:177], v[190:193], v[16:19]
	v_mfma_f32_16x16x32_bf16 v[12:15], v[166:169], v[198:201], v[12:15]
	v_mfma_f32_16x16x32_bf16 v[8:11], v[174:177], v[198:201], v[8:11]
	v_mfma_f32_16x16x32_bf16 v[4:7], v[166:169], v[218:221], v[4:7]
	v_mfma_f32_16x16x32_bf16 v[0:3], v[174:177], v[218:221], v[0:3]
	v_mfma_f32_16x16x32_bf16 v[28:31], v[170:173], v[186:189], v[28:31]
	v_mfma_f32_16x16x32_bf16 v[24:27], v[178:181], v[186:189], v[24:27]
	v_mfma_f32_16x16x32_bf16 v[20:23], v[170:173], v[194:197], v[20:23]
	v_mfma_f32_16x16x32_bf16 v[16:19], v[178:181], v[194:197], v[16:19]
	v_mfma_f32_16x16x32_bf16 v[12:15], v[170:173], v[202:205], v[12:15]
	v_mfma_f32_16x16x32_bf16 v[8:11], v[178:181], v[202:205], v[8:11]
	s_setprio 2
	s_barrier
; #define PG8_STAGE(bufoff, gbase, voff) do { _Pragma("unroll") for (int _i = 0; _i < 2; ++_i) \
;         __builtin_amdgcn_global_load_lds((const unsigned*)((const char*)(gbase) + (voff)[_i]), (PG8_LAS unsigned*)(lds + (bufoff) + ldsw + _i * 8192), 16, 0, 0); } while (0)
; #define PG8_LDA(dst, b, h) do { _Pragma("unroll") for (int m = 0; m < 4; ++m) _Pragma("unroll") for (int k = 0; k < 2; ++k) dst[m][k] = *(const PG8_LAS bf16x8*)(lds + PG8_SA(b, h) + aoff + m * 2048 + k * 1024); } while (0)
; #define PG8_LDB(dst, b, h) do { _Pragma("unroll") for (int n = 0; n < 2; ++n) _Pragma("unroll") for (int k = 0; k < 2; ++k) dst[n][k] = *(const PG8_LAS bf16x8*)(lds + PG8_SB(b, h) + boff + n * 2048 + k * 1024); } while (0)
; #define PG8_MMA(ai, bj, At, Bt) do { __builtin_amdgcn_s_setprio(1); _Pragma("unroll") for (int m = 0; m < 4; ++m) _Pragma("unroll") for (int n = 0; n < 2; ++n) _Pragma("unroll") for (int k = 0; k < 2; ++k) \
;         acc[ai][bj][m][n] = __builtin_amdgcn_mfma_f32_16x16x32_bf16(Bt[n][k], At[m][k], acc[ai][bj][m][n], 0, 0, 0); __builtin_amdgcn_s_setprio(0); } while (0)
; #define PG8_WAIT_V(n) asm volatile("s_waitcnt vmcnt(" #n ")" ::: "memory")
; #define PG8_WAIT_L(n) asm volatile("s_waitcnt lgkmcnt(" #n ")" ::: "memory")
; #define PG8_BAR __builtin_amdgcn_s_barrier()
; #define PG8_SCHED __builtin_amdgcn_sched_barrier(0)
; template <class Epi, class Sched, bool ALIGN_EPI = false, bool SP2 = false>
; __device__ __forceinline__ void gemm_phase(PG8_LAS unsigned char* lds, const Gemm g, const Sched& S, const Epi& E) {
;     ...
;             PG8_WAIT_V(8); PG8_WAIT_L(0); PG8_BAR; PG8_MMA(1, 0, At, B0); PG8_MMA(1, 1, At, B1); PG8_BAR; PG8_SCHED;
;             PG8_LDB(B0, 1, 0); PG8_LDB(B1, 1, 1); PG8_SCHED; PG8_LDA(At, 1, 0); PG8_STAGE(PG8_SA(0, 1), a2 + hstep, voffA);
;             PG8_WAIT_V(8); PG8_WAIT_L(0); PG8_BAR; PG8_MMA(0, 0, At, B0); PG8_MMA(0, 1, At, B1); PG8_BAR; PG8_SCHED;
	v_mfma_f32_16x16x32_bf16 v[4:7], v[170:173], v[222:225], v[4:7]
	v_mfma_f32_16x16x32_bf16 v[0:3], v[178:181], v[222:225], v[0:3]
	s_setprio 0
	s_add_i32 s56, 0, 0x18000
	s_add_i32 s57, 0, 0x1c000
	v_add_u32_e32 v162, s56, v212
	v_add_u32_e32 v178, s57, v212
	ds_read_b128 v[128:131], v162
	ds_read_b128 v[132:135], v162 offset:1024
	ds_read_b128 v[158:161], v162 offset:2048
	ds_read_b128 v[162:165], v162 offset:3072
	ds_read_b128 v[166:169], v178
	ds_read_b128 v[170:173], v178 offset:1024
	ds_read_b128 v[174:177], v178 offset:2048
	ds_read_b128 v[178:181], v178 offset:3072
	s_add_u32 s52, s78, 0x200000
	s_addc_u32 s53, s79, 0
	s_mov_b32 m0, s85
	ds_read_b128 v[182:185], v216 offset:32768
	ds_read_b128 v[186:189], v216 offset:33792
	ds_read_b128 v[190:193], v216 offset:34816
	ds_read_b128 v[194:197], v216 offset:35840
	ds_read_b128 v[198:201], v216 offset:36864
	ds_read_b128 v[202:205], v216 offset:37888
	ds_read_b128 v[218:221], v216 offset:38912
	ds_read_b128 v[222:225], v216 offset:39936
	global_load_lds_dwordx4 v136, s[52:53]
	s_mov_b32 m0, s86
	s_nop 0
	global_load_lds_dwordx4 v140, s[52:53]
	s_waitcnt vmcnt(8)
	s_waitcnt lgkmcnt(0)
	s_setprio 1
	s_barrier
	v_mfma_f32_16x16x32_bf16 v[124:127], v[128:131], v[182:185], v[124:127]
	v_mfma_f32_16x16x32_bf16 v[120:123], v[158:161], v[182:185], v[120:123]
	v_mfma_f32_16x16x32_bf16 v[116:119], v[128:131], v[190:193], v[116:119]
	v_mfma_f32_16x16x32_bf16 v[112:115], v[158:161], v[190:193], v[112:115]
	v_mfma_f32_16x16x32_bf16 v[108:111], v[128:131], v[198:201], v[108:111]
	v_mfma_f32_16x16x32_bf16 v[104:107], v[158:161], v[198:201], v[104:107]
	v_mfma_f32_16x16x32_bf16 v[100:103], v[128:131], v[218:221], v[100:103]
	v_mfma_f32_16x16x32_bf16 v[96:99], v[158:161], v[218:221], v[96:99]
	v_mfma_f32_16x16x32_bf16 v[124:127], v[132:135], v[186:189], v[124:127]
	v_mfma_f32_16x16x32_bf16 v[120:123], v[162:165], v[186:189], v[120:123]
	v_mfma_f32_16x16x32_bf16 v[116:119], v[132:135], v[194:197], v[116:119]
	v_mfma_f32_16x16x32_bf16 v[112:115], v[162:165], v[194:197], v[112:115]
	v_mfma_f32_16x16x32_bf16 v[108:111], v[132:135], v[202:205], v[108:111]
	v_mfma_f32_16x16x32_bf16 v[104:107], v[162:165], v[202:205], v[104:107]
	v_mfma_f32_16x16x32_bf16 v[100:103], v[132:135], v[222:225], v[100:103]
	v_mfma_f32_16x16x32_bf16 v[96:99], v[162:165], v[222:225], v[96:99]
	s_setprio 0
	s_setprio 1
	v_mfma_f32_16x16x32_bf16 v[60:63], v[166:169], v[182:185], v[60:63]
	v_mfma_f32_16x16x32_bf16 v[56:59], v[174:177], v[182:185], v[56:59]
	v_mfma_f32_16x16x32_bf16 v[52:55], v[166:169], v[190:193], v[52:55]
	v_mfma_f32_16x16x32_bf16 v[48:51], v[174:177], v[190:193], v[48:51]
	v_mfma_f32_16x16x32_bf16 v[44:47], v[166:169], v[198:201], v[44:47]
	v_mfma_f32_16x16x32_bf16 v[40:43], v[174:177], v[198:201], v[40:43]
	v_mfma_f32_16x16x32_bf16 v[36:39], v[166:169], v[218:221], v[36:39]
	v_mfma_f32_16x16x32_bf16 v[32:35], v[174:177], v[218:221], v[32:35]
	v_mfma_f32_16x16x32_bf16 v[60:63], v[170:173], v[186:189], v[60:63]
	v_mfma_f32_16x16x32_bf16 v[56:59], v[178:181], v[186:189], v[56:59]
	v_mfma_f32_16x16x32_bf16 v[52:55], v[170:173], v[194:197], v[52:55]
	v_mfma_f32_16x16x32_bf16 v[48:51], v[178:181], v[194:197], v[48:51]
	v_mfma_f32_16x16x32_bf16 v[44:47], v[170:173], v[202:205], v[44:47]
	v_mfma_f32_16x16x32_bf16 v[40:43], v[178:181], v[202:205], v[40:43]
	s_setprio 2
	s_barrier
; #define PG8_STAGE(bufoff, gbase, voff) do { _Pragma("unroll") for (int _i = 0; _i < 2; ++_i) \
;         __builtin_amdgcn_global_load_lds((const unsigned*)((const char*)(gbase) + (voff)[_i]), (PG8_LAS unsigned*)(lds + (bufoff) + ldsw + _i * 8192), 16, 0, 0); } while (0)
; #define PG8_LDA(dst, b, h) do { _Pragma("unroll") for (int m = 0; m < 4; ++m) _Pragma("unroll") for (int k = 0; k < 2; ++k) dst[m][k] = *(const PG8_LAS bf16x8*)(lds + PG8_SA(b, h) + aoff + m * 2048 + k * 1024); } while (0)
; #define PG8_MMA(ai, bj, At, Bt) do { __builtin_amdgcn_s_setprio(1); _Pragma("unroll") for (int m = 0; m < 4; ++m) _Pragma("unroll") for (int n = 0; n < 2; ++n) _Pragma("unroll") for (int k = 0; k < 2; ++k) \
;         acc[ai][bj][m][n] = __builtin_amdgcn_mfma_f32_16x16x32_bf16(Bt[n][k], At[m][k], acc[ai][bj][m][n], 0, 0, 0); __builtin_amdgcn_s_setprio(0); } while (0)
; #define PG8_WAIT_V(n) asm volatile("s_waitcnt vmcnt(" #n ")" ::: "memory")
; #define PG8_WAIT_L(n) asm volatile("s_waitcnt lgkmcnt(" #n ")" ::: "memory")
; #define PG8_BAR __builtin_amdgcn_s_barrier()
; #define PG8_SCHED __builtin_amdgcn_sched_barrier(0)
; template <class Epi, class Sched, bool ALIGN_EPI = false, bool SP2 = false>
; __device__ __forceinline__ void gemm_phase(PG8_LAS unsigned char* lds, const Gemm g, const Sched& S, const Epi& E) {
;     ...
;             PG8_WAIT_V(8); PG8_WAIT_L(0); PG8_BAR; PG8_MMA(0, 0, At, B0); PG8_MMA(0, 1, At, B1); PG8_BAR; PG8_SCHED;
;             PG8_LDA(At, 1, 1); PG8_STAGE(PG8_SB(1, 0), b3, voffB); PG8_STAGE(PG8_SB(1, 1), b3 + hstep, voffB); PG8_STAGE(PG8_SA(1, 0), a3, voffA);
;             PG8_WAIT_V(8); PG8_WAIT_L(0); PG8_BAR; PG8_MMA(1, 0, At, B0); PG8_MMA(1, 1, At, B1); PG8_BAR; PG8_SCHED;
	v_mfma_f32_16x16x32_bf16 v[36:39], v[170:173], v[222:225], v[36:39]
	v_mfma_f32_16x16x32_bf16 v[32:35], v[178:181], v[222:225], v[32:35]
	s_setprio 0
	s_add_i32 s52, s56, s82
	v_lshl_add_u64 v[226:227], v[226:227], 0, s[36:37]
	s_mov_b32 m0, s52
	ds_read_b128 v[182:185], v216 offset:49152
	ds_read_b128 v[186:189], v216 offset:50176
	ds_read_b128 v[190:193], v216 offset:51200
	ds_read_b128 v[194:197], v216 offset:52224
	ds_read_b128 v[198:201], v216 offset:53248
	ds_read_b128 v[202:205], v216 offset:54272
	ds_read_b128 v[218:221], v216 offset:55296
	ds_read_b128 v[222:225], v216 offset:56320
	global_load_lds_dwordx4 v[226:227], off
	s_add_i32 m0, s52, 0x2000
	s_add_u32 s52, s76, 0x200080
	v_lshl_add_u64 v[226:227], v[228:229], 0, s[36:37]
	s_addc_u32 s53, s77, 0
	s_add_i32 s56, s57, s82
	global_load_lds_dwordx4 v[226:227], off
	s_mov_b32 m0, s56
	s_nop 0
	global_load_lds_dwordx4 v138, s[52:53]
	s_add_i32 m0, s56, 0x2000
	s_nop 0
	global_load_lds_dwordx4 v142, s[52:53]
	s_mov_b32 m0, s94
	v_lshl_add_u64 v[226:227], v[230:231], 0, s[36:37]
	global_load_lds_dwordx4 v[226:227], off
	s_mov_b32 m0, s95
	v_lshl_add_u64 v[226:227], v[232:233], 0, s[36:37]
	global_load_lds_dwordx4 v[226:227], off
	s_waitcnt vmcnt(8)
	s_waitcnt lgkmcnt(0)
	s_setprio 1
	s_barrier
	v_mfma_f32_16x16x32_bf16 v[92:95], v[128:131], v[182:185], v[92:95]
	v_mfma_f32_16x16x32_bf16 v[88:91], v[158:161], v[182:185], v[88:91]
	v_mfma_f32_16x16x32_bf16 v[84:87], v[128:131], v[190:193], v[84:87]
	v_mfma_f32_16x16x32_bf16 v[80:83], v[158:161], v[190:193], v[80:83]
	v_mfma_f32_16x16x32_bf16 v[76:79], v[128:131], v[198:201], v[76:79]
	v_mfma_f32_16x16x32_bf16 v[72:75], v[158:161], v[198:201], v[72:75]
	v_mfma_f32_16x16x32_bf16 v[68:71], v[128:131], v[218:221], v[68:71]
	v_mfma_f32_16x16x32_bf16 v[64:67], v[158:161], v[218:221], v[64:67]
	v_mfma_f32_16x16x32_bf16 v[92:95], v[132:135], v[186:189], v[92:95]
	v_mfma_f32_16x16x32_bf16 v[88:91], v[162:165], v[186:189], v[88:91]
	v_mfma_f32_16x16x32_bf16 v[84:87], v[132:135], v[194:197], v[84:87]
	v_mfma_f32_16x16x32_bf16 v[80:83], v[162:165], v[194:197], v[80:83]
	v_mfma_f32_16x16x32_bf16 v[76:79], v[132:135], v[202:205], v[76:79]
	v_mfma_f32_16x16x32_bf16 v[72:75], v[162:165], v[202:205], v[72:75]
	v_mfma_f32_16x16x32_bf16 v[68:71], v[132:135], v[222:225], v[68:71]
	v_mfma_f32_16x16x32_bf16 v[64:67], v[162:165], v[222:225], v[64:67]
	s_setprio 0
	s_setprio 1
	v_mfma_f32_16x16x32_bf16 v[28:31], v[166:169], v[182:185], v[28:31]
	v_mfma_f32_16x16x32_bf16 v[24:27], v[174:177], v[182:185], v[24:27]
	v_mfma_f32_16x16x32_bf16 v[20:23], v[166:169], v[190:193], v[20:23]
	v_mfma_f32_16x16x32_bf16 v[16:19], v[174:177], v[190:193], v[16:19]
	v_mfma_f32_16x16x32_bf16 v[12:15], v[166:169], v[198:201], v[12:15]
	v_mfma_f32_16x16x32_bf16 v[8:11], v[174:177], v[198:201], v[8:11]
	v_mfma_f32_16x16x32_bf16 v[4:7], v[166:169], v[218:221], v[4:7]
	v_mfma_f32_16x16x32_bf16 v[0:3], v[174:177], v[218:221], v[0:3]
	v_mfma_f32_16x16x32_bf16 v[28:31], v[170:173], v[186:189], v[28:31]
	v_mfma_f32_16x16x32_bf16 v[24:27], v[178:181], v[186:189], v[24:27]
	v_mfma_f32_16x16x32_bf16 v[20:23], v[170:173], v[194:197], v[20:23]
	v_mfma_f32_16x16x32_bf16 v[16:19], v[178:181], v[194:197], v[16:19]
	v_mfma_f32_16x16x32_bf16 v[12:15], v[170:173], v[202:205], v[12:15]
	v_mfma_f32_16x16x32_bf16 v[8:11], v[178:181], v[202:205], v[8:11]
	s_setprio 2
	s_barrier
	v_mfma_f32_16x16x32_bf16 v[4:7], v[170:173], v[222:225], v[4:7]
	v_mfma_f32_16x16x32_bf16 v[0:3], v[178:181], v[222:225], v[0:3]
	s_setprio 0
	s_add_i32 vcc_hi, vcc_hi, 2
	s_add_u32 s74, s74, 0x100
	s_addc_u32 s75, s75, 0
	s_add_u32 s93, s93, 0x100
	s_addc_u32 vcc_lo, vcc_lo, 0
	s_cmpk_gt_u32 vcc_hi, 0x7d
	s_cbranch_scc0 .LBB0_624
	s_and_b64 vcc, exec, s[40:41]
	s_cbranch_vccz .LBB0_627
	s_barrier

; #define PG8_STAGE(bufoff, gbase, voff) do { _Pragma("unroll") for (int _i = 0; _i < 2; ++_i) \
;         __builtin_amdgcn_global_load_lds((const unsigned*)((const char*)(gbase) + (voff)[_i]), (PG8_LAS unsigned*)(lds + (bufoff) + ldsw + _i * 8192), 16, 0, 0); } while (0)
; #define PG8_LDA(dst, b, h) do { _Pragma("unroll") for (int m = 0; m < 4; ++m) _Pragma("unroll") for (int k = 0; k < 2; ++k) dst[m][k] = *(const PG8_LAS bf16x8*)(lds + PG8_SA(b, h) + aoff + m * 2048 + k * 1024); } while (0)
; #define PG8_LDB(dst, b, h) do { _Pragma("unroll") for (int n = 0; n < 2; ++n) _Pragma("unroll") for (int k = 0; k < 2; ++k) dst[n][k] = *(const PG8_LAS bf16x8*)(lds + PG8_SB(b, h) + boff + n * 2048 + k * 1024); } while (0)
; #define PG8_MMA(ai, bj, At, Bt) do { __builtin_amdgcn_s_setprio(1); _Pragma("unroll") for (int m = 0; m < 4; ++m) _Pragma("unroll") for (int n = 0; n < 2; ++n) _Pragma("unroll") for (int k = 0; k < 2; ++k) \
;         acc[ai][bj][m][n] = __builtin_amdgcn_mfma_f32_16x16x32_bf16(Bt[n][k], At[m][k], acc[ai][bj][m][n], 0, 0, 0); __builtin_amdgcn_s_setprio(0); } while (0)
; #define PG8_WAIT_V(n) asm volatile("s_waitcnt vmcnt(" #n ")" ::: "memory")
; #define PG8_WAIT_L(n) asm volatile("s_waitcnt lgkmcnt(" #n ")" ::: "memory")
; #define PG8_BAR __builtin_amdgcn_s_barrier()
; #define PG8_SCHED __builtin_amdgcn_sched_barrier(0)
; template <class Epi, class Sched, bool ALIGN_EPI = false, bool SP2 = false>
; __device__ __forceinline__ void gemm_phase(PG8_LAS unsigned char* lds, const Gemm g, const Sched& S, const Epi& E) {
;     ...
;             const char* a1 = cA + (size_t)(t + 1) * kstep;
;             const char* a2 = last ? nA : cA + (size_t)(t + 2) * kstep; const char* b2 = last ? nB : cB + (size_t)(t + 2) * kstep;
;             const char* a3 = a2 + kstep; const char* b3 = b2 + kstep;
;             if constexpr (SP2) {
;             PG8_LDB(B0, 0, 0); PG8_LDB(B1, 0, 1); PG8_SCHED; PG8_LDA(At, 0, 0); PG8_STAGE(PG8_SA(1, 1), a1 + hstep, voffA);
;             PG8_WAIT_V(8); PG8_WAIT_L(0); PG8_BAR; PG8_MMA(0, 0, At, B0); PG8_MMA(0, 1, At, B1); PG8_BAR; PG8_SCHED;
;             PG8_LDA(At, 0, 1); PG8_STAGE(PG8_SB(0, 0), b2, voffB); PG8_STAGE(PG8_SB(0, 1), b2 + hstep, voffB); PG8_STAGE(PG8_SA(0, 0), a2, voffA);
;             PG8_WAIT_V(8); PG8_WAIT_L(0); PG8_BAR; PG8_MMA(1, 0, At, B0); PG8_MMA(1, 1, At, B1); PG8_BAR; PG8_SCHED;
.LBB0_660:
	ds_read_b128 v[166:169], v145
	ds_read_b128 v[170:173], v145 offset:1024
	ds_read_b128 v[174:177], v145 offset:2048
	ds_read_b128 v[178:181], v145 offset:3072
	ds_read_b128 v[182:185], v149
	ds_read_b128 v[186:189], v149 offset:1024
	ds_read_b128 v[190:193], v149 offset:2048
	ds_read_b128 v[194:197], v149 offset:3072
	s_add_u32 s52, s72, 0xffe00080
	s_addc_u32 s53, s73, -1
	s_cmp_eq_u32 s49, 28
	s_cselect_b32 s77, s51, s53
	s_cselect_b32 s76, s50, s52
	s_cselect_b32 s75, s55, s41
	s_cselect_b32 s74, s54, s37
	s_mov_b32 m0, s82
	ds_read_b128 v[198:201], v164
	ds_read_b128 v[202:205], v164 offset:1024
	ds_read_b128 v[206:209], v164 offset:2048
	ds_read_b128 v[210:213], v164 offset:3072
	ds_read_b128 v[214:217], v164 offset:4096
	ds_read_b128 v[218:221], v164 offset:5120
	ds_read_b128 v[222:225], v164 offset:6144
	ds_read_b128 v[226:229], v164 offset:7168
	global_load_lds_dwordx4 v160, s[72:73]
	s_mov_b32 m0, s83
	s_nop 0
	global_load_lds_dwordx4 v162, s[72:73]
	s_waitcnt vmcnt(8)
	s_waitcnt lgkmcnt(0)
	s_setprio 1
	s_barrier
	v_mfma_f32_16x16x32_bf16 v[124:127], v[166:169], v[198:201], v[124:127]
	v_mfma_f32_16x16x32_bf16 v[120:123], v[174:177], v[198:201], v[120:123]
	v_mfma_f32_16x16x32_bf16 v[116:119], v[166:169], v[206:209], v[116:119]
	v_mfma_f32_16x16x32_bf16 v[108:111], v[174:177], v[206:209], v[108:111]
	v_mfma_f32_16x16x32_bf16 v[100:103], v[166:169], v[214:217], v[100:103]
	v_mfma_f32_16x16x32_bf16 v[92:95], v[174:177], v[214:217], v[92:95]
	v_mfma_f32_16x16x32_bf16 v[84:87], v[166:169], v[222:225], v[84:87]
	v_mfma_f32_16x16x32_bf16 v[76:79], v[174:177], v[222:225], v[76:79]
	v_mfma_f32_16x16x32_bf16 v[124:127], v[170:173], v[202:205], v[124:127]
	v_mfma_f32_16x16x32_bf16 v[120:123], v[178:181], v[202:205], v[120:123]
	v_mfma_f32_16x16x32_bf16 v[116:119], v[170:173], v[210:213], v[116:119]
	v_mfma_f32_16x16x32_bf16 v[108:111], v[178:181], v[210:213], v[108:111]
	v_mfma_f32_16x16x32_bf16 v[100:103], v[170:173], v[218:221], v[100:103]
	v_mfma_f32_16x16x32_bf16 v[92:95], v[178:181], v[218:221], v[92:95]
	v_mfma_f32_16x16x32_bf16 v[84:87], v[170:173], v[226:229], v[84:87]
	v_mfma_f32_16x16x32_bf16 v[76:79], v[178:181], v[226:229], v[76:79]
	s_setprio 0
	s_setprio 1
	v_mfma_f32_16x16x32_bf16 v[112:115], v[182:185], v[198:201], v[112:115]
	v_mfma_f32_16x16x32_bf16 v[104:107], v[190:193], v[198:201], v[104:107]
	v_mfma_f32_16x16x32_bf16 v[96:99], v[182:185], v[206:209], v[96:99]
	v_mfma_f32_16x16x32_bf16 v[88:91], v[190:193], v[206:209], v[88:91]
	v_mfma_f32_16x16x32_bf16 v[80:83], v[182:185], v[214:217], v[80:83]
	v_mfma_f32_16x16x32_bf16 v[72:75], v[190:193], v[214:217], v[72:75]
	v_mfma_f32_16x16x32_bf16 v[68:71], v[182:185], v[222:225], v[68:71]
	v_mfma_f32_16x16x32_bf16 v[64:67], v[190:193], v[222:225], v[64:67]
	v_mfma_f32_16x16x32_bf16 v[112:115], v[186:189], v[202:205], v[112:115]
	v_mfma_f32_16x16x32_bf16 v[104:107], v[194:197], v[202:205], v[104:107]
	v_mfma_f32_16x16x32_bf16 v[96:99], v[186:189], v[210:213], v[96:99]
	v_mfma_f32_16x16x32_bf16 v[88:91], v[194:197], v[210:213], v[88:91]
	v_mfma_f32_16x16x32_bf16 v[80:83], v[186:189], v[218:221], v[80:83]
	v_mfma_f32_16x16x32_bf16 v[72:75], v[194:197], v[218:221], v[72:75]
	s_setprio 2
	s_barrier
	v_mfma_f32_16x16x32_bf16 v[68:71], v[186:189], v[226:229], v[68:71]
	v_mfma_f32_16x16x32_bf16 v[64:67], v[194:197], v[226:229], v[64:67]
	s_setprio 0
	s_mov_b32 m0, s84
	v_lshl_add_u64 v[230:231], s[74:75], 0, v[138:139]
	s_add_u32 s52, s74, 0x200000
	ds_read_b128 v[198:201], v164 offset:16384
	ds_read_b128 v[202:205], v164 offset:17408
	ds_read_b128 v[206:209], v164 offset:18432
	ds_read_b128 v[210:213], v164 offset:19456
	ds_read_b128 v[214:217], v164 offset:20480
	ds_read_b128 v[218:221], v164 offset:21504
	ds_read_b128 v[222:225], v164 offset:22528
	ds_read_b128 v[226:229], v164 offset:23552
	global_load_lds_dwordx4 v[230:231], off
	v_lshl_add_u64 v[232:233], s[74:75], 0, v[142:143]
	s_mov_b32 m0, s85
	s_addc_u32 s53, s75, 0
	global_load_lds_dwordx4 v[232:233], off
	s_mov_b32 m0, s86
	v_lshl_add_u64 v[236:237], s[76:77], 0, v[140:141]
	global_load_lds_dwordx4 v138, s[52:53]
	s_mov_b32 m0, s87
	s_nop 0
	global_load_lds_dwordx4 v142, s[52:53]
	s_mov_b32 m0, s28
	v_lshl_add_u64 v[234:235], s[76:77], 0, v[136:137]
	global_load_lds_dwordx4 v[234:235], off
	s_mov_b32 m0, s29
	s_nop 0
	global_load_lds_dwordx4 v[236:237], off
	s_waitcnt vmcnt(8)
	s_waitcnt lgkmcnt(0)
	s_setprio 1
	s_barrier
	v_mfma_f32_16x16x32_bf16 v[60:63], v[166:169], v[198:201], v[60:63]
	v_mfma_f32_16x16x32_bf16 v[56:59], v[174:177], v[198:201], v[56:59]
	v_mfma_f32_16x16x32_bf16 v[52:55], v[166:169], v[206:209], v[52:55]
	v_mfma_f32_16x16x32_bf16 v[44:47], v[174:177], v[206:209], v[44:47]
	v_mfma_f32_16x16x32_bf16 v[36:39], v[166:169], v[214:217], v[36:39]
	v_mfma_f32_16x16x32_bf16 v[28:31], v[174:177], v[214:217], v[28:31]
	v_mfma_f32_16x16x32_bf16 v[20:23], v[166:169], v[222:225], v[20:23]
	v_mfma_f32_16x16x32_bf16 v[12:15], v[174:177], v[222:225], v[12:15]
	v_mfma_f32_16x16x32_bf16 v[60:63], v[170:173], v[202:205], v[60:63]
	v_mfma_f32_16x16x32_bf16 v[56:59], v[178:181], v[202:205], v[56:59]
	v_mfma_f32_16x16x32_bf16 v[52:55], v[170:173], v[210:213], v[52:55]
	v_mfma_f32_16x16x32_bf16 v[44:47], v[178:181], v[210:213], v[44:47]
	v_mfma_f32_16x16x32_bf16 v[36:39], v[170:173], v[218:221], v[36:39]
	v_mfma_f32_16x16x32_bf16 v[28:31], v[178:181], v[218:221], v[28:31]
	v_mfma_f32_16x16x32_bf16 v[20:23], v[170:173], v[226:229], v[20:23]
	v_mfma_f32_16x16x32_bf16 v[12:15], v[178:181], v[226:229], v[12:15]
	s_setprio 0
	s_setprio 1
	v_mfma_f32_16x16x32_bf16 v[48:51], v[182:185], v[198:201], v[48:51]
	v_mfma_f32_16x16x32_bf16 v[40:43], v[190:193], v[198:201], v[40:43]
	v_mfma_f32_16x16x32_bf16 v[32:35], v[182:185], v[206:209], v[32:35]
	v_mfma_f32_16x16x32_bf16 v[24:27], v[190:193], v[206:209], v[24:27]
	v_mfma_f32_16x16x32_bf16 v[16:19], v[182:185], v[214:217], v[16:19]
	v_mfma_f32_16x16x32_bf16 v[8:11], v[190:193], v[214:217], v[8:11]
	v_mfma_f32_16x16x32_bf16 v[4:7], v[182:185], v[222:225], v[4:7]
	v_mfma_f32_16x16x32_bf16 v[0:3], v[190:193], v[222:225], v[0:3]
	v_mfma_f32_16x16x32_bf16 v[48:51], v[186:189], v[202:205], v[48:51]
	v_mfma_f32_16x16x32_bf16 v[40:43], v[194:197], v[202:205], v[40:43]
	v_mfma_f32_16x16x32_bf16 v[32:35], v[186:189], v[210:213], v[32:35]
	v_mfma_f32_16x16x32_bf16 v[24:27], v[194:197], v[210:213], v[24:27]
	v_mfma_f32_16x16x32_bf16 v[16:19], v[186:189], v[218:221], v[16:19]
	v_mfma_f32_16x16x32_bf16 v[8:11], v[194:197], v[218:221], v[8:11]
	s_setprio 2
	s_barrier
; #define PG8_STAGE(bufoff, gbase, voff) do { _Pragma("unroll") for (int _i = 0; _i < 2; ++_i) \
;         __builtin_amdgcn_global_load_lds((const unsigned*)((const char*)(gbase) + (voff)[_i]), (PG8_LAS unsigned*)(lds + (bufoff) + ldsw + _i * 8192), 16, 0, 0); } while (0)
; #define PG8_LDA(dst, b, h) do { _Pragma("unroll") for (int m = 0; m < 4; ++m) _Pragma("unroll") for (int k = 0; k < 2; ++k) dst[m][k] = *(const PG8_LAS bf16x8*)(lds + PG8_SA(b, h) + aoff + m * 2048 + k * 1024); } while (0)
; #define PG8_LDB(dst, b, h) do { _Pragma("unroll") for (int n = 0; n < 2; ++n) _Pragma("unroll") for (int k = 0; k < 2; ++k) dst[n][k] = *(const PG8_LAS bf16x8*)(lds + PG8_SB(b, h) + boff + n * 2048 + k * 1024); } while (0)
; #define PG8_MMA(ai, bj, At, Bt) do { __builtin_amdgcn_s_setprio(1); _Pragma("unroll") for (int m = 0; m < 4; ++m) _Pragma("unroll") for (int n = 0; n < 2; ++n) _Pragma("unroll") for (int k = 0; k < 2; ++k) \
;         acc[ai][bj][m][n] = __builtin_amdgcn_mfma_f32_16x16x32_bf16(Bt[n][k], At[m][k], acc[ai][bj][m][n], 0, 0, 0); __builtin_amdgcn_s_setprio(0); } while (0)
; #define PG8_WAIT_V(n) asm volatile("s_waitcnt vmcnt(" #n ")" ::: "memory")
; #define PG8_WAIT_L(n) asm volatile("s_waitcnt lgkmcnt(" #n ")" ::: "memory")
; #define PG8_BAR __builtin_amdgcn_s_barrier()
; #define PG8_SCHED __builtin_amdgcn_sched_barrier(0)
; template <class Epi, class Sched, bool ALIGN_EPI = false, bool SP2 = false>
; __device__ __forceinline__ void gemm_phase(PG8_LAS unsigned char* lds, const Gemm g, const Sched& S, const Epi& E) {
;     ...
;             PG8_WAIT_V(8); PG8_WAIT_L(0); PG8_BAR; PG8_MMA(1, 0, At, B0); PG8_MMA(1, 1, At, B1); PG8_BAR; PG8_SCHED;
;             PG8_LDB(B0, 1, 0); PG8_LDB(B1, 1, 1); PG8_SCHED; PG8_LDA(At, 1, 0); PG8_STAGE(PG8_SA(0, 1), a2 + hstep, voffA);
;             PG8_WAIT_V(8); PG8_WAIT_L(0); PG8_BAR; PG8_MMA(0, 0, At, B0); PG8_MMA(0, 1, At, B1); PG8_BAR; PG8_SCHED;
;             PG8_LDA(At, 1, 1); PG8_STAGE(PG8_SB(1, 0), b3, voffB); PG8_STAGE(PG8_SB(1, 1), b3 + hstep, voffB); PG8_STAGE(PG8_SA(1, 0), a3, voffA);
;             PG8_WAIT_V(8); PG8_WAIT_L(0); PG8_BAR; PG8_MMA(1, 0, At, B0); PG8_MMA(1, 1, At, B1); PG8_BAR; PG8_SCHED;
	v_mfma_f32_16x16x32_bf16 v[4:7], v[186:189], v[226:229], v[4:7]
	v_mfma_f32_16x16x32_bf16 v[0:3], v[194:197], v[226:229], v[0:3]
	s_setprio 0
	ds_read_b128 v[166:169], v148
	ds_read_b128 v[170:173], v148 offset:1024
	ds_read_b128 v[174:177], v148 offset:2048
	ds_read_b128 v[178:181], v148 offset:3072
	ds_read_b128 v[182:185], v165
	ds_read_b128 v[186:189], v165 offset:1024
	ds_read_b128 v[190:193], v165 offset:2048
	ds_read_b128 v[194:197], v165 offset:3072
	s_add_u32 s52, s76, 0x200000
	s_addc_u32 s53, s77, 0
	s_mov_b32 m0, s33
	ds_read_b128 v[198:201], v164 offset:32768
	ds_read_b128 v[202:205], v164 offset:33792
	ds_read_b128 v[206:209], v164 offset:34816
	ds_read_b128 v[210:213], v164 offset:35840
	ds_read_b128 v[214:217], v164 offset:36864
	ds_read_b128 v[218:221], v164 offset:37888
	ds_read_b128 v[222:225], v164 offset:38912
	ds_read_b128 v[226:229], v164 offset:39936
	global_load_lds_dwordx4 v136, s[52:53]
	s_mov_b32 m0, s38
	s_nop 0
	global_load_lds_dwordx4 v140, s[52:53]
	s_waitcnt vmcnt(8)
	s_waitcnt lgkmcnt(0)
	s_setprio 1
	s_barrier
	v_mfma_f32_16x16x32_bf16 v[124:127], v[166:169], v[198:201], v[124:127]
	v_mfma_f32_16x16x32_bf16 v[120:123], v[174:177], v[198:201], v[120:123]
	v_mfma_f32_16x16x32_bf16 v[116:119], v[166:169], v[206:209], v[116:119]
	v_mfma_f32_16x16x32_bf16 v[108:111], v[174:177], v[206:209], v[108:111]
	v_mfma_f32_16x16x32_bf16 v[100:103], v[166:169], v[214:217], v[100:103]
	v_mfma_f32_16x16x32_bf16 v[92:95], v[174:177], v[214:217], v[92:95]
	v_mfma_f32_16x16x32_bf16 v[84:87], v[166:169], v[222:225], v[84:87]
	v_mfma_f32_16x16x32_bf16 v[76:79], v[174:177], v[222:225], v[76:79]
	v_mfma_f32_16x16x32_bf16 v[124:127], v[170:173], v[202:205], v[124:127]
	v_mfma_f32_16x16x32_bf16 v[120:123], v[178:181], v[202:205], v[120:123]
	v_mfma_f32_16x16x32_bf16 v[116:119], v[170:173], v[210:213], v[116:119]
	v_mfma_f32_16x16x32_bf16 v[108:111], v[178:181], v[210:213], v[108:111]
	v_mfma_f32_16x16x32_bf16 v[100:103], v[170:173], v[218:221], v[100:103]
	v_mfma_f32_16x16x32_bf16 v[92:95], v[178:181], v[218:221], v[92:95]
	v_mfma_f32_16x16x32_bf16 v[84:87], v[170:173], v[226:229], v[84:87]
	v_mfma_f32_16x16x32_bf16 v[76:79], v[178:181], v[226:229], v[76:79]
	s_setprio 0
	s_setprio 1
	v_mfma_f32_16x16x32_bf16 v[112:115], v[182:185], v[198:201], v[112:115]
	v_mfma_f32_16x16x32_bf16 v[104:107], v[190:193], v[198:201], v[104:107]
	v_mfma_f32_16x16x32_bf16 v[96:99], v[182:185], v[206:209], v[96:99]
	v_mfma_f32_16x16x32_bf16 v[88:91], v[190:193], v[206:209], v[88:91]
	v_mfma_f32_16x16x32_bf16 v[80:83], v[182:185], v[214:217], v[80:83]
	v_mfma_f32_16x16x32_bf16 v[72:75], v[190:193], v[214:217], v[72:75]
	v_mfma_f32_16x16x32_bf16 v[68:71], v[182:185], v[222:225], v[68:71]
	v_mfma_f32_16x16x32_bf16 v[64:67], v[190:193], v[222:225], v[64:67]
	v_mfma_f32_16x16x32_bf16 v[112:115], v[186:189], v[202:205], v[112:115]
	v_mfma_f32_16x16x32_bf16 v[104:107], v[194:197], v[202:205], v[104:107]
	v_mfma_f32_16x16x32_bf16 v[96:99], v[186:189], v[210:213], v[96:99]
	v_mfma_f32_16x16x32_bf16 v[88:91], v[194:197], v[210:213], v[88:91]
	v_mfma_f32_16x16x32_bf16 v[80:83], v[186:189], v[218:221], v[80:83]
	v_mfma_f32_16x16x32_bf16 v[72:75], v[194:197], v[218:221], v[72:75]
	s_setprio 2
	s_barrier
	v_mfma_f32_16x16x32_bf16 v[68:71], v[186:189], v[226:229], v[68:71]
	v_mfma_f32_16x16x32_bf16 v[64:67], v[194:197], v[226:229], v[64:67]
	s_setprio 0
	s_mov_b32 m0, s89
	v_lshl_add_u64 v[230:231], v[230:231], 0, s[12:13]
	ds_read_b128 v[198:201], v164 offset:49152
	ds_read_b128 v[202:205], v164 offset:50176
	ds_read_b128 v[206:209], v164 offset:51200
	ds_read_b128 v[210:213], v164 offset:52224
	ds_read_b128 v[214:217], v164 offset:53248
	ds_read_b128 v[218:221], v164 offset:54272
	ds_read_b128 v[222:225], v164 offset:55296
	ds_read_b128 v[226:229], v164 offset:56320
	global_load_lds_dwordx4 v[230:231], off
	s_add_i32 m0, s89, 0x2000
	s_add_u32 s52, s74, 0x200080
	v_lshl_add_u64 v[230:231], v[232:233], 0, s[12:13]
	s_addc_u32 s53, s75, 0
	s_add_i32 s56, s88, s3
	global_load_lds_dwordx4 v[230:231], off
	s_mov_b32 m0, s56
	s_nop 0
	global_load_lds_dwordx4 v138, s[52:53]
	s_add_i32 m0, s56, 0x2000
	s_nop 0
	global_load_lds_dwordx4 v142, s[52:53]
	s_mov_b32 m0, s71
	v_lshl_add_u64 v[230:231], v[234:235], 0, s[12:13]
	global_load_lds_dwordx4 v[230:231], off
	s_mov_b32 m0, s78
	v_lshl_add_u64 v[230:231], v[236:237], 0, s[12:13]
	global_load_lds_dwordx4 v[230:231], off
	s_waitcnt vmcnt(8)
	s_waitcnt lgkmcnt(0)
	s_setprio 1
	s_barrier
	v_mfma_f32_16x16x32_bf16 v[60:63], v[166:169], v[198:201], v[60:63]
	v_mfma_f32_16x16x32_bf16 v[56:59], v[174:177], v[198:201], v[56:59]
	v_mfma_f32_16x16x32_bf16 v[52:55], v[166:169], v[206:209], v[52:55]
	v_mfma_f32_16x16x32_bf16 v[44:47], v[174:177], v[206:209], v[44:47]
	v_mfma_f32_16x16x32_bf16 v[36:39], v[166:169], v[214:217], v[36:39]
	v_mfma_f32_16x16x32_bf16 v[28:31], v[174:177], v[214:217], v[28:31]
	v_mfma_f32_16x16x32_bf16 v[20:23], v[166:169], v[222:225], v[20:23]
	v_mfma_f32_16x16x32_bf16 v[12:15], v[174:177], v[222:225], v[12:15]
	v_mfma_f32_16x16x32_bf16 v[60:63], v[170:173], v[202:205], v[60:63]
	v_mfma_f32_16x16x32_bf16 v[56:59], v[178:181], v[202:205], v[56:59]
	v_mfma_f32_16x16x32_bf16 v[52:55], v[170:173], v[210:213], v[52:55]
	v_mfma_f32_16x16x32_bf16 v[44:47], v[178:181], v[210:213], v[44:47]
	v_mfma_f32_16x16x32_bf16 v[36:39], v[170:173], v[218:221], v[36:39]
	v_mfma_f32_16x16x32_bf16 v[28:31], v[178:181], v[218:221], v[28:31]
	v_mfma_f32_16x16x32_bf16 v[20:23], v[170:173], v[226:229], v[20:23]
	v_mfma_f32_16x16x32_bf16 v[12:15], v[178:181], v[226:229], v[12:15]
	s_setprio 0
	s_setprio 1
	v_mfma_f32_16x16x32_bf16 v[48:51], v[182:185], v[198:201], v[48:51]
	v_mfma_f32_16x16x32_bf16 v[40:43], v[190:193], v[198:201], v[40:43]
	v_mfma_f32_16x16x32_bf16 v[32:35], v[182:185], v[206:209], v[32:35]
	v_mfma_f32_16x16x32_bf16 v[24:27], v[190:193], v[206:209], v[24:27]
	v_mfma_f32_16x16x32_bf16 v[16:19], v[182:185], v[214:217], v[16:19]
	v_mfma_f32_16x16x32_bf16 v[8:11], v[190:193], v[214:217], v[8:11]
	v_mfma_f32_16x16x32_bf16 v[4:7], v[182:185], v[222:225], v[4:7]
	v_mfma_f32_16x16x32_bf16 v[0:3], v[190:193], v[222:225], v[0:3]
	v_mfma_f32_16x16x32_bf16 v[48:51], v[186:189], v[202:205], v[48:51]
	v_mfma_f32_16x16x32_bf16 v[40:43], v[194:197], v[202:205], v[40:43]
	v_mfma_f32_16x16x32_bf16 v[32:35], v[186:189], v[210:213], v[32:35]
	v_mfma_f32_16x16x32_bf16 v[24:27], v[194:197], v[210:213], v[24:27]
	v_mfma_f32_16x16x32_bf16 v[16:19], v[186:189], v[218:221], v[16:19]
	v_mfma_f32_16x16x32_bf16 v[8:11], v[194:197], v[218:221], v[8:11]
	s_setprio 2
	s_barrier
	v_mfma_f32_16x16x32_bf16 v[4:7], v[186:189], v[226:229], v[4:7]
	v_mfma_f32_16x16x32_bf16 v[0:3], v[194:197], v[226:229], v[0:3]
	s_setprio 0
	s_add_i32 s49, s49, 2
	s_add_u32 s72, s72, 0x100
	s_addc_u32 s73, s73, 0
	s_add_u32 s37, s37, 0x100
	s_addc_u32 s41, s41, 0
	s_cmp_gt_u32 s49, 29
	s_cbranch_scc0 .LBB0_660
	s_and_b64 vcc, exec, s[14:15]
	s_cbranch_vccz .LBB0_663
	s_barrier

; #define PG8_STAGE(bufoff, gbase, voff) do { _Pragma("unroll") for (int _i = 0; _i < 2; ++_i) \
;         __builtin_amdgcn_global_load_lds((const unsigned*)((const char*)(gbase) + (voff)[_i]), (PG8_LAS unsigned*)(lds + (bufoff) + ldsw + _i * 8192), 16, 0, 0); } while (0)
; #define PG8_LDA(dst, b, h) do { _Pragma("unroll") for (int m = 0; m < 4; ++m) _Pragma("unroll") for (int k = 0; k < 2; ++k) dst[m][k] = *(const PG8_LAS bf16x8*)(lds + PG8_SA(b, h) + aoff + m * 2048 + k * 1024); } while (0)
; #define PG8_LDB(dst, b, h) do { _Pragma("unroll") for (int n = 0; n < 2; ++n) _Pragma("unroll") for (int k = 0; k < 2; ++k) dst[n][k] = *(const PG8_LAS bf16x8*)(lds + PG8_SB(b, h) + boff + n * 2048 + k * 1024); } while (0)
; #define PG8_MMA(ai, bj, At, Bt) do { __builtin_amdgcn_s_setprio(1); _Pragma("unroll") for (int m = 0; m < 4; ++m) _Pragma("unroll") for (int n = 0; n < 2; ++n) _Pragma("unroll") for (int k = 0; k < 2; ++k) \
;         acc[ai][bj][m][n] = __builtin_amdgcn_mfma_f32_16x16x32_bf16(Bt[n][k], At[m][k], acc[ai][bj][m][n], 0, 0, 0); __builtin_amdgcn_s_setprio(0); } while (0)
; #define PG8_WAIT_V(n) asm volatile("s_waitcnt vmcnt(" #n ")" ::: "memory")
; #define PG8_WAIT_L(n) asm volatile("s_waitcnt lgkmcnt(" #n ")" ::: "memory")
; #define PG8_BAR __builtin_amdgcn_s_barrier()
; #define PG8_SCHED __builtin_amdgcn_sched_barrier(0)
; template <class Epi, class Sched, bool ALIGN_EPI = false, bool SP2 = false>
; __device__ __forceinline__ void gemm_phase(PG8_LAS unsigned char* lds, const Gemm g, const Sched& S, const Epi& E) {
;     ...
;             const char* a1 = cA + (size_t)(t + 1) * kstep;
;             const char* a2 = last ? nA : cA + (size_t)(t + 2) * kstep; const char* b2 = last ? nB : cB + (size_t)(t + 2) * kstep;
;             const char* a3 = a2 + kstep; const char* b3 = b2 + kstep;
;             if constexpr (SP2) {
;             PG8_LDB(B0, 0, 0); PG8_LDB(B1, 0, 1); PG8_SCHED; PG8_LDA(At, 0, 0); PG8_STAGE(PG8_SA(1, 1), a1 + hstep, voffA);
;             PG8_WAIT_V(8); PG8_WAIT_L(0); PG8_BAR; PG8_MMA(0, 0, At, B0); PG8_MMA(0, 1, At, B1); PG8_BAR; PG8_SCHED;
;             PG8_LDA(At, 0, 1); PG8_STAGE(PG8_SB(0, 0), b2, voffB); PG8_STAGE(PG8_SB(0, 1), b2 + hstep, voffB); PG8_STAGE(PG8_SA(0, 0), a2, voffA);
;             PG8_WAIT_V(8); PG8_WAIT_L(0); PG8_BAR; PG8_MMA(1, 0, At, B0); PG8_MMA(1, 1, At, B1); PG8_BAR; PG8_SCHED;
.LBB0_809:
	ds_read_b128 v[128:131], v180
	ds_read_b128 v[132:135], v180 offset:1024
	ds_read_b128 v[136:139], v180 offset:2048
	ds_read_b128 v[140:143], v180 offset:3072
	ds_read_b128 v[160:163], v181
	ds_read_b128 v[164:167], v181 offset:1024
	ds_read_b128 v[184:187], v181 offset:2048
	ds_read_b128 v[188:191], v181 offset:3072
	s_add_u32 s52, s72, 0xfff80080
	s_addc_u32 s53, s73, -1
	s_cmp_eq_u32 s92, 28
	s_cselect_b32 s77, s5, s53
	s_cselect_b32 s76, s49, s52
	s_cselect_b32 s75, s45, s91
	s_cselect_b32 s74, s89, s90
	s_add_i32 m0, s71, 0xc000
	ds_read_b128 v[192:195], v182
	ds_read_b128 v[196:199], v182 offset:1024
	ds_read_b128 v[200:203], v182 offset:2048
	ds_read_b128 v[204:207], v182 offset:3072
	ds_read_b128 v[208:211], v182 offset:4096
	ds_read_b128 v[212:215], v182 offset:5120
	ds_read_b128 v[216:219], v182 offset:6144
	ds_read_b128 v[220:223], v182 offset:7168
	global_load_lds_dwordx4 v154, s[72:73]
	s_add_i32 m0, s71, 0xe000
	s_nop 0
	global_load_lds_dwordx4 v156, s[72:73]
	s_waitcnt vmcnt(8)
	s_waitcnt lgkmcnt(0)
	s_setprio 1
	s_barrier
	v_mfma_f32_16x16x32_bf16 v[124:127], v[128:131], v[192:195], v[124:127]
	v_mfma_f32_16x16x32_bf16 v[120:123], v[136:139], v[192:195], v[120:123]
	v_mfma_f32_16x16x32_bf16 v[108:111], v[128:131], v[200:203], v[108:111]
	v_mfma_f32_16x16x32_bf16 v[104:107], v[136:139], v[200:203], v[104:107]
	v_mfma_f32_16x16x32_bf16 v[92:95], v[128:131], v[208:211], v[92:95]
	v_mfma_f32_16x16x32_bf16 v[88:91], v[136:139], v[208:211], v[88:91]
	v_mfma_f32_16x16x32_bf16 v[76:79], v[128:131], v[216:219], v[76:79]
	v_mfma_f32_16x16x32_bf16 v[72:75], v[136:139], v[216:219], v[72:75]
	v_mfma_f32_16x16x32_bf16 v[124:127], v[132:135], v[196:199], v[124:127]
	v_mfma_f32_16x16x32_bf16 v[120:123], v[140:143], v[196:199], v[120:123]
	v_mfma_f32_16x16x32_bf16 v[108:111], v[132:135], v[204:207], v[108:111]
	v_mfma_f32_16x16x32_bf16 v[104:107], v[140:143], v[204:207], v[104:107]
	v_mfma_f32_16x16x32_bf16 v[92:95], v[132:135], v[212:215], v[92:95]
	v_mfma_f32_16x16x32_bf16 v[88:91], v[140:143], v[212:215], v[88:91]
	v_mfma_f32_16x16x32_bf16 v[76:79], v[132:135], v[220:223], v[76:79]
	v_mfma_f32_16x16x32_bf16 v[72:75], v[140:143], v[220:223], v[72:75]
	s_setprio 0
	s_setprio 1
	v_mfma_f32_16x16x32_bf16 v[116:119], v[160:163], v[192:195], v[116:119]
	v_mfma_f32_16x16x32_bf16 v[112:115], v[184:187], v[192:195], v[112:115]
	v_mfma_f32_16x16x32_bf16 v[100:103], v[160:163], v[200:203], v[100:103]
	v_mfma_f32_16x16x32_bf16 v[96:99], v[184:187], v[200:203], v[96:99]
	v_mfma_f32_16x16x32_bf16 v[84:87], v[160:163], v[208:211], v[84:87]
	v_mfma_f32_16x16x32_bf16 v[80:83], v[184:187], v[208:211], v[80:83]
	v_mfma_f32_16x16x32_bf16 v[68:71], v[160:163], v[216:219], v[68:71]
	v_mfma_f32_16x16x32_bf16 v[64:67], v[184:187], v[216:219], v[64:67]
	v_mfma_f32_16x16x32_bf16 v[116:119], v[164:167], v[196:199], v[116:119]
	v_mfma_f32_16x16x32_bf16 v[112:115], v[188:191], v[196:199], v[112:115]
	v_mfma_f32_16x16x32_bf16 v[100:103], v[164:167], v[204:207], v[100:103]
	v_mfma_f32_16x16x32_bf16 v[96:99], v[188:191], v[204:207], v[96:99]
	v_mfma_f32_16x16x32_bf16 v[84:87], v[164:167], v[212:215], v[84:87]
	v_mfma_f32_16x16x32_bf16 v[80:83], v[188:191], v[212:215], v[80:83]
	s_setprio 2
	s_barrier
	v_mfma_f32_16x16x32_bf16 v[68:71], v[164:167], v[220:223], v[68:71]
	v_mfma_f32_16x16x32_bf16 v[64:67], v[188:191], v[220:223], v[64:67]
	s_setprio 0
	s_add_i32 s52, s83, s78
	v_lshl_add_u64 v[168:169], s[74:75], 0, v[148:149]
	s_mov_b32 m0, s52
	ds_read_b128 v[192:195], v182 offset:16384
	ds_read_b128 v[196:199], v182 offset:17408
	ds_read_b128 v[200:203], v182 offset:18432
	ds_read_b128 v[204:207], v182 offset:19456
	ds_read_b128 v[208:211], v182 offset:20480
	ds_read_b128 v[212:215], v182 offset:21504
	ds_read_b128 v[216:219], v182 offset:22528
	ds_read_b128 v[220:223], v182 offset:23552
	global_load_lds_dwordx4 v[168:169], off
	s_add_i32 m0, s52, 0x2000
	s_add_u32 s52, s74, 0x80000
	v_lshl_add_u64 v[224:225], s[74:75], 0, v[152:153]
	s_addc_u32 s53, s75, 0
	s_add_i32 s56, s84, s78
	global_load_lds_dwordx4 v[224:225], off
	s_mov_b32 m0, s56
	v_lshl_add_u64 v[228:229], s[76:77], 0, v[150:151]
	global_load_lds_dwordx4 v148, s[52:53]
	s_add_i32 m0, s56, 0x2000
	s_nop 0
	global_load_lds_dwordx4 v152, s[52:53]
	s_mov_b32 m0, s71
	v_lshl_add_u64 v[226:227], s[76:77], 0, v[144:145]
	global_load_lds_dwordx4 v[226:227], off
	s_mov_b32 m0, s79
	s_nop 0
	global_load_lds_dwordx4 v[228:229], off
	s_waitcnt vmcnt(8)
	s_waitcnt lgkmcnt(0)
	s_setprio 1
	s_barrier
	v_mfma_f32_16x16x32_bf16 v[60:63], v[128:131], v[192:195], v[60:63]
	v_mfma_f32_16x16x32_bf16 v[56:59], v[136:139], v[192:195], v[56:59]
	v_mfma_f32_16x16x32_bf16 v[44:47], v[128:131], v[200:203], v[44:47]
	v_mfma_f32_16x16x32_bf16 v[40:43], v[136:139], v[200:203], v[40:43]
	v_mfma_f32_16x16x32_bf16 v[28:31], v[128:131], v[208:211], v[28:31]
	v_mfma_f32_16x16x32_bf16 v[24:27], v[136:139], v[208:211], v[24:27]
	v_mfma_f32_16x16x32_bf16 v[12:15], v[128:131], v[216:219], v[12:15]
	v_mfma_f32_16x16x32_bf16 v[8:11], v[136:139], v[216:219], v[8:11]
	v_mfma_f32_16x16x32_bf16 v[60:63], v[132:135], v[196:199], v[60:63]
	v_mfma_f32_16x16x32_bf16 v[56:59], v[140:143], v[196:199], v[56:59]
	v_mfma_f32_16x16x32_bf16 v[44:47], v[132:135], v[204:207], v[44:47]
	v_mfma_f32_16x16x32_bf16 v[40:43], v[140:143], v[204:207], v[40:43]
	v_mfma_f32_16x16x32_bf16 v[28:31], v[132:135], v[212:215], v[28:31]
	v_mfma_f32_16x16x32_bf16 v[24:27], v[140:143], v[212:215], v[24:27]
	v_mfma_f32_16x16x32_bf16 v[12:15], v[132:135], v[220:223], v[12:15]
	v_mfma_f32_16x16x32_bf16 v[8:11], v[140:143], v[220:223], v[8:11]
	s_setprio 0
	s_setprio 1
	v_mfma_f32_16x16x32_bf16 v[52:55], v[160:163], v[192:195], v[52:55]
	v_mfma_f32_16x16x32_bf16 v[48:51], v[184:187], v[192:195], v[48:51]
	v_mfma_f32_16x16x32_bf16 v[36:39], v[160:163], v[200:203], v[36:39]
	v_mfma_f32_16x16x32_bf16 v[32:35], v[184:187], v[200:203], v[32:35]
	v_mfma_f32_16x16x32_bf16 v[20:23], v[160:163], v[208:211], v[20:23]
	v_mfma_f32_16x16x32_bf16 v[16:19], v[184:187], v[208:211], v[16:19]
	v_mfma_f32_16x16x32_bf16 v[4:7], v[160:163], v[216:219], v[4:7]
	v_mfma_f32_16x16x32_bf16 v[0:3], v[184:187], v[216:219], v[0:3]
	v_mfma_f32_16x16x32_bf16 v[52:55], v[164:167], v[196:199], v[52:55]
	v_mfma_f32_16x16x32_bf16 v[48:51], v[188:191], v[196:199], v[48:51]
	v_mfma_f32_16x16x32_bf16 v[36:39], v[164:167], v[204:207], v[36:39]
	v_mfma_f32_16x16x32_bf16 v[32:35], v[188:191], v[204:207], v[32:35]
	v_mfma_f32_16x16x32_bf16 v[20:23], v[164:167], v[212:215], v[20:23]
	v_mfma_f32_16x16x32_bf16 v[16:19], v[188:191], v[212:215], v[16:19]
	s_setprio 2
	s_barrier
; #define PG8_STAGE(bufoff, gbase, voff) do { _Pragma("unroll") for (int _i = 0; _i < 2; ++_i) \
;         __builtin_amdgcn_global_load_lds((const unsigned*)((const char*)(gbase) + (voff)[_i]), (PG8_LAS unsigned*)(lds + (bufoff) + ldsw + _i * 8192), 16, 0, 0); } while (0)
; #define PG8_LDA(dst, b, h) do { _Pragma("unroll") for (int m = 0; m < 4; ++m) _Pragma("unroll") for (int k = 0; k < 2; ++k) dst[m][k] = *(const PG8_LAS bf16x8*)(lds + PG8_SA(b, h) + aoff + m * 2048 + k * 1024); } while (0)
; #define PG8_LDB(dst, b, h) do { _Pragma("unroll") for (int n = 0; n < 2; ++n) _Pragma("unroll") for (int k = 0; k < 2; ++k) dst[n][k] = *(const PG8_LAS bf16x8*)(lds + PG8_SB(b, h) + boff + n * 2048 + k * 1024); } while (0)
; #define PG8_MMA(ai, bj, At, Bt) do { __builtin_amdgcn_s_setprio(1); _Pragma("unroll") for (int m = 0; m < 4; ++m) _Pragma("unroll") for (int n = 0; n < 2; ++n) _Pragma("unroll") for (int k = 0; k < 2; ++k) \
;         acc[ai][bj][m][n] = __builtin_amdgcn_mfma_f32_16x16x32_bf16(Bt[n][k], At[m][k], acc[ai][bj][m][n], 0, 0, 0); __builtin_amdgcn_s_setprio(0); } while (0)
; #define PG8_WAIT_V(n) asm volatile("s_waitcnt vmcnt(" #n ")" ::: "memory")
; #define PG8_WAIT_L(n) asm volatile("s_waitcnt lgkmcnt(" #n ")" ::: "memory")
; #define PG8_BAR __builtin_amdgcn_s_barrier()
; #define PG8_SCHED __builtin_amdgcn_sched_barrier(0)
; template <class Epi, class Sched, bool ALIGN_EPI = false, bool SP2 = false>
; __device__ __forceinline__ void gemm_phase(PG8_LAS unsigned char* lds, const Gemm g, const Sched& S, const Epi& E) {
;     ...
;             PG8_WAIT_V(8); PG8_WAIT_L(0); PG8_BAR; PG8_MMA(1, 0, At, B0); PG8_MMA(1, 1, At, B1); PG8_BAR; PG8_SCHED;
;             PG8_LDB(B0, 1, 0); PG8_LDB(B1, 1, 1); PG8_SCHED; PG8_LDA(At, 1, 0); PG8_STAGE(PG8_SA(0, 1), a2 + hstep, voffA);
;             PG8_WAIT_V(8); PG8_WAIT_L(0); PG8_BAR; PG8_MMA(0, 0, At, B0); PG8_MMA(0, 1, At, B1); PG8_BAR; PG8_SCHED;
	v_mfma_f32_16x16x32_bf16 v[4:7], v[164:167], v[220:223], v[4:7]
	v_mfma_f32_16x16x32_bf16 v[0:3], v[188:191], v[220:223], v[0:3]
	s_setprio 0
	s_add_i32 s56, 0, 0x18000
	s_add_i32 s57, 0, 0x1c000
	v_add_u32_e32 v140, s56, v171
	v_add_u32_e32 v188, s57, v171
	ds_read_b128 v[128:131], v140
	ds_read_b128 v[132:135], v140 offset:1024
	ds_read_b128 v[136:139], v140 offset:2048
	ds_read_b128 v[140:143], v140 offset:3072
	ds_read_b128 v[160:163], v188
	ds_read_b128 v[164:167], v188 offset:1024
	ds_read_b128 v[184:187], v188 offset:2048
	ds_read_b128 v[188:191], v188 offset:3072
	s_add_u32 s52, s76, 0x80000
	s_addc_u32 s53, s77, 0
	s_mov_b32 m0, s80
	ds_read_b128 v[192:195], v182 offset:32768
	ds_read_b128 v[196:199], v182 offset:33792
	ds_read_b128 v[200:203], v182 offset:34816
	ds_read_b128 v[204:207], v182 offset:35840
	ds_read_b128 v[208:211], v182 offset:36864
	ds_read_b128 v[212:215], v182 offset:37888
	ds_read_b128 v[216:219], v182 offset:38912
	ds_read_b128 v[220:223], v182 offset:39936
	global_load_lds_dwordx4 v144, s[52:53]
	s_mov_b32 m0, s81
	s_nop 0
	global_load_lds_dwordx4 v150, s[52:53]
	s_waitcnt vmcnt(8)
	s_waitcnt lgkmcnt(0)
	s_setprio 1
	s_barrier
	v_mfma_f32_16x16x32_bf16 v[124:127], v[128:131], v[192:195], v[124:127]
	v_mfma_f32_16x16x32_bf16 v[120:123], v[136:139], v[192:195], v[120:123]
	v_mfma_f32_16x16x32_bf16 v[108:111], v[128:131], v[200:203], v[108:111]
	v_mfma_f32_16x16x32_bf16 v[104:107], v[136:139], v[200:203], v[104:107]
	v_mfma_f32_16x16x32_bf16 v[92:95], v[128:131], v[208:211], v[92:95]
	v_mfma_f32_16x16x32_bf16 v[88:91], v[136:139], v[208:211], v[88:91]
	v_mfma_f32_16x16x32_bf16 v[76:79], v[128:131], v[216:219], v[76:79]
	v_mfma_f32_16x16x32_bf16 v[72:75], v[136:139], v[216:219], v[72:75]
	v_mfma_f32_16x16x32_bf16 v[124:127], v[132:135], v[196:199], v[124:127]
	v_mfma_f32_16x16x32_bf16 v[120:123], v[140:143], v[196:199], v[120:123]
	v_mfma_f32_16x16x32_bf16 v[108:111], v[132:135], v[204:207], v[108:111]
	v_mfma_f32_16x16x32_bf16 v[104:107], v[140:143], v[204:207], v[104:107]
	v_mfma_f32_16x16x32_bf16 v[92:95], v[132:135], v[212:215], v[92:95]
	v_mfma_f32_16x16x32_bf16 v[88:91], v[140:143], v[212:215], v[88:91]
	v_mfma_f32_16x16x32_bf16 v[76:79], v[132:135], v[220:223], v[76:79]
	v_mfma_f32_16x16x32_bf16 v[72:75], v[140:143], v[220:223], v[72:75]
	s_setprio 0
	s_setprio 1
	v_mfma_f32_16x16x32_bf16 v[116:119], v[160:163], v[192:195], v[116:119]
	v_mfma_f32_16x16x32_bf16 v[112:115], v[184:187], v[192:195], v[112:115]
	v_mfma_f32_16x16x32_bf16 v[100:103], v[160:163], v[200:203], v[100:103]
	v_mfma_f32_16x16x32_bf16 v[96:99], v[184:187], v[200:203], v[96:99]
	v_mfma_f32_16x16x32_bf16 v[84:87], v[160:163], v[208:211], v[84:87]
	v_mfma_f32_16x16x32_bf16 v[80:83], v[184:187], v[208:211], v[80:83]
	v_mfma_f32_16x16x32_bf16 v[68:71], v[160:163], v[216:219], v[68:71]
	v_mfma_f32_16x16x32_bf16 v[64:67], v[184:187], v[216:219], v[64:67]
	v_mfma_f32_16x16x32_bf16 v[116:119], v[164:167], v[196:199], v[116:119]
	v_mfma_f32_16x16x32_bf16 v[112:115], v[188:191], v[196:199], v[112:115]
	v_mfma_f32_16x16x32_bf16 v[100:103], v[164:167], v[204:207], v[100:103]
	v_mfma_f32_16x16x32_bf16 v[96:99], v[188:191], v[204:207], v[96:99]
	v_mfma_f32_16x16x32_bf16 v[84:87], v[164:167], v[212:215], v[84:87]
	v_mfma_f32_16x16x32_bf16 v[80:83], v[188:191], v[212:215], v[80:83]
	s_setprio 2
	s_barrier
; #define PG8_STAGE(bufoff, gbase, voff) do { _Pragma("unroll") for (int _i = 0; _i < 2; ++_i) \
;         __builtin_amdgcn_global_load_lds((const unsigned*)((const char*)(gbase) + (voff)[_i]), (PG8_LAS unsigned*)(lds + (bufoff) + ldsw + _i * 8192), 16, 0, 0); } while (0)
; #define PG8_LDA(dst, b, h) do { _Pragma("unroll") for (int m = 0; m < 4; ++m) _Pragma("unroll") for (int k = 0; k < 2; ++k) dst[m][k] = *(const PG8_LAS bf16x8*)(lds + PG8_SA(b, h) + aoff + m * 2048 + k * 1024); } while (0)
; #define PG8_MMA(ai, bj, At, Bt) do { __builtin_amdgcn_s_setprio(1); _Pragma("unroll") for (int m = 0; m < 4; ++m) _Pragma("unroll") for (int n = 0; n < 2; ++n) _Pragma("unroll") for (int k = 0; k < 2; ++k) \
;         acc[ai][bj][m][n] = __builtin_amdgcn_mfma_f32_16x16x32_bf16(Bt[n][k], At[m][k], acc[ai][bj][m][n], 0, 0, 0); __builtin_amdgcn_s_setprio(0); } while (0)
; #define PG8_WAIT_V(n) asm volatile("s_waitcnt vmcnt(" #n ")" ::: "memory")
; #define PG8_WAIT_L(n) asm volatile("s_waitcnt lgkmcnt(" #n ")" ::: "memory")
; #define PG8_BAR __builtin_amdgcn_s_barrier()
; #define PG8_SCHED __builtin_amdgcn_sched_barrier(0)
; template <class Epi, class Sched, bool ALIGN_EPI = false, bool SP2 = false>
; __device__ __forceinline__ void gemm_phase(PG8_LAS unsigned char* lds, const Gemm g, const Sched& S, const Epi& E) {
;     ...
;             PG8_WAIT_V(8); PG8_WAIT_L(0); PG8_BAR; PG8_MMA(0, 0, At, B0); PG8_MMA(0, 1, At, B1); PG8_BAR; PG8_SCHED;
;             PG8_LDA(At, 1, 1); PG8_STAGE(PG8_SB(1, 0), b3, voffB); PG8_STAGE(PG8_SB(1, 1), b3 + hstep, voffB); PG8_STAGE(PG8_SA(1, 0), a3, voffA);
;             PG8_WAIT_V(8); PG8_WAIT_L(0); PG8_BAR; PG8_MMA(1, 0, At, B0); PG8_MMA(1, 1, At, B1); PG8_BAR; PG8_SCHED;
	v_mfma_f32_16x16x32_bf16 v[68:71], v[164:167], v[220:223], v[68:71]
	v_mfma_f32_16x16x32_bf16 v[64:67], v[188:191], v[220:223], v[64:67]
	s_setprio 0
	s_add_i32 s52, s56, s78
	v_lshl_add_u64 v[168:169], v[168:169], 0, s[40:41]
	s_mov_b32 m0, s52
	ds_read_b128 v[192:195], v182 offset:49152
	ds_read_b128 v[196:199], v182 offset:50176
	ds_read_b128 v[200:203], v182 offset:51200
	ds_read_b128 v[204:207], v182 offset:52224
	ds_read_b128 v[208:211], v182 offset:53248
	ds_read_b128 v[212:215], v182 offset:54272
	ds_read_b128 v[216:219], v182 offset:55296
	ds_read_b128 v[220:223], v182 offset:56320
	global_load_lds_dwordx4 v[168:169], off
	s_add_i32 m0, s52, 0x2000
	s_add_u32 s52, s74, 0x80080
	v_lshl_add_u64 v[168:169], v[224:225], 0, s[40:41]
	s_addc_u32 s53, s75, 0
	s_add_i32 s56, s57, s78
	global_load_lds_dwordx4 v[168:169], off
	s_mov_b32 m0, s56
	s_nop 0
	global_load_lds_dwordx4 v148, s[52:53]
	s_add_i32 m0, s56, 0x2000
	s_nop 0
	global_load_lds_dwordx4 v152, s[52:53]
	s_mov_b32 m0, s3
	v_lshl_add_u64 v[168:169], v[226:227], 0, s[40:41]
	global_load_lds_dwordx4 v[168:169], off
	s_mov_b32 m0, s28
	v_lshl_add_u64 v[168:169], v[228:229], 0, s[40:41]
	global_load_lds_dwordx4 v[168:169], off
	s_waitcnt vmcnt(8)
	s_waitcnt lgkmcnt(0)
	s_setprio 1
	s_barrier
	v_mfma_f32_16x16x32_bf16 v[60:63], v[128:131], v[192:195], v[60:63]
	v_mfma_f32_16x16x32_bf16 v[56:59], v[136:139], v[192:195], v[56:59]
	v_mfma_f32_16x16x32_bf16 v[44:47], v[128:131], v[200:203], v[44:47]
	v_mfma_f32_16x16x32_bf16 v[40:43], v[136:139], v[200:203], v[40:43]
	v_mfma_f32_16x16x32_bf16 v[28:31], v[128:131], v[208:211], v[28:31]
	v_mfma_f32_16x16x32_bf16 v[24:27], v[136:139], v[208:211], v[24:27]
	v_mfma_f32_16x16x32_bf16 v[12:15], v[128:131], v[216:219], v[12:15]
	v_mfma_f32_16x16x32_bf16 v[8:11], v[136:139], v[216:219], v[8:11]
	v_mfma_f32_16x16x32_bf16 v[60:63], v[132:135], v[196:199], v[60:63]
	v_mfma_f32_16x16x32_bf16 v[56:59], v[140:143], v[196:199], v[56:59]
	v_mfma_f32_16x16x32_bf16 v[44:47], v[132:135], v[204:207], v[44:47]
	v_mfma_f32_16x16x32_bf16 v[40:43], v[140:143], v[204:207], v[40:43]
	v_mfma_f32_16x16x32_bf16 v[28:31], v[132:135], v[212:215], v[28:31]
	v_mfma_f32_16x16x32_bf16 v[24:27], v[140:143], v[212:215], v[24:27]
	v_mfma_f32_16x16x32_bf16 v[12:15], v[132:135], v[220:223], v[12:15]
	v_mfma_f32_16x16x32_bf16 v[8:11], v[140:143], v[220:223], v[8:11]
	s_setprio 0
	s_setprio 1
	v_mfma_f32_16x16x32_bf16 v[52:55], v[160:163], v[192:195], v[52:55]
	v_mfma_f32_16x16x32_bf16 v[48:51], v[184:187], v[192:195], v[48:51]
	v_mfma_f32_16x16x32_bf16 v[36:39], v[160:163], v[200:203], v[36:39]
	v_mfma_f32_16x16x32_bf16 v[32:35], v[184:187], v[200:203], v[32:35]
	v_mfma_f32_16x16x32_bf16 v[20:23], v[160:163], v[208:211], v[20:23]
	v_mfma_f32_16x16x32_bf16 v[16:19], v[184:187], v[208:211], v[16:19]
	v_mfma_f32_16x16x32_bf16 v[4:7], v[160:163], v[216:219], v[4:7]
	v_mfma_f32_16x16x32_bf16 v[0:3], v[184:187], v[216:219], v[0:3]
	v_mfma_f32_16x16x32_bf16 v[52:55], v[164:167], v[196:199], v[52:55]
	v_mfma_f32_16x16x32_bf16 v[48:51], v[188:191], v[196:199], v[48:51]
	v_mfma_f32_16x16x32_bf16 v[36:39], v[164:167], v[204:207], v[36:39]
	v_mfma_f32_16x16x32_bf16 v[32:35], v[188:191], v[204:207], v[32:35]
	v_mfma_f32_16x16x32_bf16 v[20:23], v[164:167], v[212:215], v[20:23]
	v_mfma_f32_16x16x32_bf16 v[16:19], v[188:191], v[212:215], v[16:19]
	s_setprio 2
	s_barrier
	v_mfma_f32_16x16x32_bf16 v[4:7], v[164:167], v[220:223], v[4:7]
	v_mfma_f32_16x16x32_bf16 v[0:3], v[188:191], v[220:223], v[0:3]
	s_setprio 0
	s_add_i32 s92, s92, 2
	s_add_u32 s72, s72, 0x100
	s_addc_u32 s73, s73, 0
	s_add_u32 s90, s90, 0x100
	s_addc_u32 s91, s91, 0
	s_cmp_gt_u32 s92, 29
	s_cbranch_scc0 .LBB0_809
	s_and_b64 vcc, exec, s[42:43]
	s_cbranch_vccz .LBB0_812
	s_barrier

; #define PG8_STAGE(bufoff, gbase, voff) do { _Pragma("unroll") for (int _i = 0; _i < 2; ++_i) \
;         __builtin_amdgcn_global_load_lds((const unsigned*)((const char*)(gbase) + (voff)[_i]), (PG8_LAS unsigned*)(lds + (bufoff) + ldsw + _i * 8192), 16, 0, 0); } while (0)
; #define PG8_LDA(dst, b, h) do { _Pragma("unroll") for (int m = 0; m < 4; ++m) _Pragma("unroll") for (int k = 0; k < 2; ++k) dst[m][k] = *(const PG8_LAS bf16x8*)(lds + PG8_SA(b, h) + aoff + m * 2048 + k * 1024); } while (0)
; #define PG8_LDB(dst, b, h) do { _Pragma("unroll") for (int n = 0; n < 2; ++n) _Pragma("unroll") for (int k = 0; k < 2; ++k) dst[n][k] = *(const PG8_LAS bf16x8*)(lds + PG8_SB(b, h) + boff + n * 2048 + k * 1024); } while (0)
; #define PG8_MMA(ai, bj, At, Bt) do { __builtin_amdgcn_s_setprio(1); _Pragma("unroll") for (int m = 0; m < 4; ++m) _Pragma("unroll") for (int n = 0; n < 2; ++n) _Pragma("unroll") for (int k = 0; k < 2; ++k) \
;         acc[ai][bj][m][n] = __builtin_amdgcn_mfma_f32_16x16x32_bf16(Bt[n][k], At[m][k], acc[ai][bj][m][n], 0, 0, 0); __builtin_amdgcn_s_setprio(0); } while (0)
; #define PG8_WAIT_V(n) asm volatile("s_waitcnt vmcnt(" #n ")" ::: "memory")
; #define PG8_WAIT_L(n) asm volatile("s_waitcnt lgkmcnt(" #n ")" ::: "memory")
; #define PG8_BAR __builtin_amdgcn_s_barrier()
; #define PG8_SCHED __builtin_amdgcn_sched_barrier(0)
; template <class Epi, class Sched, bool ALIGN_EPI = false, bool SP2 = false>
; __device__ __forceinline__ void gemm_phase(PG8_LAS unsigned char* lds, const Gemm g, const Sched& S, const Epi& E) {
;     ...
;             const char* a1 = cA + (size_t)(t + 1) * kstep;
;             const char* a2 = last ? nA : cA + (size_t)(t + 2) * kstep; const char* b2 = last ? nB : cB + (size_t)(t + 2) * kstep;
;             const char* a3 = a2 + kstep; const char* b3 = b2 + kstep;
;             if constexpr (SP2) {
;             PG8_LDB(B0, 0, 0); PG8_LDB(B1, 0, 1); PG8_SCHED; PG8_LDA(At, 0, 0); PG8_STAGE(PG8_SA(1, 1), a1 + hstep, voffA);
;             PG8_WAIT_V(8); PG8_WAIT_L(0); PG8_BAR; PG8_MMA(0, 0, At, B0); PG8_MMA(0, 1, At, B1); PG8_BAR; PG8_SCHED;
;             PG8_LDA(At, 0, 1); PG8_STAGE(PG8_SB(0, 0), b2, voffB); PG8_STAGE(PG8_SB(0, 1), b2 + hstep, voffB); PG8_STAGE(PG8_SA(0, 0), a2, voffA);
;             PG8_WAIT_V(8); PG8_WAIT_L(0); PG8_BAR; PG8_MMA(1, 0, At, B0); PG8_MMA(1, 1, At, B1); PG8_BAR; PG8_SCHED;
.LBB0_1051:
	ds_read_b128 v[128:131], v205
	ds_read_b128 v[132:135], v205 offset:1024
	ds_read_b128 v[154:157], v205 offset:2048
	ds_read_b128 v[158:161], v205 offset:3072
	ds_read_b128 v[162:165], v206
	ds_read_b128 v[166:169], v206 offset:1024
	ds_read_b128 v[170:173], v206 offset:2048
	ds_read_b128 v[174:177], v206 offset:3072
	s_add_u32 s54, s52, 0xfff80080
	s_addc_u32 s55, s53, -1
	s_cmp_eq_u32 s77, 28
	s_cselect_b32 s57, s43, s55
	s_cselect_b32 s56, s49, s54
	s_cselect_b32 s55, s37, s76
	s_cselect_b32 s54, s51, s75
	s_add_i32 m0, s61, 0xc000
	ds_read_b128 v[178:181], v207
	ds_read_b128 v[182:185], v207 offset:1024
	ds_read_b128 v[186:189], v207 offset:2048
	ds_read_b128 v[190:193], v207 offset:3072
	ds_read_b128 v[194:197], v207 offset:4096
	ds_read_b128 v[198:201], v207 offset:5120
	ds_read_b128 v[210:213], v207 offset:6144
	ds_read_b128 v[214:217], v207 offset:7168
	global_load_lds_dwordx4 v144, s[52:53]
	s_add_i32 m0, s61, 0xe000
	s_nop 0
	global_load_lds_dwordx4 v148, s[52:53]
	s_waitcnt vmcnt(8)
	s_waitcnt lgkmcnt(0)
	s_setprio 1
	s_barrier
	v_mfma_f32_16x16x32_bf16 v[124:127], v[128:131], v[178:181], v[124:127]
	v_mfma_f32_16x16x32_bf16 v[120:123], v[154:157], v[178:181], v[120:123]
	v_mfma_f32_16x16x32_bf16 v[116:119], v[128:131], v[186:189], v[116:119]
	v_mfma_f32_16x16x32_bf16 v[112:115], v[154:157], v[186:189], v[112:115]
	v_mfma_f32_16x16x32_bf16 v[108:111], v[128:131], v[194:197], v[108:111]
	v_mfma_f32_16x16x32_bf16 v[104:107], v[154:157], v[194:197], v[104:107]
	v_mfma_f32_16x16x32_bf16 v[100:103], v[128:131], v[210:213], v[100:103]
	v_mfma_f32_16x16x32_bf16 v[96:99], v[154:157], v[210:213], v[96:99]
	v_mfma_f32_16x16x32_bf16 v[124:127], v[132:135], v[182:185], v[124:127]
	v_mfma_f32_16x16x32_bf16 v[120:123], v[158:161], v[182:185], v[120:123]
	v_mfma_f32_16x16x32_bf16 v[116:119], v[132:135], v[190:193], v[116:119]
	v_mfma_f32_16x16x32_bf16 v[112:115], v[158:161], v[190:193], v[112:115]
	v_mfma_f32_16x16x32_bf16 v[108:111], v[132:135], v[198:201], v[108:111]
	v_mfma_f32_16x16x32_bf16 v[104:107], v[158:161], v[198:201], v[104:107]
	v_mfma_f32_16x16x32_bf16 v[100:103], v[132:135], v[214:217], v[100:103]
	v_mfma_f32_16x16x32_bf16 v[96:99], v[158:161], v[214:217], v[96:99]
	s_setprio 0
	s_setprio 1
	v_mfma_f32_16x16x32_bf16 v[60:63], v[162:165], v[178:181], v[60:63]
	v_mfma_f32_16x16x32_bf16 v[56:59], v[170:173], v[178:181], v[56:59]
	v_mfma_f32_16x16x32_bf16 v[52:55], v[162:165], v[186:189], v[52:55]
	v_mfma_f32_16x16x32_bf16 v[48:51], v[170:173], v[186:189], v[48:51]
	v_mfma_f32_16x16x32_bf16 v[44:47], v[162:165], v[194:197], v[44:47]
	v_mfma_f32_16x16x32_bf16 v[40:43], v[170:173], v[194:197], v[40:43]
	v_mfma_f32_16x16x32_bf16 v[36:39], v[162:165], v[210:213], v[36:39]
	v_mfma_f32_16x16x32_bf16 v[32:35], v[170:173], v[210:213], v[32:35]
	v_mfma_f32_16x16x32_bf16 v[60:63], v[166:169], v[182:185], v[60:63]
	v_mfma_f32_16x16x32_bf16 v[56:59], v[174:177], v[182:185], v[56:59]
	v_mfma_f32_16x16x32_bf16 v[52:55], v[166:169], v[190:193], v[52:55]
	v_mfma_f32_16x16x32_bf16 v[48:51], v[174:177], v[190:193], v[48:51]
	v_mfma_f32_16x16x32_bf16 v[44:47], v[166:169], v[198:201], v[44:47]
	v_mfma_f32_16x16x32_bf16 v[40:43], v[174:177], v[198:201], v[40:43]
	s_setprio 2
	s_barrier
	v_mfma_f32_16x16x32_bf16 v[36:39], v[166:169], v[214:217], v[36:39]
	v_mfma_f32_16x16x32_bf16 v[32:35], v[174:177], v[214:217], v[32:35]
	s_setprio 0
	s_add_i32 s78, s33, s60
	v_lshl_add_u64 v[218:219], s[54:55], 0, v[138:139]
	s_mov_b32 m0, s78
	ds_read_b128 v[178:181], v207 offset:16384
	ds_read_b128 v[182:185], v207 offset:17408
	ds_read_b128 v[186:189], v207 offset:18432
	ds_read_b128 v[190:193], v207 offset:19456
	ds_read_b128 v[194:197], v207 offset:20480
	ds_read_b128 v[198:201], v207 offset:21504
	ds_read_b128 v[210:213], v207 offset:22528
	ds_read_b128 v[214:217], v207 offset:23552
	global_load_lds_dwordx4 v[218:219], off
	s_add_i32 m0, s78, 0x2000
	s_add_u32 s78, s54, 0x80000
	v_lshl_add_u64 v[220:221], s[54:55], 0, v[142:143]
	s_addc_u32 s79, s55, 0
	s_add_i32 s80, s74, s60
	global_load_lds_dwordx4 v[220:221], off
	s_mov_b32 m0, s80
	v_lshl_add_u64 v[224:225], s[56:57], 0, v[140:141]
	global_load_lds_dwordx4 v138, s[78:79]
	s_add_i32 m0, s80, 0x2000
	s_nop 0
	global_load_lds_dwordx4 v142, s[78:79]
	s_mov_b32 m0, s61
	v_lshl_add_u64 v[222:223], s[56:57], 0, v[136:137]
	global_load_lds_dwordx4 v[222:223], off
	s_mov_b32 m0, s62
	s_nop 0
	global_load_lds_dwordx4 v[224:225], off
	s_waitcnt vmcnt(8)
	s_waitcnt lgkmcnt(0)
	s_setprio 1
	s_barrier
	v_mfma_f32_16x16x32_bf16 v[92:95], v[128:131], v[178:181], v[92:95]
	v_mfma_f32_16x16x32_bf16 v[88:91], v[154:157], v[178:181], v[88:91]
	v_mfma_f32_16x16x32_bf16 v[84:87], v[128:131], v[186:189], v[84:87]
	v_mfma_f32_16x16x32_bf16 v[80:83], v[154:157], v[186:189], v[80:83]
	v_mfma_f32_16x16x32_bf16 v[76:79], v[128:131], v[194:197], v[76:79]
	v_mfma_f32_16x16x32_bf16 v[72:75], v[154:157], v[194:197], v[72:75]
	v_mfma_f32_16x16x32_bf16 v[68:71], v[128:131], v[210:213], v[68:71]
	v_mfma_f32_16x16x32_bf16 v[64:67], v[154:157], v[210:213], v[64:67]
	v_mfma_f32_16x16x32_bf16 v[92:95], v[132:135], v[182:185], v[92:95]
	v_mfma_f32_16x16x32_bf16 v[88:91], v[158:161], v[182:185], v[88:91]
	v_mfma_f32_16x16x32_bf16 v[84:87], v[132:135], v[190:193], v[84:87]
	v_mfma_f32_16x16x32_bf16 v[80:83], v[158:161], v[190:193], v[80:83]
	v_mfma_f32_16x16x32_bf16 v[76:79], v[132:135], v[198:201], v[76:79]
	v_mfma_f32_16x16x32_bf16 v[72:75], v[158:161], v[198:201], v[72:75]
	v_mfma_f32_16x16x32_bf16 v[68:71], v[132:135], v[214:217], v[68:71]
	v_mfma_f32_16x16x32_bf16 v[64:67], v[158:161], v[214:217], v[64:67]
	s_setprio 0
	s_setprio 1
	v_mfma_f32_16x16x32_bf16 v[28:31], v[162:165], v[178:181], v[28:31]
	v_mfma_f32_16x16x32_bf16 v[24:27], v[170:173], v[178:181], v[24:27]
	v_mfma_f32_16x16x32_bf16 v[20:23], v[162:165], v[186:189], v[20:23]
	v_mfma_f32_16x16x32_bf16 v[16:19], v[170:173], v[186:189], v[16:19]
	v_mfma_f32_16x16x32_bf16 v[12:15], v[162:165], v[194:197], v[12:15]
	v_mfma_f32_16x16x32_bf16 v[8:11], v[170:173], v[194:197], v[8:11]
	v_mfma_f32_16x16x32_bf16 v[4:7], v[162:165], v[210:213], v[4:7]
	v_mfma_f32_16x16x32_bf16 v[0:3], v[170:173], v[210:213], v[0:3]
	v_mfma_f32_16x16x32_bf16 v[28:31], v[166:169], v[182:185], v[28:31]
	v_mfma_f32_16x16x32_bf16 v[24:27], v[174:177], v[182:185], v[24:27]
	v_mfma_f32_16x16x32_bf16 v[20:23], v[166:169], v[190:193], v[20:23]
	v_mfma_f32_16x16x32_bf16 v[16:19], v[174:177], v[190:193], v[16:19]
	v_mfma_f32_16x16x32_bf16 v[12:15], v[166:169], v[198:201], v[12:15]
	v_mfma_f32_16x16x32_bf16 v[8:11], v[174:177], v[198:201], v[8:11]
	s_setprio 2
	s_barrier
; #define PG8_STAGE(bufoff, gbase, voff) do { _Pragma("unroll") for (int _i = 0; _i < 2; ++_i) \
;         __builtin_amdgcn_global_load_lds((const unsigned*)((const char*)(gbase) + (voff)[_i]), (PG8_LAS unsigned*)(lds + (bufoff) + ldsw + _i * 8192), 16, 0, 0); } while (0)
; #define PG8_LDA(dst, b, h) do { _Pragma("unroll") for (int m = 0; m < 4; ++m) _Pragma("unroll") for (int k = 0; k < 2; ++k) dst[m][k] = *(const PG8_LAS bf16x8*)(lds + PG8_SA(b, h) + aoff + m * 2048 + k * 1024); } while (0)
; #define PG8_LDB(dst, b, h) do { _Pragma("unroll") for (int n = 0; n < 2; ++n) _Pragma("unroll") for (int k = 0; k < 2; ++k) dst[n][k] = *(const PG8_LAS bf16x8*)(lds + PG8_SB(b, h) + boff + n * 2048 + k * 1024); } while (0)
; #define PG8_MMA(ai, bj, At, Bt) do { __builtin_amdgcn_s_setprio(1); _Pragma("unroll") for (int m = 0; m < 4; ++m) _Pragma("unroll") for (int n = 0; n < 2; ++n) _Pragma("unroll") for (int k = 0; k < 2; ++k) \
;         acc[ai][bj][m][n] = __builtin_amdgcn_mfma_f32_16x16x32_bf16(Bt[n][k], At[m][k], acc[ai][bj][m][n], 0, 0, 0); __builtin_amdgcn_s_setprio(0); } while (0)
; #define PG8_WAIT_V(n) asm volatile("s_waitcnt vmcnt(" #n ")" ::: "memory")
; #define PG8_WAIT_L(n) asm volatile("s_waitcnt lgkmcnt(" #n ")" ::: "memory")
; #define PG8_BAR __builtin_amdgcn_s_barrier()
; #define PG8_SCHED __builtin_amdgcn_sched_barrier(0)
; template <class Epi, class Sched, bool ALIGN_EPI = false, bool SP2 = false>
; __device__ __forceinline__ void gemm_phase(PG8_LAS unsigned char* lds, const Gemm g, const Sched& S, const Epi& E) {
;     ...
;             PG8_WAIT_V(8); PG8_WAIT_L(0); PG8_BAR; PG8_MMA(1, 0, At, B0); PG8_MMA(1, 1, At, B1); PG8_BAR; PG8_SCHED;
;             PG8_LDB(B0, 1, 0); PG8_LDB(B1, 1, 1); PG8_SCHED; PG8_LDA(At, 1, 0); PG8_STAGE(PG8_SA(0, 1), a2 + hstep, voffA);
;             PG8_WAIT_V(8); PG8_WAIT_L(0); PG8_BAR; PG8_MMA(0, 0, At, B0); PG8_MMA(0, 1, At, B1); PG8_BAR; PG8_SCHED;
	v_mfma_f32_16x16x32_bf16 v[4:7], v[166:169], v[214:217], v[4:7]
	v_mfma_f32_16x16x32_bf16 v[0:3], v[174:177], v[214:217], v[0:3]
	s_setprio 0
	s_add_i32 s78, 0, 0x18000
	s_add_i32 s79, 0, 0x1c000
	v_add_u32_e32 v158, s78, v203
	v_add_u32_e32 v174, s79, v203
	ds_read_b128 v[128:131], v158
	ds_read_b128 v[132:135], v158 offset:1024
	ds_read_b128 v[154:157], v158 offset:2048
	ds_read_b128 v[158:161], v158 offset:3072
	ds_read_b128 v[162:165], v174
	ds_read_b128 v[166:169], v174 offset:1024
	ds_read_b128 v[170:173], v174 offset:2048
	ds_read_b128 v[174:177], v174 offset:3072
	s_add_u32 s56, s56, 0x80000
	s_addc_u32 s57, s57, 0
	s_mov_b32 m0, s63
	ds_read_b128 v[178:181], v207 offset:32768
	ds_read_b128 v[182:185], v207 offset:33792
	ds_read_b128 v[186:189], v207 offset:34816
	ds_read_b128 v[190:193], v207 offset:35840
	ds_read_b128 v[194:197], v207 offset:36864
	ds_read_b128 v[198:201], v207 offset:37888
	ds_read_b128 v[210:213], v207 offset:38912
	ds_read_b128 v[214:217], v207 offset:39936
	global_load_lds_dwordx4 v136, s[56:57]
	s_mov_b32 m0, s64
	s_nop 0
	global_load_lds_dwordx4 v140, s[56:57]
	s_waitcnt vmcnt(8)
	s_waitcnt lgkmcnt(0)
	s_setprio 1
	s_barrier
	v_mfma_f32_16x16x32_bf16 v[124:127], v[128:131], v[178:181], v[124:127]
	v_mfma_f32_16x16x32_bf16 v[120:123], v[154:157], v[178:181], v[120:123]
	v_mfma_f32_16x16x32_bf16 v[116:119], v[128:131], v[186:189], v[116:119]
	v_mfma_f32_16x16x32_bf16 v[112:115], v[154:157], v[186:189], v[112:115]
	v_mfma_f32_16x16x32_bf16 v[108:111], v[128:131], v[194:197], v[108:111]
	v_mfma_f32_16x16x32_bf16 v[104:107], v[154:157], v[194:197], v[104:107]
	v_mfma_f32_16x16x32_bf16 v[100:103], v[128:131], v[210:213], v[100:103]
	v_mfma_f32_16x16x32_bf16 v[96:99], v[154:157], v[210:213], v[96:99]
	v_mfma_f32_16x16x32_bf16 v[124:127], v[132:135], v[182:185], v[124:127]
	v_mfma_f32_16x16x32_bf16 v[120:123], v[158:161], v[182:185], v[120:123]
	v_mfma_f32_16x16x32_bf16 v[116:119], v[132:135], v[190:193], v[116:119]
	v_mfma_f32_16x16x32_bf16 v[112:115], v[158:161], v[190:193], v[112:115]
	v_mfma_f32_16x16x32_bf16 v[108:111], v[132:135], v[198:201], v[108:111]
	v_mfma_f32_16x16x32_bf16 v[104:107], v[158:161], v[198:201], v[104:107]
	v_mfma_f32_16x16x32_bf16 v[100:103], v[132:135], v[214:217], v[100:103]
	v_mfma_f32_16x16x32_bf16 v[96:99], v[158:161], v[214:217], v[96:99]
	s_setprio 0
	s_setprio 1
	v_mfma_f32_16x16x32_bf16 v[60:63], v[162:165], v[178:181], v[60:63]
	v_mfma_f32_16x16x32_bf16 v[56:59], v[170:173], v[178:181], v[56:59]
	v_mfma_f32_16x16x32_bf16 v[52:55], v[162:165], v[186:189], v[52:55]
	v_mfma_f32_16x16x32_bf16 v[48:51], v[170:173], v[186:189], v[48:51]
	v_mfma_f32_16x16x32_bf16 v[44:47], v[162:165], v[194:197], v[44:47]
	v_mfma_f32_16x16x32_bf16 v[40:43], v[170:173], v[194:197], v[40:43]
	v_mfma_f32_16x16x32_bf16 v[36:39], v[162:165], v[210:213], v[36:39]
	v_mfma_f32_16x16x32_bf16 v[32:35], v[170:173], v[210:213], v[32:35]
	v_mfma_f32_16x16x32_bf16 v[60:63], v[166:169], v[182:185], v[60:63]
	v_mfma_f32_16x16x32_bf16 v[56:59], v[174:177], v[182:185], v[56:59]
	v_mfma_f32_16x16x32_bf16 v[52:55], v[166:169], v[190:193], v[52:55]
	v_mfma_f32_16x16x32_bf16 v[48:51], v[174:177], v[190:193], v[48:51]
	v_mfma_f32_16x16x32_bf16 v[44:47], v[166:169], v[198:201], v[44:47]
	v_mfma_f32_16x16x32_bf16 v[40:43], v[174:177], v[198:201], v[40:43]
	s_setprio 2
	s_barrier
; #define PG8_STAGE(bufoff, gbase, voff) do { _Pragma("unroll") for (int _i = 0; _i < 2; ++_i) \
;         __builtin_amdgcn_global_load_lds((const unsigned*)((const char*)(gbase) + (voff)[_i]), (PG8_LAS unsigned*)(lds + (bufoff) + ldsw + _i * 8192), 16, 0, 0); } while (0)
; #define PG8_LDA(dst, b, h) do { _Pragma("unroll") for (int m = 0; m < 4; ++m) _Pragma("unroll") for (int k = 0; k < 2; ++k) dst[m][k] = *(const PG8_LAS bf16x8*)(lds + PG8_SA(b, h) + aoff + m * 2048 + k * 1024); } while (0)
; #define PG8_MMA(ai, bj, At, Bt) do { __builtin_amdgcn_s_setprio(1); _Pragma("unroll") for (int m = 0; m < 4; ++m) _Pragma("unroll") for (int n = 0; n < 2; ++n) _Pragma("unroll") for (int k = 0; k < 2; ++k) \
;         acc[ai][bj][m][n] = __builtin_amdgcn_mfma_f32_16x16x32_bf16(Bt[n][k], At[m][k], acc[ai][bj][m][n], 0, 0, 0); __builtin_amdgcn_s_setprio(0); } while (0)
; #define PG8_WAIT_V(n) asm volatile("s_waitcnt vmcnt(" #n ")" ::: "memory")
; #define PG8_WAIT_L(n) asm volatile("s_waitcnt lgkmcnt(" #n ")" ::: "memory")
; #define PG8_BAR __builtin_amdgcn_s_barrier()
; #define PG8_SCHED __builtin_amdgcn_sched_barrier(0)
; template <class Epi, class Sched, bool ALIGN_EPI = false, bool SP2 = false>
; __device__ __forceinline__ void gemm_phase(PG8_LAS unsigned char* lds, const Gemm g, const Sched& S, const Epi& E) {
;     ...
;             PG8_LDA(At, 1, 1); PG8_STAGE(PG8_SB(1, 0), b3, voffB); PG8_STAGE(PG8_SB(1, 1), b3 + hstep, voffB); PG8_STAGE(PG8_SA(1, 0), a3, voffA);
;             PG8_WAIT_V(8); PG8_WAIT_L(0); PG8_BAR; PG8_MMA(1, 0, At, B0); PG8_MMA(1, 1, At, B1); PG8_BAR; PG8_SCHED;
	v_mfma_f32_16x16x32_bf16 v[36:39], v[166:169], v[214:217], v[36:39]
	v_mfma_f32_16x16x32_bf16 v[32:35], v[174:177], v[214:217], v[32:35]
	s_setprio 0
	s_add_i32 s56, s78, s60
	v_lshl_add_u64 v[218:219], v[218:219], 0, s[12:13]
	s_mov_b32 m0, s56
	ds_read_b128 v[178:181], v207 offset:49152
	ds_read_b128 v[182:185], v207 offset:50176
	ds_read_b128 v[186:189], v207 offset:51200
	ds_read_b128 v[190:193], v207 offset:52224
	ds_read_b128 v[194:197], v207 offset:53248
	ds_read_b128 v[198:201], v207 offset:54272
	ds_read_b128 v[210:213], v207 offset:55296
	ds_read_b128 v[214:217], v207 offset:56320
	global_load_lds_dwordx4 v[218:219], off
	s_add_i32 m0, s56, 0x2000
	s_add_u32 s54, s54, 0x80080
	v_lshl_add_u64 v[218:219], v[220:221], 0, s[12:13]
	s_addc_u32 s55, s55, 0
	s_add_i32 s56, s79, s60
	global_load_lds_dwordx4 v[218:219], off
	s_mov_b32 m0, s56
	s_nop 0
	global_load_lds_dwordx4 v138, s[54:55]
	s_add_i32 m0, s56, 0x2000
	s_nop 0
	global_load_lds_dwordx4 v142, s[54:55]
	s_mov_b32 m0, s70
	v_lshl_add_u64 v[218:219], v[222:223], 0, s[12:13]
	global_load_lds_dwordx4 v[218:219], off
	s_mov_b32 m0, s71
	v_lshl_add_u64 v[218:219], v[224:225], 0, s[12:13]
	global_load_lds_dwordx4 v[218:219], off
	s_waitcnt vmcnt(8)
	s_waitcnt lgkmcnt(0)
	s_setprio 1
	s_barrier
	v_mfma_f32_16x16x32_bf16 v[92:95], v[128:131], v[178:181], v[92:95]
	v_mfma_f32_16x16x32_bf16 v[88:91], v[154:157], v[178:181], v[88:91]
	v_mfma_f32_16x16x32_bf16 v[84:87], v[128:131], v[186:189], v[84:87]
	v_mfma_f32_16x16x32_bf16 v[80:83], v[154:157], v[186:189], v[80:83]
	v_mfma_f32_16x16x32_bf16 v[76:79], v[128:131], v[194:197], v[76:79]
	v_mfma_f32_16x16x32_bf16 v[72:75], v[154:157], v[194:197], v[72:75]
	v_mfma_f32_16x16x32_bf16 v[68:71], v[128:131], v[210:213], v[68:71]
	v_mfma_f32_16x16x32_bf16 v[64:67], v[154:157], v[210:213], v[64:67]
	v_mfma_f32_16x16x32_bf16 v[92:95], v[132:135], v[182:185], v[92:95]
	v_mfma_f32_16x16x32_bf16 v[88:91], v[158:161], v[182:185], v[88:91]
	v_mfma_f32_16x16x32_bf16 v[84:87], v[132:135], v[190:193], v[84:87]
	v_mfma_f32_16x16x32_bf16 v[80:83], v[158:161], v[190:193], v[80:83]
	v_mfma_f32_16x16x32_bf16 v[76:79], v[132:135], v[198:201], v[76:79]
	v_mfma_f32_16x16x32_bf16 v[72:75], v[158:161], v[198:201], v[72:75]
	v_mfma_f32_16x16x32_bf16 v[68:71], v[132:135], v[214:217], v[68:71]
	v_mfma_f32_16x16x32_bf16 v[64:67], v[158:161], v[214:217], v[64:67]
	s_setprio 0
	s_setprio 1
	v_mfma_f32_16x16x32_bf16 v[28:31], v[162:165], v[178:181], v[28:31]
	v_mfma_f32_16x16x32_bf16 v[24:27], v[170:173], v[178:181], v[24:27]
	v_mfma_f32_16x16x32_bf16 v[20:23], v[162:165], v[186:189], v[20:23]
	v_mfma_f32_16x16x32_bf16 v[16:19], v[170:173], v[186:189], v[16:19]
	v_mfma_f32_16x16x32_bf16 v[12:15], v[162:165], v[194:197], v[12:15]
	v_mfma_f32_16x16x32_bf16 v[8:11], v[170:173], v[194:197], v[8:11]
	v_mfma_f32_16x16x32_bf16 v[4:7], v[162:165], v[210:213], v[4:7]
	v_mfma_f32_16x16x32_bf16 v[0:3], v[170:173], v[210:213], v[0:3]
	v_mfma_f32_16x16x32_bf16 v[28:31], v[166:169], v[182:185], v[28:31]
	v_mfma_f32_16x16x32_bf16 v[24:27], v[174:177], v[182:185], v[24:27]
	v_mfma_f32_16x16x32_bf16 v[20:23], v[166:169], v[190:193], v[20:23]
	v_mfma_f32_16x16x32_bf16 v[16:19], v[174:177], v[190:193], v[16:19]
	v_mfma_f32_16x16x32_bf16 v[12:15], v[166:169], v[198:201], v[12:15]
	v_mfma_f32_16x16x32_bf16 v[8:11], v[174:177], v[198:201], v[8:11]
	s_setprio 2
	s_barrier
	v_mfma_f32_16x16x32_bf16 v[4:7], v[166:169], v[214:217], v[4:7]
	v_mfma_f32_16x16x32_bf16 v[0:3], v[174:177], v[214:217], v[0:3]
	s_setprio 0
	s_add_i32 s77, s77, 2
	s_add_u32 s52, s52, 0x100
	s_addc_u32 s53, s53, 0
	s_add_u32 s75, s75, 0x100
	s_addc_u32 s76, s76, 0
	s_cmp_gt_u32 s77, 29
	s_cbranch_scc0 .LBB0_1051
	s_and_b64 vcc, exec, s[14:15]
	s_cbranch_vccz .LBB0_1054
	s_barrier

; #define PG8_STAGE(bufoff, gbase, voff) do { _Pragma("unroll") for (int _i = 0; _i < 2; ++_i) \
;         __builtin_amdgcn_global_load_lds((const unsigned*)((const char*)(gbase) + (voff)[_i]), (PG8_LAS unsigned*)(lds + (bufoff) + ldsw + _i * 8192), 16, 0, 0); } while (0)
; #define PG8_LDA(dst, b, h) do { _Pragma("unroll") for (int m = 0; m < 4; ++m) _Pragma("unroll") for (int k = 0; k < 2; ++k) dst[m][k] = *(const PG8_LAS bf16x8*)(lds + PG8_SA(b, h) + aoff + m * 2048 + k * 1024); } while (0)
; #define PG8_LDB(dst, b, h) do { _Pragma("unroll") for (int n = 0; n < 2; ++n) _Pragma("unroll") for (int k = 0; k < 2; ++k) dst[n][k] = *(const PG8_LAS bf16x8*)(lds + PG8_SB(b, h) + boff + n * 2048 + k * 1024); } while (0)
; #define PG8_MMA(ai, bj, At, Bt) do { __builtin_amdgcn_s_setprio(1); _Pragma("unroll") for (int m = 0; m < 4; ++m) _Pragma("unroll") for (int n = 0; n < 2; ++n) _Pragma("unroll") for (int k = 0; k < 2; ++k) \
;         acc[ai][bj][m][n] = __builtin_amdgcn_mfma_f32_16x16x32_bf16(Bt[n][k], At[m][k], acc[ai][bj][m][n], 0, 0, 0); __builtin_amdgcn_s_setprio(0); } while (0)
; #define PG8_WAIT_V(n) asm volatile("s_waitcnt vmcnt(" #n ")" ::: "memory")
; #define PG8_WAIT_L(n) asm volatile("s_waitcnt lgkmcnt(" #n ")" ::: "memory")
; #define PG8_BAR __builtin_amdgcn_s_barrier()
; #define PG8_SCHED __builtin_amdgcn_sched_barrier(0)
; template <class Epi, class Sched, bool ALIGN_EPI = false, bool SP2 = false>
; __device__ __forceinline__ void gemm_phase(PG8_LAS unsigned char* lds, const Gemm g, const Sched& S, const Epi& E) {
;     ...
;             const bool last = (t == nt - 2);
;             const char* a1 = cA + (size_t)(t + 1) * kstep;
;             const char* a2 = last ? nA : cA + (size_t)(t + 2) * kstep; const char* b2 = last ? nB : cB + (size_t)(t + 2) * kstep;
;     ...
;             PG8_LDB(B0, 0, 0); PG8_LDB(B1, 0, 1); PG8_SCHED; PG8_LDA(At, 0, 0); PG8_STAGE(PG8_SA(1, 1), a1 + hstep, voffA);
;             PG8_WAIT_V(8); PG8_WAIT_L(0); PG8_BAR; PG8_MMA(0, 0, At, B0); PG8_MMA(0, 1, At, B1); PG8_BAR; PG8_SCHED;
;             PG8_LDA(At, 0, 1); PG8_STAGE(PG8_SB(0, 0), b2, voffB); PG8_STAGE(PG8_SB(0, 1), b2 + hstep, voffB); PG8_STAGE(PG8_SA(0, 0), a2, voffA);
;             PG8_WAIT_V(8); PG8_WAIT_L(0); PG8_BAR; PG8_MMA(1, 0, At, B0); PG8_MMA(1, 1, At, B1); PG8_BAR; PG8_SCHED;
.LBB0_1142:
	ds_read_b128 v[80:83], v171
	ds_read_b128 v[84:87], v171 offset:1024
	ds_read_b128 v[88:91], v171 offset:2048
	ds_read_b128 v[92:95], v171 offset:3072
	ds_read_b128 v[164:167], v172
	ds_read_b128 v[176:179], v172 offset:1024
	ds_read_b128 v[180:183], v172 offset:2048
	ds_read_b128 v[184:187], v172 offset:3072
	s_add_u32 s44, s42, 0xfff80080
	s_addc_u32 s45, s43, -1
	s_cmp_eq_u32 s64, 28
	s_cselect_b32 s47, s15, s45
	s_cselect_b32 s46, s60, s44
	s_cselect_b32 s45, s13, s63
	s_cselect_b32 s44, s61, s62
	s_add_i32 m0, s41, 0xc000
	ds_read_b128 v[188:191], v173
	ds_read_b128 v[192:195], v173 offset:1024
	ds_read_b128 v[196:199], v173 offset:2048
	ds_read_b128 v[200:203], v173 offset:3072
	ds_read_b128 v[204:207], v173 offset:4096
	ds_read_b128 v[208:211], v173 offset:5120
	ds_read_b128 v[212:215], v173 offset:6144
	ds_read_b128 v[216:219], v173 offset:7168
	global_load_lds_dwordx4 v156, s[42:43]
	s_add_i32 m0, s41, 0xe000
	s_nop 0
	global_load_lds_dwordx4 v158, s[42:43]
	s_waitcnt vmcnt(8)
	s_waitcnt lgkmcnt(0)
	s_setprio 1
	s_barrier
	v_mfma_f32_16x16x32_bf16 v[140:143], v[80:83], v[188:191], v[140:143]
	v_mfma_f32_16x16x32_bf16 v[136:139], v[88:91], v[188:191], v[136:139]
	v_mfma_f32_16x16x32_bf16 v[124:127], v[80:83], v[196:199], v[124:127]
	v_mfma_f32_16x16x32_bf16 v[120:123], v[88:91], v[196:199], v[120:123]
	v_mfma_f32_16x16x32_bf16 v[108:111], v[80:83], v[204:207], v[108:111]
	v_mfma_f32_16x16x32_bf16 v[104:107], v[88:91], v[204:207], v[104:107]
	v_mfma_f32_16x16x32_bf16 v[76:79], v[80:83], v[212:215], v[76:79]
	v_mfma_f32_16x16x32_bf16 v[72:75], v[88:91], v[212:215], v[72:75]
	v_mfma_f32_16x16x32_bf16 v[140:143], v[84:87], v[192:195], v[140:143]
	v_mfma_f32_16x16x32_bf16 v[136:139], v[92:95], v[192:195], v[136:139]
	v_mfma_f32_16x16x32_bf16 v[124:127], v[84:87], v[200:203], v[124:127]
	v_mfma_f32_16x16x32_bf16 v[120:123], v[92:95], v[200:203], v[120:123]
	v_mfma_f32_16x16x32_bf16 v[108:111], v[84:87], v[208:211], v[108:111]
	v_mfma_f32_16x16x32_bf16 v[104:107], v[92:95], v[208:211], v[104:107]
	v_mfma_f32_16x16x32_bf16 v[76:79], v[84:87], v[216:219], v[76:79]
	v_mfma_f32_16x16x32_bf16 v[72:75], v[92:95], v[216:219], v[72:75]
	s_setprio 0
	s_setprio 1
	v_mfma_f32_16x16x32_bf16 v[132:135], v[164:167], v[188:191], v[132:135]
	v_mfma_f32_16x16x32_bf16 v[128:131], v[180:183], v[188:191], v[128:131]
	v_mfma_f32_16x16x32_bf16 v[116:119], v[164:167], v[196:199], v[116:119]
	v_mfma_f32_16x16x32_bf16 v[112:115], v[180:183], v[196:199], v[112:115]
	v_mfma_f32_16x16x32_bf16 v[100:103], v[164:167], v[204:207], v[100:103]
	v_mfma_f32_16x16x32_bf16 v[96:99], v[180:183], v[204:207], v[96:99]
	v_mfma_f32_16x16x32_bf16 v[68:71], v[164:167], v[212:215], v[68:71]
	v_mfma_f32_16x16x32_bf16 v[64:67], v[180:183], v[212:215], v[64:67]
	v_mfma_f32_16x16x32_bf16 v[132:135], v[176:179], v[192:195], v[132:135]
	v_mfma_f32_16x16x32_bf16 v[128:131], v[184:187], v[192:195], v[128:131]
	v_mfma_f32_16x16x32_bf16 v[116:119], v[176:179], v[200:203], v[116:119]
	v_mfma_f32_16x16x32_bf16 v[112:115], v[184:187], v[200:203], v[112:115]
	v_mfma_f32_16x16x32_bf16 v[100:103], v[176:179], v[208:211], v[100:103]
	v_mfma_f32_16x16x32_bf16 v[96:99], v[184:187], v[208:211], v[96:99]
	s_setprio 2
	s_barrier
	v_mfma_f32_16x16x32_bf16 v[68:71], v[176:179], v[216:219], v[68:71]
	v_mfma_f32_16x16x32_bf16 v[64:67], v[184:187], v[216:219], v[64:67]
	s_setprio 0
	s_add_i32 s65, s56, s33
	v_lshl_add_u64 v[220:221], s[44:45], 0, v[148:149]
	s_mov_b32 m0, s65
	ds_read_b128 v[188:191], v173 offset:16384
	ds_read_b128 v[192:195], v173 offset:17408
	ds_read_b128 v[196:199], v173 offset:18432
	ds_read_b128 v[200:203], v173 offset:19456
	ds_read_b128 v[204:207], v173 offset:20480
	ds_read_b128 v[208:211], v173 offset:21504
	ds_read_b128 v[212:215], v173 offset:22528
	ds_read_b128 v[216:219], v173 offset:23552
	global_load_lds_dwordx4 v[220:221], off
	s_add_i32 m0, s65, 0x2000
	s_add_u32 s66, s44, 0x80000
	v_lshl_add_u64 v[222:223], s[44:45], 0, v[152:153]
	s_addc_u32 s67, s45, 0
	s_add_i32 s65, s57, s33
	global_load_lds_dwordx4 v[222:223], off
	s_mov_b32 m0, s65
	v_lshl_add_u64 v[226:227], s[46:47], 0, v[150:151]
	global_load_lds_dwordx4 v148, s[66:67]
	s_add_i32 m0, s65, 0x2000
	s_nop 0
	global_load_lds_dwordx4 v152, s[66:67]
	s_mov_b32 m0, s41
	v_lshl_add_u64 v[224:225], s[46:47], 0, v[144:145]
	global_load_lds_dwordx4 v[224:225], off
	s_mov_b32 m0, s48
	s_nop 0
	global_load_lds_dwordx4 v[226:227], off
	s_waitcnt vmcnt(8)
	s_waitcnt lgkmcnt(0)
	s_setprio 1
	s_barrier
	v_mfma_f32_16x16x32_bf16 v[60:63], v[80:83], v[188:191], v[60:63]
	v_mfma_f32_16x16x32_bf16 v[56:59], v[88:91], v[188:191], v[56:59]
	v_mfma_f32_16x16x32_bf16 v[44:47], v[80:83], v[196:199], v[44:47]
	v_mfma_f32_16x16x32_bf16 v[40:43], v[88:91], v[196:199], v[40:43]
	v_mfma_f32_16x16x32_bf16 v[28:31], v[80:83], v[204:207], v[28:31]
	v_mfma_f32_16x16x32_bf16 v[24:27], v[88:91], v[204:207], v[24:27]
	v_mfma_f32_16x16x32_bf16 v[12:15], v[80:83], v[212:215], v[12:15]
	v_mfma_f32_16x16x32_bf16 v[8:11], v[88:91], v[212:215], v[8:11]
	v_mfma_f32_16x16x32_bf16 v[60:63], v[84:87], v[192:195], v[60:63]
	v_mfma_f32_16x16x32_bf16 v[56:59], v[92:95], v[192:195], v[56:59]
	v_mfma_f32_16x16x32_bf16 v[44:47], v[84:87], v[200:203], v[44:47]
	v_mfma_f32_16x16x32_bf16 v[40:43], v[92:95], v[200:203], v[40:43]
	v_mfma_f32_16x16x32_bf16 v[28:31], v[84:87], v[208:211], v[28:31]
	v_mfma_f32_16x16x32_bf16 v[24:27], v[92:95], v[208:211], v[24:27]
	v_mfma_f32_16x16x32_bf16 v[12:15], v[84:87], v[216:219], v[12:15]
	v_mfma_f32_16x16x32_bf16 v[8:11], v[92:95], v[216:219], v[8:11]
	s_setprio 0
	s_setprio 1
	v_mfma_f32_16x16x32_bf16 v[52:55], v[164:167], v[188:191], v[52:55]
	v_mfma_f32_16x16x32_bf16 v[48:51], v[180:183], v[188:191], v[48:51]
	v_mfma_f32_16x16x32_bf16 v[36:39], v[164:167], v[196:199], v[36:39]
	v_mfma_f32_16x16x32_bf16 v[32:35], v[180:183], v[196:199], v[32:35]
	v_mfma_f32_16x16x32_bf16 v[20:23], v[164:167], v[204:207], v[20:23]
	v_mfma_f32_16x16x32_bf16 v[16:19], v[180:183], v[204:207], v[16:19]
	v_mfma_f32_16x16x32_bf16 v[4:7], v[164:167], v[212:215], v[4:7]
	v_mfma_f32_16x16x32_bf16 v[0:3], v[180:183], v[212:215], v[0:3]
	v_mfma_f32_16x16x32_bf16 v[52:55], v[176:179], v[192:195], v[52:55]
	v_mfma_f32_16x16x32_bf16 v[48:51], v[184:187], v[192:195], v[48:51]
	v_mfma_f32_16x16x32_bf16 v[36:39], v[176:179], v[200:203], v[36:39]
	v_mfma_f32_16x16x32_bf16 v[32:35], v[184:187], v[200:203], v[32:35]
	v_mfma_f32_16x16x32_bf16 v[20:23], v[176:179], v[208:211], v[20:23]
	v_mfma_f32_16x16x32_bf16 v[16:19], v[184:187], v[208:211], v[16:19]
	s_setprio 2
	s_barrier
; #define PG8_STAGE(bufoff, gbase, voff) do { _Pragma("unroll") for (int _i = 0; _i < 2; ++_i) \
;         __builtin_amdgcn_global_load_lds((const unsigned*)((const char*)(gbase) + (voff)[_i]), (PG8_LAS unsigned*)(lds + (bufoff) + ldsw + _i * 8192), 16, 0, 0); } while (0)
; #define PG8_LDA(dst, b, h) do { _Pragma("unroll") for (int m = 0; m < 4; ++m) _Pragma("unroll") for (int k = 0; k < 2; ++k) dst[m][k] = *(const PG8_LAS bf16x8*)(lds + PG8_SA(b, h) + aoff + m * 2048 + k * 1024); } while (0)
; #define PG8_LDB(dst, b, h) do { _Pragma("unroll") for (int n = 0; n < 2; ++n) _Pragma("unroll") for (int k = 0; k < 2; ++k) dst[n][k] = *(const PG8_LAS bf16x8*)(lds + PG8_SB(b, h) + boff + n * 2048 + k * 1024); } while (0)
; #define PG8_MMA(ai, bj, At, Bt) do { __builtin_amdgcn_s_setprio(1); _Pragma("unroll") for (int m = 0; m < 4; ++m) _Pragma("unroll") for (int n = 0; n < 2; ++n) _Pragma("unroll") for (int k = 0; k < 2; ++k) \
;         acc[ai][bj][m][n] = __builtin_amdgcn_mfma_f32_16x16x32_bf16(Bt[n][k], At[m][k], acc[ai][bj][m][n], 0, 0, 0); __builtin_amdgcn_s_setprio(0); } while (0)
; #define PG8_WAIT_V(n) asm volatile("s_waitcnt vmcnt(" #n ")" ::: "memory")
; #define PG8_WAIT_L(n) asm volatile("s_waitcnt lgkmcnt(" #n ")" ::: "memory")
; #define PG8_BAR __builtin_amdgcn_s_barrier()
; #define PG8_SCHED __builtin_amdgcn_sched_barrier(0)
; template <class Epi, class Sched, bool ALIGN_EPI = false, bool SP2 = false>
; __device__ __forceinline__ void gemm_phase(PG8_LAS unsigned char* lds, const Gemm g, const Sched& S, const Epi& E) {
;     ...
;             PG8_LDB(B0, 1, 0); PG8_LDB(B1, 1, 1); PG8_SCHED; PG8_LDA(At, 1, 0); PG8_STAGE(PG8_SA(0, 1), a2 + hstep, voffA);
;             PG8_WAIT_V(8); PG8_WAIT_L(0); PG8_BAR; PG8_MMA(0, 0, At, B0); PG8_MMA(0, 1, At, B1); PG8_BAR; PG8_SCHED;
	v_mfma_f32_16x16x32_bf16 v[4:7], v[176:179], v[216:219], v[4:7]
	v_mfma_f32_16x16x32_bf16 v[0:3], v[184:187], v[216:219], v[0:3]
	s_setprio 0
	s_add_i32 s65, 0, 0x18000
	s_add_i32 s66, 0, 0x1c000
	v_add_u32_e32 v92, s65, v169
	v_add_u32_e32 v184, s66, v169
	ds_read_b128 v[80:83], v92
	ds_read_b128 v[84:87], v92 offset:1024
	ds_read_b128 v[88:91], v92 offset:2048
	ds_read_b128 v[92:95], v92 offset:3072
	ds_read_b128 v[164:167], v184
	ds_read_b128 v[176:179], v184 offset:1024
	ds_read_b128 v[180:183], v184 offset:2048
	ds_read_b128 v[184:187], v184 offset:3072
	s_add_u32 s46, s46, 0x80000
	s_addc_u32 s47, s47, 0
	s_mov_b32 m0, s49
	ds_read_b128 v[188:191], v173 offset:32768
	ds_read_b128 v[192:195], v173 offset:33792
	ds_read_b128 v[196:199], v173 offset:34816
	ds_read_b128 v[200:203], v173 offset:35840
	ds_read_b128 v[204:207], v173 offset:36864
	ds_read_b128 v[208:211], v173 offset:37888
	ds_read_b128 v[212:215], v173 offset:38912
	ds_read_b128 v[216:219], v173 offset:39936
	global_load_lds_dwordx4 v144, s[46:47]
	s_mov_b32 m0, s50
	s_nop 0
	global_load_lds_dwordx4 v150, s[46:47]
	s_waitcnt vmcnt(8)
	s_waitcnt lgkmcnt(0)
	s_setprio 1
	s_barrier
	v_mfma_f32_16x16x32_bf16 v[140:143], v[80:83], v[188:191], v[140:143]
	v_mfma_f32_16x16x32_bf16 v[136:139], v[88:91], v[188:191], v[136:139]
	v_mfma_f32_16x16x32_bf16 v[124:127], v[80:83], v[196:199], v[124:127]
	v_mfma_f32_16x16x32_bf16 v[120:123], v[88:91], v[196:199], v[120:123]
	v_mfma_f32_16x16x32_bf16 v[108:111], v[80:83], v[204:207], v[108:111]
	v_mfma_f32_16x16x32_bf16 v[104:107], v[88:91], v[204:207], v[104:107]
	v_mfma_f32_16x16x32_bf16 v[76:79], v[80:83], v[212:215], v[76:79]
	v_mfma_f32_16x16x32_bf16 v[72:75], v[88:91], v[212:215], v[72:75]
	v_mfma_f32_16x16x32_bf16 v[140:143], v[84:87], v[192:195], v[140:143]
	v_mfma_f32_16x16x32_bf16 v[136:139], v[92:95], v[192:195], v[136:139]
	v_mfma_f32_16x16x32_bf16 v[124:127], v[84:87], v[200:203], v[124:127]
	v_mfma_f32_16x16x32_bf16 v[120:123], v[92:95], v[200:203], v[120:123]
	v_mfma_f32_16x16x32_bf16 v[108:111], v[84:87], v[208:211], v[108:111]
	v_mfma_f32_16x16x32_bf16 v[104:107], v[92:95], v[208:211], v[104:107]
	v_mfma_f32_16x16x32_bf16 v[76:79], v[84:87], v[216:219], v[76:79]
	v_mfma_f32_16x16x32_bf16 v[72:75], v[92:95], v[216:219], v[72:75]
	s_setprio 0
	s_setprio 1
	v_mfma_f32_16x16x32_bf16 v[132:135], v[164:167], v[188:191], v[132:135]
	v_mfma_f32_16x16x32_bf16 v[128:131], v[180:183], v[188:191], v[128:131]
	v_mfma_f32_16x16x32_bf16 v[116:119], v[164:167], v[196:199], v[116:119]
	v_mfma_f32_16x16x32_bf16 v[112:115], v[180:183], v[196:199], v[112:115]
	v_mfma_f32_16x16x32_bf16 v[100:103], v[164:167], v[204:207], v[100:103]
	v_mfma_f32_16x16x32_bf16 v[96:99], v[180:183], v[204:207], v[96:99]
	v_mfma_f32_16x16x32_bf16 v[68:71], v[164:167], v[212:215], v[68:71]
	v_mfma_f32_16x16x32_bf16 v[64:67], v[180:183], v[212:215], v[64:67]
	v_mfma_f32_16x16x32_bf16 v[132:135], v[176:179], v[192:195], v[132:135]
	v_mfma_f32_16x16x32_bf16 v[128:131], v[184:187], v[192:195], v[128:131]
	v_mfma_f32_16x16x32_bf16 v[116:119], v[176:179], v[200:203], v[116:119]
	v_mfma_f32_16x16x32_bf16 v[112:115], v[184:187], v[200:203], v[112:115]
	v_mfma_f32_16x16x32_bf16 v[100:103], v[176:179], v[208:211], v[100:103]
	v_mfma_f32_16x16x32_bf16 v[96:99], v[184:187], v[208:211], v[96:99]
	s_setprio 2
	s_barrier
; #define PG8_STAGE(bufoff, gbase, voff) do { _Pragma("unroll") for (int _i = 0; _i < 2; ++_i) \
;         __builtin_amdgcn_global_load_lds((const unsigned*)((const char*)(gbase) + (voff)[_i]), (PG8_LAS unsigned*)(lds + (bufoff) + ldsw + _i * 8192), 16, 0, 0); } while (0)
; #define PG8_LDA(dst, b, h) do { _Pragma("unroll") for (int m = 0; m < 4; ++m) _Pragma("unroll") for (int k = 0; k < 2; ++k) dst[m][k] = *(const PG8_LAS bf16x8*)(lds + PG8_SA(b, h) + aoff + m * 2048 + k * 1024); } while (0)
; #define PG8_MMA(ai, bj, At, Bt) do { __builtin_amdgcn_s_setprio(1); _Pragma("unroll") for (int m = 0; m < 4; ++m) _Pragma("unroll") for (int n = 0; n < 2; ++n) _Pragma("unroll") for (int k = 0; k < 2; ++k) \
;         acc[ai][bj][m][n] = __builtin_amdgcn_mfma_f32_16x16x32_bf16(Bt[n][k], At[m][k], acc[ai][bj][m][n], 0, 0, 0); __builtin_amdgcn_s_setprio(0); } while (0)
; #define PG8_WAIT_V(n) asm volatile("s_waitcnt vmcnt(" #n ")" ::: "memory")
; #define PG8_WAIT_L(n) asm volatile("s_waitcnt lgkmcnt(" #n ")" ::: "memory")
; #define PG8_BAR __builtin_amdgcn_s_barrier()
; #define PG8_SCHED __builtin_amdgcn_sched_barrier(0)
; template <class Epi, class Sched, bool ALIGN_EPI = false, bool SP2 = false>
; __device__ __forceinline__ void gemm_phase(PG8_LAS unsigned char* lds, const Gemm g, const Sched& S, const Epi& E) {
;     ...
;             PG8_LDA(At, 1, 1); PG8_STAGE(PG8_SB(1, 0), b3, voffB); PG8_STAGE(PG8_SB(1, 1), b3 + hstep, voffB); PG8_STAGE(PG8_SA(1, 0), a3, voffA);
;             PG8_WAIT_V(8); PG8_WAIT_L(0); PG8_BAR; PG8_MMA(1, 0, At, B0); PG8_MMA(1, 1, At, B1); PG8_BAR; PG8_SCHED;
	v_mfma_f32_16x16x32_bf16 v[68:71], v[176:179], v[216:219], v[68:71]
	v_mfma_f32_16x16x32_bf16 v[64:67], v[184:187], v[216:219], v[64:67]
	s_setprio 0
	s_add_i32 s46, s65, s33
	v_lshl_add_u64 v[220:221], v[220:221], 0, s[8:9]
	s_mov_b32 m0, s46
	ds_read_b128 v[188:191], v173 offset:49152
	ds_read_b128 v[192:195], v173 offset:50176
	ds_read_b128 v[196:199], v173 offset:51200
	ds_read_b128 v[200:203], v173 offset:52224
	ds_read_b128 v[204:207], v173 offset:53248
	ds_read_b128 v[208:211], v173 offset:54272
	ds_read_b128 v[212:215], v173 offset:55296
	ds_read_b128 v[216:219], v173 offset:56320
	global_load_lds_dwordx4 v[220:221], off
	s_add_i32 m0, s46, 0x2000
	s_add_u32 s44, s44, 0x80080
	v_lshl_add_u64 v[220:221], v[222:223], 0, s[8:9]
	s_addc_u32 s45, s45, 0
	s_add_i32 s46, s66, s33
	global_load_lds_dwordx4 v[220:221], off
	s_mov_b32 m0, s46
	s_nop 0
	global_load_lds_dwordx4 v148, s[44:45]
	s_add_i32 m0, s46, 0x2000
	s_nop 0
	global_load_lds_dwordx4 v152, s[44:45]
	s_mov_b32 m0, s52
	v_lshl_add_u64 v[220:221], v[224:225], 0, s[8:9]
	global_load_lds_dwordx4 v[220:221], off
	s_mov_b32 m0, s53
	v_lshl_add_u64 v[220:221], v[226:227], 0, s[8:9]
	global_load_lds_dwordx4 v[220:221], off
	s_waitcnt vmcnt(8)
	s_waitcnt lgkmcnt(0)
	s_setprio 1
	s_barrier
	v_mfma_f32_16x16x32_bf16 v[60:63], v[80:83], v[188:191], v[60:63]
	v_mfma_f32_16x16x32_bf16 v[56:59], v[88:91], v[188:191], v[56:59]
	v_mfma_f32_16x16x32_bf16 v[44:47], v[80:83], v[196:199], v[44:47]
	v_mfma_f32_16x16x32_bf16 v[40:43], v[88:91], v[196:199], v[40:43]
	v_mfma_f32_16x16x32_bf16 v[28:31], v[80:83], v[204:207], v[28:31]
	v_mfma_f32_16x16x32_bf16 v[24:27], v[88:91], v[204:207], v[24:27]
	v_mfma_f32_16x16x32_bf16 v[12:15], v[80:83], v[212:215], v[12:15]
	v_mfma_f32_16x16x32_bf16 v[8:11], v[88:91], v[212:215], v[8:11]
	v_mfma_f32_16x16x32_bf16 v[60:63], v[84:87], v[192:195], v[60:63]
	v_mfma_f32_16x16x32_bf16 v[56:59], v[92:95], v[192:195], v[56:59]
	v_mfma_f32_16x16x32_bf16 v[44:47], v[84:87], v[200:203], v[44:47]
	v_mfma_f32_16x16x32_bf16 v[40:43], v[92:95], v[200:203], v[40:43]
	v_mfma_f32_16x16x32_bf16 v[28:31], v[84:87], v[208:211], v[28:31]
	v_mfma_f32_16x16x32_bf16 v[24:27], v[92:95], v[208:211], v[24:27]
	v_mfma_f32_16x16x32_bf16 v[12:15], v[84:87], v[216:219], v[12:15]
	v_mfma_f32_16x16x32_bf16 v[8:11], v[92:95], v[216:219], v[8:11]
	s_setprio 0
	s_setprio 1
	v_mfma_f32_16x16x32_bf16 v[52:55], v[164:167], v[188:191], v[52:55]
	v_mfma_f32_16x16x32_bf16 v[48:51], v[180:183], v[188:191], v[48:51]
	v_mfma_f32_16x16x32_bf16 v[36:39], v[164:167], v[196:199], v[36:39]
	v_mfma_f32_16x16x32_bf16 v[32:35], v[180:183], v[196:199], v[32:35]
	v_mfma_f32_16x16x32_bf16 v[20:23], v[164:167], v[204:207], v[20:23]
	v_mfma_f32_16x16x32_bf16 v[16:19], v[180:183], v[204:207], v[16:19]
	v_mfma_f32_16x16x32_bf16 v[4:7], v[164:167], v[212:215], v[4:7]
	v_mfma_f32_16x16x32_bf16 v[0:3], v[180:183], v[212:215], v[0:3]
	v_mfma_f32_16x16x32_bf16 v[52:55], v[176:179], v[192:195], v[52:55]
	v_mfma_f32_16x16x32_bf16 v[48:51], v[184:187], v[192:195], v[48:51]
	v_mfma_f32_16x16x32_bf16 v[36:39], v[176:179], v[200:203], v[36:39]
	v_mfma_f32_16x16x32_bf16 v[32:35], v[184:187], v[200:203], v[32:35]
	v_mfma_f32_16x16x32_bf16 v[20:23], v[176:179], v[208:211], v[20:23]
	v_mfma_f32_16x16x32_bf16 v[16:19], v[184:187], v[208:211], v[16:19]
	s_setprio 2
	s_barrier
	v_mfma_f32_16x16x32_bf16 v[4:7], v[176:179], v[216:219], v[4:7]
	v_mfma_f32_16x16x32_bf16 v[0:3], v[184:187], v[216:219], v[0:3]
	s_setprio 0
	s_add_i32 s64, s64, 2
	s_add_u32 s42, s42, 0x100
	s_addc_u32 s43, s43, 0
	s_add_u32 s62, s62, 0x100
	s_addc_u32 s63, s63, 0
	s_cmp_gt_u32 s64, 29
	s_cbranch_scc0 .LBB0_1142
	s_and_b64 vcc, exec, s[10:11]
	s_cbranch_vccz .LBB0_1145
	s_barrier

; #define PG8_STAGE(bufoff, gbase, voff) do { _Pragma("unroll") for (int _i = 0; _i < 2; ++_i) \
;         __builtin_amdgcn_global_load_lds((const unsigned*)((const char*)(gbase) + (voff)[_i]), (PG8_LAS unsigned*)(lds + (bufoff) + ldsw + _i * 8192), 16, 0, 0); } while (0)
; #define PG8_LDA(dst, b, h) do { _Pragma("unroll") for (int m = 0; m < 4; ++m) _Pragma("unroll") for (int k = 0; k < 2; ++k) dst[m][k] = *(const PG8_LAS bf16x8*)(lds + PG8_SA(b, h) + aoff + m * 2048 + k * 1024); } while (0)
; #define PG8_LDB(dst, b, h) do { _Pragma("unroll") for (int n = 0; n < 2; ++n) _Pragma("unroll") for (int k = 0; k < 2; ++k) dst[n][k] = *(const PG8_LAS bf16x8*)(lds + PG8_SB(b, h) + boff + n * 2048 + k * 1024); } while (0)
; #define PG8_MMA(ai, bj, At, Bt) do { __builtin_amdgcn_s_setprio(1); _Pragma("unroll") for (int m = 0; m < 4; ++m) _Pragma("unroll") for (int n = 0; n < 2; ++n) _Pragma("unroll") for (int k = 0; k < 2; ++k) \
;         acc[ai][bj][m][n] = __builtin_amdgcn_mfma_f32_16x16x32_bf16(Bt[n][k], At[m][k], acc[ai][bj][m][n], 0, 0, 0); __builtin_amdgcn_s_setprio(0); } while (0)
; #define PG8_WAIT_V(n) asm volatile("s_waitcnt vmcnt(" #n ")" ::: "memory")
; #define PG8_WAIT_L(n) asm volatile("s_waitcnt lgkmcnt(" #n ")" ::: "memory")
; #define PG8_BAR __builtin_amdgcn_s_barrier()
; #define PG8_SCHED __builtin_amdgcn_sched_barrier(0)
; template <class Epi, class Sched, bool ALIGN_EPI = false, bool SP2 = false>
; __device__ __forceinline__ void gemm_phase(PG8_LAS unsigned char* lds, const Gemm g, const Sched& S, const Epi& E) {
;     ...
;             const bool last = (t == nt - 2);
;             const char* a1 = cA + (size_t)(t + 1) * kstep;
;             const char* a2 = last ? nA : cA + (size_t)(t + 2) * kstep; const char* b2 = last ? nB : cB + (size_t)(t + 2) * kstep;
;     ...
;             PG8_LDB(B0, 0, 0); PG8_LDB(B1, 0, 1); PG8_SCHED; PG8_LDA(At, 0, 0); PG8_STAGE(PG8_SA(1, 1), a1 + hstep, voffA);
;             PG8_WAIT_V(8); PG8_WAIT_L(0); PG8_BAR; PG8_MMA(0, 0, At, B0); PG8_MMA(0, 1, At, B1); PG8_BAR; PG8_SCHED;
;             PG8_LDA(At, 0, 1); PG8_STAGE(PG8_SB(0, 0), b2, voffB); PG8_STAGE(PG8_SB(0, 1), b2 + hstep, voffB); PG8_STAGE(PG8_SA(0, 0), a2, voffA);
;             PG8_WAIT_V(8); PG8_WAIT_L(0); PG8_BAR; PG8_MMA(1, 0, At, B0); PG8_MMA(1, 1, At, B1); PG8_BAR; PG8_SCHED;
.LBB0_1219:
	ds_read_b128 v[128:131], v167
	ds_read_b128 v[132:135], v167 offset:1024
	ds_read_b128 v[154:157], v167 offset:2048
	ds_read_b128 v[158:161], v167 offset:3072
	ds_read_b128 v[170:173], v168
	ds_read_b128 v[174:177], v168 offset:1024
	ds_read_b128 v[178:181], v168 offset:2048
	ds_read_b128 v[182:185], v168 offset:3072
	s_add_u32 s42, s40, 0xffe00080
	s_addc_u32 s43, s41, -1
	s_cmpk_eq_i32 s63, 0x7c
	s_cselect_b32 s45, s15, s43
	s_cselect_b32 s44, s59, s42
	s_cselect_b32 s43, s13, s62
	s_cselect_b32 s42, s60, s61
	s_add_i32 m0, s39, 0xc000
	ds_read_b128 v[186:189], v169
	ds_read_b128 v[190:193], v169 offset:1024
	ds_read_b128 v[194:197], v169 offset:2048
	ds_read_b128 v[198:201], v169 offset:3072
	ds_read_b128 v[202:205], v169 offset:4096
	ds_read_b128 v[206:209], v169 offset:5120
	ds_read_b128 v[210:213], v169 offset:6144
	ds_read_b128 v[214:217], v169 offset:7168
	global_load_lds_dwordx4 v144, s[40:41]
	s_add_i32 m0, s39, 0xe000
	s_nop 0
	global_load_lds_dwordx4 v148, s[40:41]
	s_waitcnt vmcnt(8)
	s_waitcnt lgkmcnt(0)
	s_setprio 1
	s_barrier
	v_mfma_f32_16x16x32_bf16 v[124:127], v[128:131], v[186:189], v[124:127]
	v_mfma_f32_16x16x32_bf16 v[120:123], v[154:157], v[186:189], v[120:123]
	v_mfma_f32_16x16x32_bf16 v[116:119], v[128:131], v[194:197], v[116:119]
	v_mfma_f32_16x16x32_bf16 v[112:115], v[154:157], v[194:197], v[112:115]
	v_mfma_f32_16x16x32_bf16 v[108:111], v[128:131], v[202:205], v[108:111]
	v_mfma_f32_16x16x32_bf16 v[104:107], v[154:157], v[202:205], v[104:107]
	v_mfma_f32_16x16x32_bf16 v[100:103], v[128:131], v[210:213], v[100:103]
	v_mfma_f32_16x16x32_bf16 v[96:99], v[154:157], v[210:213], v[96:99]
	v_mfma_f32_16x16x32_bf16 v[124:127], v[132:135], v[190:193], v[124:127]
	v_mfma_f32_16x16x32_bf16 v[120:123], v[158:161], v[190:193], v[120:123]
	v_mfma_f32_16x16x32_bf16 v[116:119], v[132:135], v[198:201], v[116:119]
	v_mfma_f32_16x16x32_bf16 v[112:115], v[158:161], v[198:201], v[112:115]
	v_mfma_f32_16x16x32_bf16 v[108:111], v[132:135], v[206:209], v[108:111]
	v_mfma_f32_16x16x32_bf16 v[104:107], v[158:161], v[206:209], v[104:107]
	v_mfma_f32_16x16x32_bf16 v[100:103], v[132:135], v[214:217], v[100:103]
	v_mfma_f32_16x16x32_bf16 v[96:99], v[158:161], v[214:217], v[96:99]
	s_setprio 0
	s_setprio 1
	v_mfma_f32_16x16x32_bf16 v[68:71], v[170:173], v[186:189], v[68:71]
	v_mfma_f32_16x16x32_bf16 v[60:63], v[178:181], v[186:189], v[60:63]
	v_mfma_f32_16x16x32_bf16 v[52:55], v[170:173], v[194:197], v[52:55]
	v_mfma_f32_16x16x32_bf16 v[48:51], v[178:181], v[194:197], v[48:51]
	v_mfma_f32_16x16x32_bf16 v[44:47], v[170:173], v[202:205], v[44:47]
	v_mfma_f32_16x16x32_bf16 v[40:43], v[178:181], v[202:205], v[40:43]
	v_mfma_f32_16x16x32_bf16 v[36:39], v[170:173], v[210:213], v[36:39]
	v_mfma_f32_16x16x32_bf16 v[32:35], v[178:181], v[210:213], v[32:35]
	v_mfma_f32_16x16x32_bf16 v[68:71], v[174:177], v[190:193], v[68:71]
	v_mfma_f32_16x16x32_bf16 v[60:63], v[182:185], v[190:193], v[60:63]
	v_mfma_f32_16x16x32_bf16 v[52:55], v[174:177], v[198:201], v[52:55]
	v_mfma_f32_16x16x32_bf16 v[48:51], v[182:185], v[198:201], v[48:51]
	v_mfma_f32_16x16x32_bf16 v[44:47], v[174:177], v[206:209], v[44:47]
	v_mfma_f32_16x16x32_bf16 v[40:43], v[182:185], v[206:209], v[40:43]
	s_setprio 2
	s_barrier
	v_mfma_f32_16x16x32_bf16 v[36:39], v[174:177], v[214:217], v[36:39]
	v_mfma_f32_16x16x32_bf16 v[32:35], v[182:185], v[214:217], v[32:35]
	s_setprio 0
	s_add_i32 s64, s56, s33
	v_lshl_add_u64 v[162:163], s[42:43], 0, v[138:139]
	s_mov_b32 m0, s64
	ds_read_b128 v[186:189], v169 offset:16384
	ds_read_b128 v[190:193], v169 offset:17408
	ds_read_b128 v[194:197], v169 offset:18432
	ds_read_b128 v[198:201], v169 offset:19456
	ds_read_b128 v[202:205], v169 offset:20480
	ds_read_b128 v[206:209], v169 offset:21504
	ds_read_b128 v[210:213], v169 offset:22528
	ds_read_b128 v[214:217], v169 offset:23552
	global_load_lds_dwordx4 v[162:163], off
	s_add_i32 m0, s64, 0x2000
	s_add_u32 s64, s42, 0x200000
	v_lshl_add_u64 v[218:219], s[42:43], 0, v[142:143]
	s_addc_u32 s65, s43, 0
	s_add_i32 s66, s57, s33
	global_load_lds_dwordx4 v[218:219], off
	s_mov_b32 m0, s66
	v_lshl_add_u64 v[222:223], s[44:45], 0, v[140:141]
	global_load_lds_dwordx4 v138, s[64:65]
	s_add_i32 m0, s66, 0x2000
	s_nop 0
	global_load_lds_dwordx4 v142, s[64:65]
	s_mov_b32 m0, s39
	v_lshl_add_u64 v[220:221], s[44:45], 0, v[136:137]
	global_load_lds_dwordx4 v[220:221], off
	s_mov_b32 m0, s46
	s_nop 0
	global_load_lds_dwordx4 v[222:223], off
	s_waitcnt vmcnt(8)
	s_waitcnt lgkmcnt(0)
	s_setprio 1
	s_barrier
	v_mfma_f32_16x16x32_bf16 v[92:95], v[128:131], v[186:189], v[92:95]
	v_mfma_f32_16x16x32_bf16 v[88:91], v[154:157], v[186:189], v[88:91]
	v_mfma_f32_16x16x32_bf16 v[84:87], v[128:131], v[194:197], v[84:87]
	v_mfma_f32_16x16x32_bf16 v[80:83], v[154:157], v[194:197], v[80:83]
	v_mfma_f32_16x16x32_bf16 v[76:79], v[128:131], v[202:205], v[76:79]
	v_mfma_f32_16x16x32_bf16 v[72:75], v[154:157], v[202:205], v[72:75]
	v_mfma_f32_16x16x32_bf16 v[64:67], v[128:131], v[210:213], v[64:67]
	v_mfma_f32_16x16x32_bf16 v[56:59], v[154:157], v[210:213], v[56:59]
	v_mfma_f32_16x16x32_bf16 v[92:95], v[132:135], v[190:193], v[92:95]
	v_mfma_f32_16x16x32_bf16 v[88:91], v[158:161], v[190:193], v[88:91]
	v_mfma_f32_16x16x32_bf16 v[84:87], v[132:135], v[198:201], v[84:87]
	v_mfma_f32_16x16x32_bf16 v[80:83], v[158:161], v[198:201], v[80:83]
	v_mfma_f32_16x16x32_bf16 v[76:79], v[132:135], v[206:209], v[76:79]
	v_mfma_f32_16x16x32_bf16 v[72:75], v[158:161], v[206:209], v[72:75]
	v_mfma_f32_16x16x32_bf16 v[64:67], v[132:135], v[214:217], v[64:67]
	v_mfma_f32_16x16x32_bf16 v[56:59], v[158:161], v[214:217], v[56:59]
	s_setprio 0
	s_setprio 1
	v_mfma_f32_16x16x32_bf16 v[28:31], v[170:173], v[186:189], v[28:31]
	v_mfma_f32_16x16x32_bf16 v[24:27], v[178:181], v[186:189], v[24:27]
	v_mfma_f32_16x16x32_bf16 v[20:23], v[170:173], v[194:197], v[20:23]
	v_mfma_f32_16x16x32_bf16 v[16:19], v[178:181], v[194:197], v[16:19]
	v_mfma_f32_16x16x32_bf16 v[12:15], v[170:173], v[202:205], v[12:15]
	v_mfma_f32_16x16x32_bf16 v[8:11], v[178:181], v[202:205], v[8:11]
	v_mfma_f32_16x16x32_bf16 v[4:7], v[170:173], v[210:213], v[4:7]
	v_mfma_f32_16x16x32_bf16 v[0:3], v[178:181], v[210:213], v[0:3]
	v_mfma_f32_16x16x32_bf16 v[28:31], v[174:177], v[190:193], v[28:31]
	v_mfma_f32_16x16x32_bf16 v[24:27], v[182:185], v[190:193], v[24:27]
	v_mfma_f32_16x16x32_bf16 v[20:23], v[174:177], v[198:201], v[20:23]
	v_mfma_f32_16x16x32_bf16 v[16:19], v[182:185], v[198:201], v[16:19]
	v_mfma_f32_16x16x32_bf16 v[12:15], v[174:177], v[206:209], v[12:15]
	v_mfma_f32_16x16x32_bf16 v[8:11], v[182:185], v[206:209], v[8:11]
	s_setprio 2
	s_barrier
; #define PG8_STAGE(bufoff, gbase, voff) do { _Pragma("unroll") for (int _i = 0; _i < 2; ++_i) \
;         __builtin_amdgcn_global_load_lds((const unsigned*)((const char*)(gbase) + (voff)[_i]), (PG8_LAS unsigned*)(lds + (bufoff) + ldsw + _i * 8192), 16, 0, 0); } while (0)
; #define PG8_LDA(dst, b, h) do { _Pragma("unroll") for (int m = 0; m < 4; ++m) _Pragma("unroll") for (int k = 0; k < 2; ++k) dst[m][k] = *(const PG8_LAS bf16x8*)(lds + PG8_SA(b, h) + aoff + m * 2048 + k * 1024); } while (0)
; #define PG8_LDB(dst, b, h) do { _Pragma("unroll") for (int n = 0; n < 2; ++n) _Pragma("unroll") for (int k = 0; k < 2; ++k) dst[n][k] = *(const PG8_LAS bf16x8*)(lds + PG8_SB(b, h) + boff + n * 2048 + k * 1024); } while (0)
; #define PG8_MMA(ai, bj, At, Bt) do { __builtin_amdgcn_s_setprio(1); _Pragma("unroll") for (int m = 0; m < 4; ++m) _Pragma("unroll") for (int n = 0; n < 2; ++n) _Pragma("unroll") for (int k = 0; k < 2; ++k) \
;         acc[ai][bj][m][n] = __builtin_amdgcn_mfma_f32_16x16x32_bf16(Bt[n][k], At[m][k], acc[ai][bj][m][n], 0, 0, 0); __builtin_amdgcn_s_setprio(0); } while (0)
; #define PG8_WAIT_V(n) asm volatile("s_waitcnt vmcnt(" #n ")" ::: "memory")
; #define PG8_WAIT_L(n) asm volatile("s_waitcnt lgkmcnt(" #n ")" ::: "memory")
; #define PG8_BAR __builtin_amdgcn_s_barrier()
; #define PG8_SCHED __builtin_amdgcn_sched_barrier(0)
; template <class Epi, class Sched, bool ALIGN_EPI = false, bool SP2 = false>
; __device__ __forceinline__ void gemm_phase(PG8_LAS unsigned char* lds, const Gemm g, const Sched& S, const Epi& E) {
;     ...
;             PG8_LDB(B0, 1, 0); PG8_LDB(B1, 1, 1); PG8_SCHED; PG8_LDA(At, 1, 0); PG8_STAGE(PG8_SA(0, 1), a2 + hstep, voffA);
;             PG8_WAIT_V(8); PG8_WAIT_L(0); PG8_BAR; PG8_MMA(0, 0, At, B0); PG8_MMA(0, 1, At, B1); PG8_BAR; PG8_SCHED;
	v_mfma_f32_16x16x32_bf16 v[4:7], v[174:177], v[214:217], v[4:7]
	v_mfma_f32_16x16x32_bf16 v[0:3], v[182:185], v[214:217], v[0:3]
	s_setprio 0
	s_add_i32 s64, 0, 0x18000
	s_add_i32 s65, 0, 0x1c000
	v_add_u32_e32 v158, s64, v165
	v_add_u32_e32 v182, s65, v165
	ds_read_b128 v[128:131], v158
	ds_read_b128 v[132:135], v158 offset:1024
	ds_read_b128 v[154:157], v158 offset:2048
	ds_read_b128 v[158:161], v158 offset:3072
	ds_read_b128 v[170:173], v182
	ds_read_b128 v[174:177], v182 offset:1024
	ds_read_b128 v[178:181], v182 offset:2048
	ds_read_b128 v[182:185], v182 offset:3072
	s_add_u32 s44, s44, 0x200000
	s_addc_u32 s45, s45, 0
	s_mov_b32 m0, s47
	ds_read_b128 v[186:189], v169 offset:32768
	ds_read_b128 v[190:193], v169 offset:33792
	ds_read_b128 v[194:197], v169 offset:34816
	ds_read_b128 v[198:201], v169 offset:35840
	ds_read_b128 v[202:205], v169 offset:36864
	ds_read_b128 v[206:209], v169 offset:37888
	ds_read_b128 v[210:213], v169 offset:38912
	ds_read_b128 v[214:217], v169 offset:39936
	global_load_lds_dwordx4 v136, s[44:45]
	s_mov_b32 m0, s48
	s_nop 0
	global_load_lds_dwordx4 v140, s[44:45]
	s_waitcnt vmcnt(8)
	s_waitcnt lgkmcnt(0)
	s_setprio 1
	s_barrier
	v_mfma_f32_16x16x32_bf16 v[124:127], v[128:131], v[186:189], v[124:127]
	v_mfma_f32_16x16x32_bf16 v[120:123], v[154:157], v[186:189], v[120:123]
	v_mfma_f32_16x16x32_bf16 v[116:119], v[128:131], v[194:197], v[116:119]
	v_mfma_f32_16x16x32_bf16 v[112:115], v[154:157], v[194:197], v[112:115]
	v_mfma_f32_16x16x32_bf16 v[108:111], v[128:131], v[202:205], v[108:111]
	v_mfma_f32_16x16x32_bf16 v[104:107], v[154:157], v[202:205], v[104:107]
	v_mfma_f32_16x16x32_bf16 v[100:103], v[128:131], v[210:213], v[100:103]
	v_mfma_f32_16x16x32_bf16 v[96:99], v[154:157], v[210:213], v[96:99]
	v_mfma_f32_16x16x32_bf16 v[124:127], v[132:135], v[190:193], v[124:127]
	v_mfma_f32_16x16x32_bf16 v[120:123], v[158:161], v[190:193], v[120:123]
	v_mfma_f32_16x16x32_bf16 v[116:119], v[132:135], v[198:201], v[116:119]
	v_mfma_f32_16x16x32_bf16 v[112:115], v[158:161], v[198:201], v[112:115]
	v_mfma_f32_16x16x32_bf16 v[108:111], v[132:135], v[206:209], v[108:111]
	v_mfma_f32_16x16x32_bf16 v[104:107], v[158:161], v[206:209], v[104:107]
	v_mfma_f32_16x16x32_bf16 v[100:103], v[132:135], v[214:217], v[100:103]
	v_mfma_f32_16x16x32_bf16 v[96:99], v[158:161], v[214:217], v[96:99]
	s_setprio 0
	s_setprio 1
	v_mfma_f32_16x16x32_bf16 v[68:71], v[170:173], v[186:189], v[68:71]
	v_mfma_f32_16x16x32_bf16 v[60:63], v[178:181], v[186:189], v[60:63]
	v_mfma_f32_16x16x32_bf16 v[52:55], v[170:173], v[194:197], v[52:55]
	v_mfma_f32_16x16x32_bf16 v[48:51], v[178:181], v[194:197], v[48:51]
	v_mfma_f32_16x16x32_bf16 v[44:47], v[170:173], v[202:205], v[44:47]
	v_mfma_f32_16x16x32_bf16 v[40:43], v[178:181], v[202:205], v[40:43]
	v_mfma_f32_16x16x32_bf16 v[36:39], v[170:173], v[210:213], v[36:39]
	v_mfma_f32_16x16x32_bf16 v[32:35], v[178:181], v[210:213], v[32:35]
	v_mfma_f32_16x16x32_bf16 v[68:71], v[174:177], v[190:193], v[68:71]
	v_mfma_f32_16x16x32_bf16 v[60:63], v[182:185], v[190:193], v[60:63]
	v_mfma_f32_16x16x32_bf16 v[52:55], v[174:177], v[198:201], v[52:55]
	v_mfma_f32_16x16x32_bf16 v[48:51], v[182:185], v[198:201], v[48:51]
	v_mfma_f32_16x16x32_bf16 v[44:47], v[174:177], v[206:209], v[44:47]
	v_mfma_f32_16x16x32_bf16 v[40:43], v[182:185], v[206:209], v[40:43]
	s_setprio 2
	s_barrier
; #define PG8_STAGE(bufoff, gbase, voff) do { _Pragma("unroll") for (int _i = 0; _i < 2; ++_i) \
;         __builtin_amdgcn_global_load_lds((const unsigned*)((const char*)(gbase) + (voff)[_i]), (PG8_LAS unsigned*)(lds + (bufoff) + ldsw + _i * 8192), 16, 0, 0); } while (0)
; #define PG8_LDA(dst, b, h) do { _Pragma("unroll") for (int m = 0; m < 4; ++m) _Pragma("unroll") for (int k = 0; k < 2; ++k) dst[m][k] = *(const PG8_LAS bf16x8*)(lds + PG8_SA(b, h) + aoff + m * 2048 + k * 1024); } while (0)
; #define PG8_MMA(ai, bj, At, Bt) do { __builtin_amdgcn_s_setprio(1); _Pragma("unroll") for (int m = 0; m < 4; ++m) _Pragma("unroll") for (int n = 0; n < 2; ++n) _Pragma("unroll") for (int k = 0; k < 2; ++k) \
;         acc[ai][bj][m][n] = __builtin_amdgcn_mfma_f32_16x16x32_bf16(Bt[n][k], At[m][k], acc[ai][bj][m][n], 0, 0, 0); __builtin_amdgcn_s_setprio(0); } while (0)
; #define PG8_WAIT_V(n) asm volatile("s_waitcnt vmcnt(" #n ")" ::: "memory")
; #define PG8_WAIT_L(n) asm volatile("s_waitcnt lgkmcnt(" #n ")" ::: "memory")
; #define PG8_BAR __builtin_amdgcn_s_barrier()
; #define PG8_SCHED __builtin_amdgcn_sched_barrier(0)
; template <class Epi, class Sched, bool ALIGN_EPI = false, bool SP2 = false>
; __device__ __forceinline__ void gemm_phase(PG8_LAS unsigned char* lds, const Gemm g, const Sched& S, const Epi& E) {
;     ...
;             PG8_LDA(At, 1, 1); PG8_STAGE(PG8_SB(1, 0), b3, voffB); PG8_STAGE(PG8_SB(1, 1), b3 + hstep, voffB); PG8_STAGE(PG8_SA(1, 0), a3, voffA);
;             PG8_WAIT_V(8); PG8_WAIT_L(0); PG8_BAR; PG8_MMA(1, 0, At, B0); PG8_MMA(1, 1, At, B1); PG8_BAR; PG8_SCHED;
	v_mfma_f32_16x16x32_bf16 v[36:39], v[174:177], v[214:217], v[36:39]
	v_mfma_f32_16x16x32_bf16 v[32:35], v[182:185], v[214:217], v[32:35]
	s_setprio 0
	s_add_i32 s44, s64, s33
	v_lshl_add_u64 v[162:163], v[162:163], 0, s[8:9]
	s_mov_b32 m0, s44
	ds_read_b128 v[186:189], v169 offset:49152
	ds_read_b128 v[190:193], v169 offset:50176
	ds_read_b128 v[194:197], v169 offset:51200
	ds_read_b128 v[198:201], v169 offset:52224
	ds_read_b128 v[202:205], v169 offset:53248
	ds_read_b128 v[206:209], v169 offset:54272
	ds_read_b128 v[210:213], v169 offset:55296
	ds_read_b128 v[214:217], v169 offset:56320
	global_load_lds_dwordx4 v[162:163], off
	s_add_i32 m0, s44, 0x2000
	s_add_u32 s42, s42, 0x200080
	v_lshl_add_u64 v[162:163], v[218:219], 0, s[8:9]
	s_addc_u32 s43, s43, 0
	s_add_i32 s44, s65, s33
	global_load_lds_dwordx4 v[162:163], off
	s_mov_b32 m0, s44
	s_nop 0
	global_load_lds_dwordx4 v138, s[42:43]
	s_add_i32 m0, s44, 0x2000
	s_nop 0
	global_load_lds_dwordx4 v142, s[42:43]
	s_mov_b32 m0, s52
	v_lshl_add_u64 v[162:163], v[220:221], 0, s[8:9]
	global_load_lds_dwordx4 v[162:163], off
	s_mov_b32 m0, s53
	v_lshl_add_u64 v[162:163], v[222:223], 0, s[8:9]
	global_load_lds_dwordx4 v[162:163], off
	s_waitcnt vmcnt(8)
	s_waitcnt lgkmcnt(0)
	s_setprio 1
	s_barrier
	v_mfma_f32_16x16x32_bf16 v[92:95], v[128:131], v[186:189], v[92:95]
	v_mfma_f32_16x16x32_bf16 v[88:91], v[154:157], v[186:189], v[88:91]
	v_mfma_f32_16x16x32_bf16 v[84:87], v[128:131], v[194:197], v[84:87]
	v_mfma_f32_16x16x32_bf16 v[80:83], v[154:157], v[194:197], v[80:83]
	v_mfma_f32_16x16x32_bf16 v[76:79], v[128:131], v[202:205], v[76:79]
	v_mfma_f32_16x16x32_bf16 v[72:75], v[154:157], v[202:205], v[72:75]
	v_mfma_f32_16x16x32_bf16 v[64:67], v[128:131], v[210:213], v[64:67]
	v_mfma_f32_16x16x32_bf16 v[56:59], v[154:157], v[210:213], v[56:59]
	v_mfma_f32_16x16x32_bf16 v[92:95], v[132:135], v[190:193], v[92:95]
	v_mfma_f32_16x16x32_bf16 v[88:91], v[158:161], v[190:193], v[88:91]
	v_mfma_f32_16x16x32_bf16 v[84:87], v[132:135], v[198:201], v[84:87]
	v_mfma_f32_16x16x32_bf16 v[80:83], v[158:161], v[198:201], v[80:83]
	v_mfma_f32_16x16x32_bf16 v[76:79], v[132:135], v[206:209], v[76:79]
	v_mfma_f32_16x16x32_bf16 v[72:75], v[158:161], v[206:209], v[72:75]
	v_mfma_f32_16x16x32_bf16 v[64:67], v[132:135], v[214:217], v[64:67]
	v_mfma_f32_16x16x32_bf16 v[56:59], v[158:161], v[214:217], v[56:59]
	s_setprio 0
	s_setprio 1
	v_mfma_f32_16x16x32_bf16 v[28:31], v[170:173], v[186:189], v[28:31]
	v_mfma_f32_16x16x32_bf16 v[24:27], v[178:181], v[186:189], v[24:27]
	v_mfma_f32_16x16x32_bf16 v[20:23], v[170:173], v[194:197], v[20:23]
	v_mfma_f32_16x16x32_bf16 v[16:19], v[178:181], v[194:197], v[16:19]
	v_mfma_f32_16x16x32_bf16 v[12:15], v[170:173], v[202:205], v[12:15]
	v_mfma_f32_16x16x32_bf16 v[8:11], v[178:181], v[202:205], v[8:11]
	v_mfma_f32_16x16x32_bf16 v[4:7], v[170:173], v[210:213], v[4:7]
	v_mfma_f32_16x16x32_bf16 v[0:3], v[178:181], v[210:213], v[0:3]
	v_mfma_f32_16x16x32_bf16 v[28:31], v[174:177], v[190:193], v[28:31]
	v_mfma_f32_16x16x32_bf16 v[24:27], v[182:185], v[190:193], v[24:27]
	v_mfma_f32_16x16x32_bf16 v[20:23], v[174:177], v[198:201], v[20:23]
	v_mfma_f32_16x16x32_bf16 v[16:19], v[182:185], v[198:201], v[16:19]
	v_mfma_f32_16x16x32_bf16 v[12:15], v[174:177], v[206:209], v[12:15]
	v_mfma_f32_16x16x32_bf16 v[8:11], v[182:185], v[206:209], v[8:11]
	s_setprio 2
	s_barrier
	v_mfma_f32_16x16x32_bf16 v[4:7], v[174:177], v[214:217], v[4:7]
	v_mfma_f32_16x16x32_bf16 v[0:3], v[182:185], v[214:217], v[0:3]
	s_setprio 0
	s_add_i32 s63, s63, 2
	s_add_u32 s40, s40, 0x100
	s_addc_u32 s41, s41, 0
	s_add_u32 s61, s61, 0x100
	s_addc_u32 s62, s62, 0
	s_cmpk_gt_u32 s63, 0x7d
	s_cbranch_scc0 .LBB0_1219
	s_and_b64 vcc, exec, s[10:11]
	s_cbranch_vccz .LBB0_1222
	s_barrier
